# v23 + strategy 7.11 back-edge rotation: loop-carried SALU block of all 12 GEMM K-loops moved in front of the loop-back barrier
# baseline (speedup 1.0000x reference)
.LBB0_91:
	ds_read_b128 v[150:153], v158
	ds_read_b128 v[162:165], v158 offset:1024
	ds_read_b128 v[166:169], v158 offset:2048
	ds_read_b128 v[170:173], v158 offset:3072
	ds_read_b128 v[174:177], v159
	ds_read_b128 v[178:181], v159 offset:1024
	ds_read_b128 v[182:185], v159 offset:2048
	ds_read_b128 v[186:189], v159 offset:3072
	s_add_u32 s36, s34, 0xfff00080
	s_addc_u32 s37, s35, -1
	s_cmp_eq_u32 s57, 60
	s_cselect_b32 s39, s2, s37
	s_cselect_b32 s38, s25, s36
	s_cselect_b32 s37, s23, s56
	s_cselect_b32 s36, s54, s55
	v_lshl_add_u64 v[146:147], s[34:35], 0, v[138:139]
	s_add_i32 m0, s43, 0xc000
	ds_read_b128 v[190:193], v160
	ds_read_b128 v[194:197], v160 offset:1024
	ds_read_b128 v[198:201], v160 offset:2048
	ds_read_b128 v[202:205], v160 offset:3072
	ds_read_b128 v[206:209], v160 offset:4096
	ds_read_b128 v[210:213], v160 offset:5120
	ds_read_b128 v[214:217], v160 offset:6144
	ds_read_b128 v[218:221], v160 offset:7168
	global_load_lds_dwordx4 v[146:147], off
	v_lshl_add_u64 v[146:147], s[34:35], 0, v[140:141]
	s_add_i32 m0, s43, 0xe000
	s_nop 0
	global_load_lds_dwordx4 v[146:147], off
	s_waitcnt vmcnt(8)
	s_waitcnt lgkmcnt(0)
	s_barrier
	s_setprio 1
	s_waitcnt lgkmcnt(0)
	v_mfma_f32_16x16x32_bf16 v[78:81], v[150:153], v[190:193], v[78:81]
	v_mfma_f32_16x16x32_bf16 v[70:73], v[166:169], v[190:193], v[70:73]
	v_mfma_f32_16x16x32_bf16 v[62:65], v[150:153], v[198:201], v[62:65]
	v_mfma_f32_16x16x32_bf16 v[58:61], v[166:169], v[198:201], v[58:61]
	v_mfma_f32_16x16x32_bf16 v[54:57], v[150:153], v[206:209], v[54:57]
	v_mfma_f32_16x16x32_bf16 v[50:53], v[166:169], v[206:209], v[50:53]
	v_mfma_f32_16x16x32_bf16 v[46:49], v[150:153], v[214:217], v[46:49]
	v_mfma_f32_16x16x32_bf16 v[42:45], v[166:169], v[214:217], v[42:45]
	v_mfma_f32_16x16x32_bf16 v[78:81], v[162:165], v[194:197], v[78:81]
	v_mfma_f32_16x16x32_bf16 v[70:73], v[170:173], v[194:197], v[70:73]
	v_mfma_f32_16x16x32_bf16 v[62:65], v[162:165], v[202:205], v[62:65]
	v_mfma_f32_16x16x32_bf16 v[58:61], v[170:173], v[202:205], v[58:61]
	v_mfma_f32_16x16x32_bf16 v[54:57], v[162:165], v[210:213], v[54:57]
	v_mfma_f32_16x16x32_bf16 v[50:53], v[170:173], v[210:213], v[50:53]
	v_mfma_f32_16x16x32_bf16 v[46:49], v[162:165], v[218:221], v[46:49]
	v_mfma_f32_16x16x32_bf16 v[42:45], v[170:173], v[218:221], v[42:45]
	s_setprio 0
	s_setprio 1
	v_mfma_f32_16x16x32_bf16 v[126:129], v[174:177], v[190:193], v[126:129]
	v_mfma_f32_16x16x32_bf16 v[122:125], v[182:185], v[190:193], v[122:125]
	v_mfma_f32_16x16x32_bf16 v[118:121], v[174:177], v[198:201], v[118:121]
	v_mfma_f32_16x16x32_bf16 v[114:117], v[182:185], v[198:201], v[114:117]
	v_mfma_f32_16x16x32_bf16 v[110:113], v[174:177], v[206:209], v[110:113]
	v_mfma_f32_16x16x32_bf16 v[106:109], v[182:185], v[206:209], v[106:109]
	v_mfma_f32_16x16x32_bf16 v[102:105], v[174:177], v[214:217], v[102:105]
	v_mfma_f32_16x16x32_bf16 v[98:101], v[182:185], v[214:217], v[98:101]
	v_mfma_f32_16x16x32_bf16 v[126:129], v[178:181], v[194:197], v[126:129]
	v_mfma_f32_16x16x32_bf16 v[122:125], v[186:189], v[194:197], v[122:125]
	v_mfma_f32_16x16x32_bf16 v[118:121], v[178:181], v[202:205], v[118:121]
	v_mfma_f32_16x16x32_bf16 v[114:117], v[186:189], v[202:205], v[114:117]
	v_mfma_f32_16x16x32_bf16 v[110:113], v[178:181], v[210:213], v[110:113]
	v_mfma_f32_16x16x32_bf16 v[106:109], v[186:189], v[210:213], v[106:109]
	v_mfma_f32_16x16x32_bf16 v[102:105], v[178:181], v[218:221], v[102:105]
	v_mfma_f32_16x16x32_bf16 v[98:101], v[186:189], v[218:221], v[98:101]
	s_setprio 0
	s_barrier
	s_add_i32 s58, s51, s40
	v_lshl_add_u64 v[146:147], s[36:37], 0, v[134:135]
	s_mov_b32 m0, s58
	ds_read_b128 v[190:193], v160 offset:16384
	ds_read_b128 v[194:197], v160 offset:17408
	ds_read_b128 v[198:201], v160 offset:18432
	ds_read_b128 v[202:205], v160 offset:19456
	ds_read_b128 v[206:209], v160 offset:20480
	ds_read_b128 v[210:213], v160 offset:21504
	ds_read_b128 v[214:217], v160 offset:22528
	ds_read_b128 v[218:221], v160 offset:23552
	global_load_lds_dwordx4 v[146:147], off
	s_add_i32 m0, s58, 0x2000
	s_add_u32 s58, s36, 0x100000
	v_lshl_add_u64 v[222:223], s[36:37], 0, v[130:131]
	s_addc_u32 s59, s37, 0
	s_add_i32 s60, s52, s40
	global_load_lds_dwordx4 v[222:223], off
	v_lshl_add_u64 v[224:225], s[58:59], 0, v[134:135]
	s_mov_b32 m0, s60
	v_lshl_add_u64 v[226:227], s[38:39], 0, v[132:133]
	global_load_lds_dwordx4 v[224:225], off
	v_lshl_add_u64 v[224:225], s[58:59], 0, v[130:131]
	s_add_i32 m0, s60, 0x2000
	s_nop 0
	global_load_lds_dwordx4 v[224:225], off
	v_lshl_add_u64 v[224:225], s[38:39], 0, v[136:137]
	s_mov_b32 m0, s43
	s_nop 0
	global_load_lds_dwordx4 v[224:225], off
	s_mov_b32 m0, s44
	s_nop 0
	global_load_lds_dwordx4 v[226:227], off
	s_waitcnt vmcnt(8)
	s_waitcnt lgkmcnt(0)
	s_barrier
	s_setprio 1
	s_waitcnt lgkmcnt(0)
	v_mfma_f32_16x16x32_bf16 v[30:33], v[150:153], v[190:193], v[30:33]
	v_mfma_f32_16x16x32_bf16 v[26:29], v[166:169], v[190:193], v[26:29]
	v_mfma_f32_16x16x32_bf16 v[22:25], v[150:153], v[198:201], v[22:25]
	v_mfma_f32_16x16x32_bf16 v[18:21], v[166:169], v[198:201], v[18:21]
	v_mfma_f32_16x16x32_bf16 v[14:17], v[150:153], v[206:209], v[14:17]
	v_mfma_f32_16x16x32_bf16 v[10:13], v[166:169], v[206:209], v[10:13]
	v_mfma_f32_16x16x32_bf16 v[6:9], v[150:153], v[214:217], v[6:9]
	v_mfma_f32_16x16x32_bf16 v[2:5], v[166:169], v[214:217], v[2:5]
	v_mfma_f32_16x16x32_bf16 v[30:33], v[162:165], v[194:197], v[30:33]
	v_mfma_f32_16x16x32_bf16 v[26:29], v[170:173], v[194:197], v[26:29]
	v_mfma_f32_16x16x32_bf16 v[22:25], v[162:165], v[202:205], v[22:25]
	v_mfma_f32_16x16x32_bf16 v[18:21], v[170:173], v[202:205], v[18:21]
	v_mfma_f32_16x16x32_bf16 v[14:17], v[162:165], v[210:213], v[14:17]
	v_mfma_f32_16x16x32_bf16 v[10:13], v[170:173], v[210:213], v[10:13]
	v_mfma_f32_16x16x32_bf16 v[6:9], v[162:165], v[218:221], v[6:9]
	v_mfma_f32_16x16x32_bf16 v[2:5], v[170:173], v[218:221], v[2:5]
	s_setprio 0
	s_setprio 1
	v_mfma_f32_16x16x32_bf16 v[94:97], v[174:177], v[190:193], v[94:97]
	v_mfma_f32_16x16x32_bf16 v[90:93], v[182:185], v[190:193], v[90:93]
	v_mfma_f32_16x16x32_bf16 v[86:89], v[174:177], v[198:201], v[86:89]
	v_mfma_f32_16x16x32_bf16 v[82:85], v[182:185], v[198:201], v[82:85]
	v_mfma_f32_16x16x32_bf16 v[74:77], v[174:177], v[206:209], v[74:77]
	v_mfma_f32_16x16x32_bf16 v[66:69], v[182:185], v[206:209], v[66:69]
	v_mfma_f32_16x16x32_bf16 v[38:41], v[174:177], v[214:217], v[38:41]
	v_mfma_f32_16x16x32_bf16 v[34:37], v[182:185], v[214:217], v[34:37]
	v_mfma_f32_16x16x32_bf16 v[94:97], v[178:181], v[194:197], v[94:97]
	v_mfma_f32_16x16x32_bf16 v[90:93], v[186:189], v[194:197], v[90:93]
	v_mfma_f32_16x16x32_bf16 v[86:89], v[178:181], v[202:205], v[86:89]
	v_mfma_f32_16x16x32_bf16 v[82:85], v[186:189], v[202:205], v[82:85]
	v_mfma_f32_16x16x32_bf16 v[74:77], v[178:181], v[210:213], v[74:77]
	v_mfma_f32_16x16x32_bf16 v[66:69], v[186:189], v[210:213], v[66:69]
	v_mfma_f32_16x16x32_bf16 v[38:41], v[178:181], v[218:221], v[38:41]
	v_mfma_f32_16x16x32_bf16 v[34:37], v[186:189], v[218:221], v[34:37]
	s_setprio 0
	s_barrier
	s_add_i32 s58, 0, 0x18000
	v_add_u32_e32 v148, s58, v156
	s_add_i32 s59, 0, 0x1c000
	ds_read_b128 v[150:153], v148
	ds_read_b128 v[162:165], v148 offset:1024
	ds_read_b128 v[166:169], v148 offset:2048
	ds_read_b128 v[170:173], v148 offset:3072
	v_add_u32_e32 v148, s59, v156
	ds_read_b128 v[174:177], v148
	ds_read_b128 v[178:181], v148 offset:1024
	ds_read_b128 v[182:185], v148 offset:2048
	ds_read_b128 v[186:189], v148 offset:3072
	s_add_u32 s38, s38, 0x100000
	s_addc_u32 s39, s39, 0
	s_mov_b32 m0, s45
	v_lshl_add_u64 v[228:229], s[38:39], 0, v[136:137]
	ds_read_b128 v[190:193], v160 offset:32768
	ds_read_b128 v[194:197], v160 offset:33792
	ds_read_b128 v[198:201], v160 offset:34816
	ds_read_b128 v[202:205], v160 offset:35840
	ds_read_b128 v[206:209], v160 offset:36864
	ds_read_b128 v[210:213], v160 offset:37888
	ds_read_b128 v[214:217], v160 offset:38912
	ds_read_b128 v[218:221], v160 offset:39936
	global_load_lds_dwordx4 v[228:229], off
	v_lshl_add_u64 v[228:229], s[38:39], 0, v[132:133]
	s_mov_b32 m0, s46
	s_nop 0
	global_load_lds_dwordx4 v[228:229], off
	s_waitcnt vmcnt(8)
	s_waitcnt lgkmcnt(0)
	s_barrier
	s_setprio 1
	s_waitcnt lgkmcnt(0)
	v_mfma_f32_16x16x32_bf16 v[78:81], v[150:153], v[190:193], v[78:81]
	v_mfma_f32_16x16x32_bf16 v[70:73], v[166:169], v[190:193], v[70:73]
	v_mfma_f32_16x16x32_bf16 v[62:65], v[150:153], v[198:201], v[62:65]
	v_mfma_f32_16x16x32_bf16 v[58:61], v[166:169], v[198:201], v[58:61]
	v_mfma_f32_16x16x32_bf16 v[54:57], v[150:153], v[206:209], v[54:57]
	v_mfma_f32_16x16x32_bf16 v[50:53], v[166:169], v[206:209], v[50:53]
	v_mfma_f32_16x16x32_bf16 v[46:49], v[150:153], v[214:217], v[46:49]
	v_mfma_f32_16x16x32_bf16 v[42:45], v[166:169], v[214:217], v[42:45]
	v_mfma_f32_16x16x32_bf16 v[78:81], v[162:165], v[194:197], v[78:81]
	v_mfma_f32_16x16x32_bf16 v[70:73], v[170:173], v[194:197], v[70:73]
	v_mfma_f32_16x16x32_bf16 v[62:65], v[162:165], v[202:205], v[62:65]
	v_mfma_f32_16x16x32_bf16 v[58:61], v[170:173], v[202:205], v[58:61]
	v_mfma_f32_16x16x32_bf16 v[54:57], v[162:165], v[210:213], v[54:57]
	v_mfma_f32_16x16x32_bf16 v[50:53], v[170:173], v[210:213], v[50:53]
	v_mfma_f32_16x16x32_bf16 v[46:49], v[162:165], v[218:221], v[46:49]
	v_mfma_f32_16x16x32_bf16 v[42:45], v[170:173], v[218:221], v[42:45]
	s_setprio 0
	s_setprio 1
	v_mfma_f32_16x16x32_bf16 v[126:129], v[174:177], v[190:193], v[126:129]
	v_mfma_f32_16x16x32_bf16 v[122:125], v[182:185], v[190:193], v[122:125]
	v_mfma_f32_16x16x32_bf16 v[118:121], v[174:177], v[198:201], v[118:121]
	v_mfma_f32_16x16x32_bf16 v[114:117], v[182:185], v[198:201], v[114:117]
	v_mfma_f32_16x16x32_bf16 v[110:113], v[174:177], v[206:209], v[110:113]
	v_mfma_f32_16x16x32_bf16 v[106:109], v[182:185], v[206:209], v[106:109]
	v_mfma_f32_16x16x32_bf16 v[102:105], v[174:177], v[214:217], v[102:105]
	v_mfma_f32_16x16x32_bf16 v[98:101], v[182:185], v[214:217], v[98:101]
	v_mfma_f32_16x16x32_bf16 v[126:129], v[178:181], v[194:197], v[126:129]
	v_mfma_f32_16x16x32_bf16 v[122:125], v[186:189], v[194:197], v[122:125]
	v_mfma_f32_16x16x32_bf16 v[118:121], v[178:181], v[202:205], v[118:121]
	v_mfma_f32_16x16x32_bf16 v[114:117], v[186:189], v[202:205], v[114:117]
	v_mfma_f32_16x16x32_bf16 v[110:113], v[178:181], v[210:213], v[110:113]
	v_mfma_f32_16x16x32_bf16 v[106:109], v[186:189], v[210:213], v[106:109]
	v_mfma_f32_16x16x32_bf16 v[102:105], v[178:181], v[218:221], v[102:105]
	v_mfma_f32_16x16x32_bf16 v[98:101], v[186:189], v[218:221], v[98:101]
	s_setprio 0
	s_barrier
	s_add_i32 s38, s58, s40
	v_lshl_add_u64 v[146:147], v[146:147], 0, s[18:19]
	s_mov_b32 m0, s38
	ds_read_b128 v[190:193], v160 offset:49152
	ds_read_b128 v[194:197], v160 offset:50176
	ds_read_b128 v[198:201], v160 offset:51200
	ds_read_b128 v[202:205], v160 offset:52224
	ds_read_b128 v[206:209], v160 offset:53248
	ds_read_b128 v[210:213], v160 offset:54272
	ds_read_b128 v[214:217], v160 offset:55296
	ds_read_b128 v[218:221], v160 offset:56320
	global_load_lds_dwordx4 v[146:147], off
	s_add_i32 m0, s38, 0x2000
	s_add_u32 s36, s36, 0x100080
	v_lshl_add_u64 v[146:147], v[222:223], 0, s[18:19]
	s_addc_u32 s37, s37, 0
	s_add_i32 s38, s59, s40
	global_load_lds_dwordx4 v[146:147], off
	v_lshl_add_u64 v[146:147], s[36:37], 0, v[134:135]
	s_mov_b32 m0, s38
	s_nop 0
	global_load_lds_dwordx4 v[146:147], off
	v_lshl_add_u64 v[146:147], s[36:37], 0, v[130:131]
	s_add_i32 m0, s38, 0x2000
	s_nop 0
	global_load_lds_dwordx4 v[146:147], off
	v_lshl_add_u64 v[146:147], v[224:225], 0, s[18:19]
	s_mov_b32 m0, s48
	s_nop 0
	global_load_lds_dwordx4 v[146:147], off
	v_lshl_add_u64 v[146:147], v[226:227], 0, s[18:19]
	s_mov_b32 m0, s49
	s_nop 0
	global_load_lds_dwordx4 v[146:147], off
	s_waitcnt vmcnt(8)
	s_waitcnt lgkmcnt(0)
	s_barrier
	s_setprio 1
	s_waitcnt lgkmcnt(0)
	v_mfma_f32_16x16x32_bf16 v[30:33], v[150:153], v[190:193], v[30:33]
	v_mfma_f32_16x16x32_bf16 v[26:29], v[166:169], v[190:193], v[26:29]
	v_mfma_f32_16x16x32_bf16 v[22:25], v[150:153], v[198:201], v[22:25]
	v_mfma_f32_16x16x32_bf16 v[18:21], v[166:169], v[198:201], v[18:21]
	v_mfma_f32_16x16x32_bf16 v[14:17], v[150:153], v[206:209], v[14:17]
	v_mfma_f32_16x16x32_bf16 v[10:13], v[166:169], v[206:209], v[10:13]
	v_mfma_f32_16x16x32_bf16 v[6:9], v[150:153], v[214:217], v[6:9]
	v_mfma_f32_16x16x32_bf16 v[2:5], v[166:169], v[214:217], v[2:5]
	v_mfma_f32_16x16x32_bf16 v[30:33], v[162:165], v[194:197], v[30:33]
	v_mfma_f32_16x16x32_bf16 v[26:29], v[170:173], v[194:197], v[26:29]
	v_mfma_f32_16x16x32_bf16 v[22:25], v[162:165], v[202:205], v[22:25]
	v_mfma_f32_16x16x32_bf16 v[18:21], v[170:173], v[202:205], v[18:21]
	v_mfma_f32_16x16x32_bf16 v[14:17], v[162:165], v[210:213], v[14:17]
	v_mfma_f32_16x16x32_bf16 v[10:13], v[170:173], v[210:213], v[10:13]
	v_mfma_f32_16x16x32_bf16 v[6:9], v[162:165], v[218:221], v[6:9]
	v_mfma_f32_16x16x32_bf16 v[2:5], v[170:173], v[218:221], v[2:5]
	s_setprio 0
	s_setprio 1
	v_mfma_f32_16x16x32_bf16 v[94:97], v[174:177], v[190:193], v[94:97]
	v_mfma_f32_16x16x32_bf16 v[90:93], v[182:185], v[190:193], v[90:93]
	v_mfma_f32_16x16x32_bf16 v[86:89], v[174:177], v[198:201], v[86:89]
	v_mfma_f32_16x16x32_bf16 v[82:85], v[182:185], v[198:201], v[82:85]
	v_mfma_f32_16x16x32_bf16 v[74:77], v[174:177], v[206:209], v[74:77]
	v_mfma_f32_16x16x32_bf16 v[66:69], v[182:185], v[206:209], v[66:69]
	v_mfma_f32_16x16x32_bf16 v[38:41], v[174:177], v[214:217], v[38:41]
	v_mfma_f32_16x16x32_bf16 v[34:37], v[182:185], v[214:217], v[34:37]
	v_mfma_f32_16x16x32_bf16 v[94:97], v[178:181], v[194:197], v[94:97]
	v_mfma_f32_16x16x32_bf16 v[90:93], v[186:189], v[194:197], v[90:93]
	v_mfma_f32_16x16x32_bf16 v[86:89], v[178:181], v[202:205], v[86:89]
	v_mfma_f32_16x16x32_bf16 v[82:85], v[186:189], v[202:205], v[82:85]
	v_mfma_f32_16x16x32_bf16 v[74:77], v[178:181], v[210:213], v[74:77]
	v_mfma_f32_16x16x32_bf16 v[66:69], v[186:189], v[210:213], v[66:69]
	v_mfma_f32_16x16x32_bf16 v[38:41], v[178:181], v[218:221], v[38:41]
	v_mfma_f32_16x16x32_bf16 v[34:37], v[186:189], v[218:221], v[34:37]
	s_setprio 0
	s_add_i32 s57, s57, 2
	s_add_u32 s34, s34, 0x100
	s_addc_u32 s35, s35, 0
	s_add_u32 s55, s55, 0x100
	s_addc_u32 s56, s56, 0
	s_cmp_gt_u32 s57, 61
	s_barrier
	s_cbranch_scc0 .LBB0_91
	s_and_b64 vcc, exec, s[20:21]
	s_cbranch_vccz .LBB0_94
	s_barrier

.LBB0_317:
	ds_read_b128 v[148:151], v166
	ds_read_b128 v[170:173], v166 offset:1024
	ds_read_b128 v[174:177], v166 offset:2048
	ds_read_b128 v[178:181], v166 offset:3072
	ds_read_b128 v[182:185], v167
	ds_read_b128 v[186:189], v167 offset:1024
	ds_read_b128 v[190:193], v167 offset:2048
	ds_read_b128 v[194:197], v167 offset:3072
	s_add_u32 s28, s26, 0xfffc0080
	s_addc_u32 s29, s27, -1
	s_cmp_eq_u32 s53, 12
	s_cselect_b32 s31, s19, s29
	s_cselect_b32 s30, s49, s28
	s_cselect_b32 s29, s17, s52
	s_cselect_b32 s28, s50, s51
	v_lshl_add_u64 v[230:231], s[26:27], 0, v[138:139]
	s_add_i32 m0, s25, 0xc000
	ds_read_b128 v[198:201], v168
	ds_read_b128 v[202:205], v168 offset:1024
	ds_read_b128 v[206:209], v168 offset:2048
	ds_read_b128 v[210:213], v168 offset:3072
	ds_read_b128 v[214:217], v168 offset:4096
	ds_read_b128 v[218:221], v168 offset:5120
	ds_read_b128 v[222:225], v168 offset:6144
	ds_read_b128 v[226:229], v168 offset:7168
	global_load_lds_dwordx4 v[230:231], off
	v_lshl_add_u64 v[230:231], s[26:27], 0, v[140:141]
	s_add_i32 m0, s25, 0xe000
	s_nop 0
	global_load_lds_dwordx4 v[230:231], off
	s_waitcnt vmcnt(8)
	s_waitcnt lgkmcnt(0)
	s_barrier
	s_setprio 1
	s_waitcnt lgkmcnt(0)
	v_mfma_f32_16x16x32_bf16 v[126:129], v[148:151], v[198:201], v[126:129]
	v_mfma_f32_16x16x32_bf16 v[122:125], v[174:177], v[198:201], v[122:125]
	v_mfma_f32_16x16x32_bf16 v[114:117], v[148:151], v[206:209], v[114:117]
	v_mfma_f32_16x16x32_bf16 v[106:109], v[174:177], v[206:209], v[106:109]
	v_mfma_f32_16x16x32_bf16 v[98:101], v[148:151], v[214:217], v[98:101]
	v_mfma_f32_16x16x32_bf16 v[90:93], v[174:177], v[214:217], v[90:93]
	v_mfma_f32_16x16x32_bf16 v[82:85], v[148:151], v[222:225], v[82:85]
	v_mfma_f32_16x16x32_bf16 v[74:77], v[174:177], v[222:225], v[74:77]
	v_mfma_f32_16x16x32_bf16 v[126:129], v[170:173], v[202:205], v[126:129]
	v_mfma_f32_16x16x32_bf16 v[122:125], v[178:181], v[202:205], v[122:125]
	v_mfma_f32_16x16x32_bf16 v[114:117], v[170:173], v[210:213], v[114:117]
	v_mfma_f32_16x16x32_bf16 v[106:109], v[178:181], v[210:213], v[106:109]
	v_mfma_f32_16x16x32_bf16 v[98:101], v[170:173], v[218:221], v[98:101]
	v_mfma_f32_16x16x32_bf16 v[90:93], v[178:181], v[218:221], v[90:93]
	v_mfma_f32_16x16x32_bf16 v[82:85], v[170:173], v[226:229], v[82:85]
	v_mfma_f32_16x16x32_bf16 v[74:77], v[178:181], v[226:229], v[74:77]
	s_setprio 0
	s_setprio 1
	v_mfma_f32_16x16x32_bf16 v[118:121], v[182:185], v[198:201], v[118:121]
	v_mfma_f32_16x16x32_bf16 v[110:113], v[190:193], v[198:201], v[110:113]
	v_mfma_f32_16x16x32_bf16 v[102:105], v[182:185], v[206:209], v[102:105]
	v_mfma_f32_16x16x32_bf16 v[94:97], v[190:193], v[206:209], v[94:97]
	v_mfma_f32_16x16x32_bf16 v[86:89], v[182:185], v[214:217], v[86:89]
	v_mfma_f32_16x16x32_bf16 v[78:81], v[190:193], v[214:217], v[78:81]
	v_mfma_f32_16x16x32_bf16 v[70:73], v[182:185], v[222:225], v[70:73]
	v_mfma_f32_16x16x32_bf16 v[66:69], v[190:193], v[222:225], v[66:69]
	v_mfma_f32_16x16x32_bf16 v[118:121], v[186:189], v[202:205], v[118:121]
	v_mfma_f32_16x16x32_bf16 v[110:113], v[194:197], v[202:205], v[110:113]
	v_mfma_f32_16x16x32_bf16 v[102:105], v[186:189], v[210:213], v[102:105]
	v_mfma_f32_16x16x32_bf16 v[94:97], v[194:197], v[210:213], v[94:97]
	v_mfma_f32_16x16x32_bf16 v[86:89], v[186:189], v[218:221], v[86:89]
	v_mfma_f32_16x16x32_bf16 v[78:81], v[194:197], v[218:221], v[78:81]
	v_mfma_f32_16x16x32_bf16 v[70:73], v[186:189], v[226:229], v[70:73]
	v_mfma_f32_16x16x32_bf16 v[66:69], v[194:197], v[226:229], v[66:69]
	s_setprio 0
	s_barrier
	s_add_i32 s54, s46, s36
	v_lshl_add_u64 v[230:231], s[28:29], 0, v[134:135]
	s_mov_b32 m0, s54
	ds_read_b128 v[198:201], v168 offset:16384
	ds_read_b128 v[202:205], v168 offset:17408
	ds_read_b128 v[206:209], v168 offset:18432
	ds_read_b128 v[210:213], v168 offset:19456
	ds_read_b128 v[214:217], v168 offset:20480
	ds_read_b128 v[218:221], v168 offset:21504
	ds_read_b128 v[222:225], v168 offset:22528
	ds_read_b128 v[226:229], v168 offset:23552
	global_load_lds_dwordx4 v[230:231], off
	s_add_i32 m0, s54, 0x2000
	s_add_u32 s54, s28, 0x40000
	v_lshl_add_u64 v[232:233], s[28:29], 0, v[130:131]
	s_addc_u32 s55, s29, 0
	s_add_i32 s56, s47, s36
	global_load_lds_dwordx4 v[232:233], off
	v_lshl_add_u64 v[234:235], s[54:55], 0, v[134:135]
	s_mov_b32 m0, s56
	v_lshl_add_u64 v[236:237], s[30:31], 0, v[132:133]
	global_load_lds_dwordx4 v[234:235], off
	v_lshl_add_u64 v[234:235], s[54:55], 0, v[130:131]
	s_add_i32 m0, s56, 0x2000
	s_nop 0
	global_load_lds_dwordx4 v[234:235], off
	v_lshl_add_u64 v[234:235], s[30:31], 0, v[136:137]
	s_mov_b32 m0, s25
	s_nop 0
	global_load_lds_dwordx4 v[234:235], off
	s_mov_b32 m0, s38
	s_nop 0
	global_load_lds_dwordx4 v[236:237], off
	s_waitcnt vmcnt(8)
	s_waitcnt lgkmcnt(0)
	s_barrier
	s_setprio 1
	s_waitcnt lgkmcnt(0)
	v_mfma_f32_16x16x32_bf16 v[62:65], v[148:151], v[198:201], v[62:65]
	v_mfma_f32_16x16x32_bf16 v[58:61], v[174:177], v[198:201], v[58:61]
	v_mfma_f32_16x16x32_bf16 v[50:53], v[148:151], v[206:209], v[50:53]
	v_mfma_f32_16x16x32_bf16 v[42:45], v[174:177], v[206:209], v[42:45]
	v_mfma_f32_16x16x32_bf16 v[34:37], v[148:151], v[214:217], v[34:37]
	v_mfma_f32_16x16x32_bf16 v[26:29], v[174:177], v[214:217], v[26:29]
	v_mfma_f32_16x16x32_bf16 v[18:21], v[148:151], v[222:225], v[18:21]
	v_mfma_f32_16x16x32_bf16 v[10:13], v[174:177], v[222:225], v[10:13]
	v_mfma_f32_16x16x32_bf16 v[62:65], v[170:173], v[202:205], v[62:65]
	v_mfma_f32_16x16x32_bf16 v[58:61], v[178:181], v[202:205], v[58:61]
	v_mfma_f32_16x16x32_bf16 v[50:53], v[170:173], v[210:213], v[50:53]
	v_mfma_f32_16x16x32_bf16 v[42:45], v[178:181], v[210:213], v[42:45]
	v_mfma_f32_16x16x32_bf16 v[34:37], v[170:173], v[218:221], v[34:37]
	v_mfma_f32_16x16x32_bf16 v[26:29], v[178:181], v[218:221], v[26:29]
	v_mfma_f32_16x16x32_bf16 v[18:21], v[170:173], v[226:229], v[18:21]
	v_mfma_f32_16x16x32_bf16 v[10:13], v[178:181], v[226:229], v[10:13]
	s_setprio 0
	s_setprio 1
	v_mfma_f32_16x16x32_bf16 v[54:57], v[182:185], v[198:201], v[54:57]
	v_mfma_f32_16x16x32_bf16 v[46:49], v[190:193], v[198:201], v[46:49]
	v_mfma_f32_16x16x32_bf16 v[38:41], v[182:185], v[206:209], v[38:41]
	v_mfma_f32_16x16x32_bf16 v[30:33], v[190:193], v[206:209], v[30:33]
	v_mfma_f32_16x16x32_bf16 v[22:25], v[182:185], v[214:217], v[22:25]
	v_mfma_f32_16x16x32_bf16 v[14:17], v[190:193], v[214:217], v[14:17]
	v_mfma_f32_16x16x32_bf16 v[6:9], v[182:185], v[222:225], v[6:9]
	v_mfma_f32_16x16x32_bf16 v[2:5], v[190:193], v[222:225], v[2:5]
	v_mfma_f32_16x16x32_bf16 v[54:57], v[186:189], v[202:205], v[54:57]
	v_mfma_f32_16x16x32_bf16 v[46:49], v[194:197], v[202:205], v[46:49]
	v_mfma_f32_16x16x32_bf16 v[38:41], v[186:189], v[210:213], v[38:41]
	v_mfma_f32_16x16x32_bf16 v[30:33], v[194:197], v[210:213], v[30:33]
	v_mfma_f32_16x16x32_bf16 v[22:25], v[186:189], v[218:221], v[22:25]
	v_mfma_f32_16x16x32_bf16 v[14:17], v[194:197], v[218:221], v[14:17]
	v_mfma_f32_16x16x32_bf16 v[6:9], v[186:189], v[226:229], v[6:9]
	v_mfma_f32_16x16x32_bf16 v[2:5], v[194:197], v[226:229], v[2:5]
	s_setprio 0
	s_barrier
	s_add_i32 s54, 0, 0x18000
	v_add_u32_e32 v146, s54, v164
	s_add_i32 s55, 0, 0x1c000
	ds_read_b128 v[148:151], v146
	ds_read_b128 v[170:173], v146 offset:1024
	ds_read_b128 v[174:177], v146 offset:2048
	ds_read_b128 v[178:181], v146 offset:3072
	v_add_u32_e32 v146, s55, v164
	ds_read_b128 v[182:185], v146
	ds_read_b128 v[186:189], v146 offset:1024
	ds_read_b128 v[190:193], v146 offset:2048
	ds_read_b128 v[194:197], v146 offset:3072
	s_add_u32 s30, s30, 0x40000
	s_addc_u32 s31, s31, 0
	s_mov_b32 m0, s39
	v_lshl_add_u64 v[238:239], s[30:31], 0, v[136:137]
	ds_read_b128 v[198:201], v168 offset:32768
	ds_read_b128 v[202:205], v168 offset:33792
	ds_read_b128 v[206:209], v168 offset:34816
	ds_read_b128 v[210:213], v168 offset:35840
	ds_read_b128 v[214:217], v168 offset:36864
	ds_read_b128 v[218:221], v168 offset:37888
	ds_read_b128 v[222:225], v168 offset:38912
	ds_read_b128 v[226:229], v168 offset:39936
	global_load_lds_dwordx4 v[238:239], off
	v_lshl_add_u64 v[238:239], s[30:31], 0, v[132:133]
	s_mov_b32 m0, s40
	s_nop 0
	global_load_lds_dwordx4 v[238:239], off
	s_waitcnt vmcnt(8)
	s_waitcnt lgkmcnt(0)
	s_barrier
	s_setprio 1
	s_waitcnt lgkmcnt(0)
	v_mfma_f32_16x16x32_bf16 v[126:129], v[148:151], v[198:201], v[126:129]
	v_mfma_f32_16x16x32_bf16 v[122:125], v[174:177], v[198:201], v[122:125]
	v_mfma_f32_16x16x32_bf16 v[114:117], v[148:151], v[206:209], v[114:117]
	v_mfma_f32_16x16x32_bf16 v[106:109], v[174:177], v[206:209], v[106:109]
	v_mfma_f32_16x16x32_bf16 v[98:101], v[148:151], v[214:217], v[98:101]
	v_mfma_f32_16x16x32_bf16 v[90:93], v[174:177], v[214:217], v[90:93]
	v_mfma_f32_16x16x32_bf16 v[82:85], v[148:151], v[222:225], v[82:85]
	v_mfma_f32_16x16x32_bf16 v[74:77], v[174:177], v[222:225], v[74:77]
	v_mfma_f32_16x16x32_bf16 v[126:129], v[170:173], v[202:205], v[126:129]
	v_mfma_f32_16x16x32_bf16 v[122:125], v[178:181], v[202:205], v[122:125]
	v_mfma_f32_16x16x32_bf16 v[114:117], v[170:173], v[210:213], v[114:117]
	v_mfma_f32_16x16x32_bf16 v[106:109], v[178:181], v[210:213], v[106:109]
	v_mfma_f32_16x16x32_bf16 v[98:101], v[170:173], v[218:221], v[98:101]
	v_mfma_f32_16x16x32_bf16 v[90:93], v[178:181], v[218:221], v[90:93]
	v_mfma_f32_16x16x32_bf16 v[82:85], v[170:173], v[226:229], v[82:85]
	v_mfma_f32_16x16x32_bf16 v[74:77], v[178:181], v[226:229], v[74:77]
	s_setprio 0
	s_setprio 1
	v_mfma_f32_16x16x32_bf16 v[118:121], v[182:185], v[198:201], v[118:121]
	v_mfma_f32_16x16x32_bf16 v[110:113], v[190:193], v[198:201], v[110:113]
	v_mfma_f32_16x16x32_bf16 v[102:105], v[182:185], v[206:209], v[102:105]
	v_mfma_f32_16x16x32_bf16 v[94:97], v[190:193], v[206:209], v[94:97]
	v_mfma_f32_16x16x32_bf16 v[86:89], v[182:185], v[214:217], v[86:89]
	v_mfma_f32_16x16x32_bf16 v[78:81], v[190:193], v[214:217], v[78:81]
	v_mfma_f32_16x16x32_bf16 v[70:73], v[182:185], v[222:225], v[70:73]
	v_mfma_f32_16x16x32_bf16 v[66:69], v[190:193], v[222:225], v[66:69]
	v_mfma_f32_16x16x32_bf16 v[118:121], v[186:189], v[202:205], v[118:121]
	v_mfma_f32_16x16x32_bf16 v[110:113], v[194:197], v[202:205], v[110:113]
	v_mfma_f32_16x16x32_bf16 v[102:105], v[186:189], v[210:213], v[102:105]
	v_mfma_f32_16x16x32_bf16 v[94:97], v[194:197], v[210:213], v[94:97]
	v_mfma_f32_16x16x32_bf16 v[86:89], v[186:189], v[218:221], v[86:89]
	v_mfma_f32_16x16x32_bf16 v[78:81], v[194:197], v[218:221], v[78:81]
	v_mfma_f32_16x16x32_bf16 v[70:73], v[186:189], v[226:229], v[70:73]
	v_mfma_f32_16x16x32_bf16 v[66:69], v[194:197], v[226:229], v[66:69]
	s_setprio 0
	s_barrier
	s_add_i32 s30, s54, s36
	v_lshl_add_u64 v[230:231], v[230:231], 0, s[12:13]
	s_mov_b32 m0, s30
	ds_read_b128 v[198:201], v168 offset:49152
	ds_read_b128 v[202:205], v168 offset:50176
	ds_read_b128 v[206:209], v168 offset:51200
	ds_read_b128 v[210:213], v168 offset:52224
	ds_read_b128 v[214:217], v168 offset:53248
	ds_read_b128 v[218:221], v168 offset:54272
	ds_read_b128 v[222:225], v168 offset:55296
	ds_read_b128 v[226:229], v168 offset:56320
	global_load_lds_dwordx4 v[230:231], off
	s_add_i32 m0, s30, 0x2000
	s_add_u32 s28, s28, 0x40080
	v_lshl_add_u64 v[230:231], v[232:233], 0, s[12:13]
	s_addc_u32 s29, s29, 0
	s_add_i32 s30, s55, s36
	global_load_lds_dwordx4 v[230:231], off
	v_lshl_add_u64 v[230:231], s[28:29], 0, v[134:135]
	s_mov_b32 m0, s30
	s_nop 0
	global_load_lds_dwordx4 v[230:231], off
	v_lshl_add_u64 v[230:231], s[28:29], 0, v[130:131]
	s_add_i32 m0, s30, 0x2000
	s_nop 0
	global_load_lds_dwordx4 v[230:231], off
	v_lshl_add_u64 v[230:231], v[234:235], 0, s[12:13]
	s_mov_b32 m0, s42
	s_nop 0
	global_load_lds_dwordx4 v[230:231], off
	v_lshl_add_u64 v[230:231], v[236:237], 0, s[12:13]
	s_mov_b32 m0, s43
	s_nop 0
	global_load_lds_dwordx4 v[230:231], off
	s_waitcnt vmcnt(8)
	s_waitcnt lgkmcnt(0)
	s_barrier
	s_setprio 1
	s_waitcnt lgkmcnt(0)
	v_mfma_f32_16x16x32_bf16 v[62:65], v[148:151], v[198:201], v[62:65]
	v_mfma_f32_16x16x32_bf16 v[58:61], v[174:177], v[198:201], v[58:61]
	v_mfma_f32_16x16x32_bf16 v[50:53], v[148:151], v[206:209], v[50:53]
	v_mfma_f32_16x16x32_bf16 v[42:45], v[174:177], v[206:209], v[42:45]
	v_mfma_f32_16x16x32_bf16 v[34:37], v[148:151], v[214:217], v[34:37]
	v_mfma_f32_16x16x32_bf16 v[26:29], v[174:177], v[214:217], v[26:29]
	v_mfma_f32_16x16x32_bf16 v[18:21], v[148:151], v[222:225], v[18:21]
	v_mfma_f32_16x16x32_bf16 v[10:13], v[174:177], v[222:225], v[10:13]
	v_mfma_f32_16x16x32_bf16 v[62:65], v[170:173], v[202:205], v[62:65]
	v_mfma_f32_16x16x32_bf16 v[58:61], v[178:181], v[202:205], v[58:61]
	v_mfma_f32_16x16x32_bf16 v[50:53], v[170:173], v[210:213], v[50:53]
	v_mfma_f32_16x16x32_bf16 v[42:45], v[178:181], v[210:213], v[42:45]
	v_mfma_f32_16x16x32_bf16 v[34:37], v[170:173], v[218:221], v[34:37]
	v_mfma_f32_16x16x32_bf16 v[26:29], v[178:181], v[218:221], v[26:29]
	v_mfma_f32_16x16x32_bf16 v[18:21], v[170:173], v[226:229], v[18:21]
	v_mfma_f32_16x16x32_bf16 v[10:13], v[178:181], v[226:229], v[10:13]
	s_setprio 0
	s_setprio 1
	v_mfma_f32_16x16x32_bf16 v[54:57], v[182:185], v[198:201], v[54:57]
	v_mfma_f32_16x16x32_bf16 v[46:49], v[190:193], v[198:201], v[46:49]
	v_mfma_f32_16x16x32_bf16 v[38:41], v[182:185], v[206:209], v[38:41]
	v_mfma_f32_16x16x32_bf16 v[30:33], v[190:193], v[206:209], v[30:33]
	v_mfma_f32_16x16x32_bf16 v[22:25], v[182:185], v[214:217], v[22:25]
	v_mfma_f32_16x16x32_bf16 v[14:17], v[190:193], v[214:217], v[14:17]
	v_mfma_f32_16x16x32_bf16 v[6:9], v[182:185], v[222:225], v[6:9]
	v_mfma_f32_16x16x32_bf16 v[2:5], v[190:193], v[222:225], v[2:5]
	v_mfma_f32_16x16x32_bf16 v[54:57], v[186:189], v[202:205], v[54:57]
	v_mfma_f32_16x16x32_bf16 v[46:49], v[194:197], v[202:205], v[46:49]
	v_mfma_f32_16x16x32_bf16 v[38:41], v[186:189], v[210:213], v[38:41]
	v_mfma_f32_16x16x32_bf16 v[30:33], v[194:197], v[210:213], v[30:33]
	v_mfma_f32_16x16x32_bf16 v[22:25], v[186:189], v[218:221], v[22:25]
	v_mfma_f32_16x16x32_bf16 v[14:17], v[194:197], v[218:221], v[14:17]
	v_mfma_f32_16x16x32_bf16 v[6:9], v[186:189], v[226:229], v[6:9]
	v_mfma_f32_16x16x32_bf16 v[2:5], v[194:197], v[226:229], v[2:5]
	s_setprio 0
	s_add_i32 s53, s53, 2
	s_add_u32 s26, s26, 0x100
	s_addc_u32 s27, s27, 0
	s_add_u32 s51, s51, 0x100
	s_addc_u32 s52, s52, 0
	s_cmp_gt_u32 s53, 13
	s_barrier
	s_cbranch_scc0 .LBB0_317
	s_and_b64 vcc, exec, s[14:15]
	s_cbranch_vccz .LBB0_320
	s_barrier

.LBB0_341:
	ds_read_b128 v[156:159], v1
	ds_read_b128 v[160:163], v1 offset:1024
	ds_read_b128 v[164:167], v1 offset:2048
	ds_read_b128 v[168:171], v1 offset:3072
	ds_read_b128 v[172:175], v147
	ds_read_b128 v[176:179], v147 offset:1024
	ds_read_b128 v[180:183], v147 offset:2048
	ds_read_b128 v[184:187], v147 offset:3072
	s_add_u32 s38, s36, 0xfffe0080
	s_addc_u32 s39, s37, -1
	s_cmp_eq_u32 s63, 4
	s_cselect_b32 s41, s27, s39
	s_cselect_b32 s40, s59, s38
	s_cselect_b32 s39, s25, s62
	s_cselect_b32 s38, s60, s61
	v_lshl_add_u64 v[148:149], s[36:37], 0, v[138:139]
	s_add_i32 m0, s35, 0xc000
	ds_read_b128 v[188:191], v152
	ds_read_b128 v[192:195], v152 offset:1024
	ds_read_b128 v[196:199], v152 offset:2048
	ds_read_b128 v[200:203], v152 offset:3072
	ds_read_b128 v[204:207], v152 offset:4096
	ds_read_b128 v[208:211], v152 offset:5120
	ds_read_b128 v[212:215], v152 offset:6144
	ds_read_b128 v[216:219], v152 offset:7168
	global_load_lds_dwordx4 v[148:149], off
	v_lshl_add_u64 v[148:149], s[36:37], 0, v[140:141]
	s_add_i32 m0, s35, 0xe000
	s_nop 0
	global_load_lds_dwordx4 v[148:149], off
	s_waitcnt vmcnt(8)
	s_waitcnt lgkmcnt(0)
	s_barrier
	s_setprio 1
	s_waitcnt lgkmcnt(0)
	v_mfma_f32_16x16x32_bf16 v[126:129], v[156:159], v[188:191], v[126:129]
	v_mfma_f32_16x16x32_bf16 v[122:125], v[164:167], v[188:191], v[122:125]
	v_mfma_f32_16x16x32_bf16 v[114:117], v[156:159], v[196:199], v[114:117]
	v_mfma_f32_16x16x32_bf16 v[106:109], v[164:167], v[196:199], v[106:109]
	v_mfma_f32_16x16x32_bf16 v[98:101], v[156:159], v[204:207], v[98:101]
	v_mfma_f32_16x16x32_bf16 v[90:93], v[164:167], v[204:207], v[90:93]
	v_mfma_f32_16x16x32_bf16 v[82:85], v[156:159], v[212:215], v[82:85]
	v_mfma_f32_16x16x32_bf16 v[74:77], v[164:167], v[212:215], v[74:77]
	v_mfma_f32_16x16x32_bf16 v[126:129], v[160:163], v[192:195], v[126:129]
	v_mfma_f32_16x16x32_bf16 v[122:125], v[168:171], v[192:195], v[122:125]
	v_mfma_f32_16x16x32_bf16 v[114:117], v[160:163], v[200:203], v[114:117]
	v_mfma_f32_16x16x32_bf16 v[106:109], v[168:171], v[200:203], v[106:109]
	v_mfma_f32_16x16x32_bf16 v[98:101], v[160:163], v[208:211], v[98:101]
	v_mfma_f32_16x16x32_bf16 v[90:93], v[168:171], v[208:211], v[90:93]
	v_mfma_f32_16x16x32_bf16 v[82:85], v[160:163], v[216:219], v[82:85]
	v_mfma_f32_16x16x32_bf16 v[74:77], v[168:171], v[216:219], v[74:77]
	s_setprio 0
	s_setprio 1
	v_mfma_f32_16x16x32_bf16 v[118:121], v[172:175], v[188:191], v[118:121]
	v_mfma_f32_16x16x32_bf16 v[110:113], v[180:183], v[188:191], v[110:113]
	v_mfma_f32_16x16x32_bf16 v[102:105], v[172:175], v[196:199], v[102:105]
	v_mfma_f32_16x16x32_bf16 v[94:97], v[180:183], v[196:199], v[94:97]
	v_mfma_f32_16x16x32_bf16 v[86:89], v[172:175], v[204:207], v[86:89]
	v_mfma_f32_16x16x32_bf16 v[78:81], v[180:183], v[204:207], v[78:81]
	v_mfma_f32_16x16x32_bf16 v[70:73], v[172:175], v[212:215], v[70:73]
	v_mfma_f32_16x16x32_bf16 v[66:69], v[180:183], v[212:215], v[66:69]
	v_mfma_f32_16x16x32_bf16 v[118:121], v[176:179], v[192:195], v[118:121]
	v_mfma_f32_16x16x32_bf16 v[110:113], v[184:187], v[192:195], v[110:113]
	v_mfma_f32_16x16x32_bf16 v[102:105], v[176:179], v[200:203], v[102:105]
	v_mfma_f32_16x16x32_bf16 v[94:97], v[184:187], v[200:203], v[94:97]
	v_mfma_f32_16x16x32_bf16 v[86:89], v[176:179], v[208:211], v[86:89]
	v_mfma_f32_16x16x32_bf16 v[78:81], v[184:187], v[208:211], v[78:81]
	v_mfma_f32_16x16x32_bf16 v[70:73], v[176:179], v[216:219], v[70:73]
	v_mfma_f32_16x16x32_bf16 v[66:69], v[184:187], v[216:219], v[66:69]
	s_setprio 0
	s_barrier
	s_add_i32 s64, s53, s45
	v_lshl_add_u64 v[148:149], s[38:39], 0, v[132:133]
	s_mov_b32 m0, s64
	ds_read_b128 v[188:191], v152 offset:16384
	ds_read_b128 v[192:195], v152 offset:17408
	ds_read_b128 v[196:199], v152 offset:18432
	ds_read_b128 v[200:203], v152 offset:19456
	ds_read_b128 v[204:207], v152 offset:20480
	ds_read_b128 v[208:211], v152 offset:21504
	ds_read_b128 v[212:215], v152 offset:22528
	ds_read_b128 v[216:219], v152 offset:23552
	global_load_lds_dwordx4 v[148:149], off
	s_add_i32 m0, s64, 0x2000
	s_add_u32 s64, s38, 0x20000
	v_lshl_add_u64 v[220:221], s[38:39], 0, v[136:137]
	s_addc_u32 s65, s39, 0
	s_add_i32 s66, s54, s45
	global_load_lds_dwordx4 v[220:221], off
	v_lshl_add_u64 v[222:223], s[64:65], 0, v[132:133]
	s_mov_b32 m0, s66
	v_lshl_add_u64 v[224:225], s[40:41], 0, v[134:135]
	global_load_lds_dwordx4 v[222:223], off
	v_lshl_add_u64 v[222:223], s[64:65], 0, v[136:137]
	s_add_i32 m0, s66, 0x2000
	s_nop 0
	global_load_lds_dwordx4 v[222:223], off
	v_lshl_add_u64 v[222:223], s[40:41], 0, v[130:131]
	s_mov_b32 m0, s35
	s_nop 0
	global_load_lds_dwordx4 v[222:223], off
	s_mov_b32 m0, s46
	s_nop 0
	global_load_lds_dwordx4 v[224:225], off
	s_waitcnt vmcnt(8)
	s_waitcnt lgkmcnt(0)
	s_barrier
	s_setprio 1
	s_waitcnt lgkmcnt(0)
	v_mfma_f32_16x16x32_bf16 v[62:65], v[156:159], v[188:191], v[62:65]
	v_mfma_f32_16x16x32_bf16 v[58:61], v[164:167], v[188:191], v[58:61]
	v_mfma_f32_16x16x32_bf16 v[50:53], v[156:159], v[196:199], v[50:53]
	v_mfma_f32_16x16x32_bf16 v[42:45], v[164:167], v[196:199], v[42:45]
	v_mfma_f32_16x16x32_bf16 v[34:37], v[156:159], v[204:207], v[34:37]
	v_mfma_f32_16x16x32_bf16 v[26:29], v[164:167], v[204:207], v[26:29]
	v_mfma_f32_16x16x32_bf16 v[18:21], v[156:159], v[212:215], v[18:21]
	v_mfma_f32_16x16x32_bf16 v[10:13], v[164:167], v[212:215], v[10:13]
	v_mfma_f32_16x16x32_bf16 v[62:65], v[160:163], v[192:195], v[62:65]
	v_mfma_f32_16x16x32_bf16 v[58:61], v[168:171], v[192:195], v[58:61]
	v_mfma_f32_16x16x32_bf16 v[50:53], v[160:163], v[200:203], v[50:53]
	v_mfma_f32_16x16x32_bf16 v[42:45], v[168:171], v[200:203], v[42:45]
	v_mfma_f32_16x16x32_bf16 v[34:37], v[160:163], v[208:211], v[34:37]
	v_mfma_f32_16x16x32_bf16 v[26:29], v[168:171], v[208:211], v[26:29]
	v_mfma_f32_16x16x32_bf16 v[18:21], v[160:163], v[216:219], v[18:21]
	v_mfma_f32_16x16x32_bf16 v[10:13], v[168:171], v[216:219], v[10:13]
	s_setprio 0
	s_setprio 1
	v_mfma_f32_16x16x32_bf16 v[54:57], v[172:175], v[188:191], v[54:57]
	v_mfma_f32_16x16x32_bf16 v[46:49], v[180:183], v[188:191], v[46:49]
	v_mfma_f32_16x16x32_bf16 v[38:41], v[172:175], v[196:199], v[38:41]
	v_mfma_f32_16x16x32_bf16 v[30:33], v[180:183], v[196:199], v[30:33]
	v_mfma_f32_16x16x32_bf16 v[22:25], v[172:175], v[204:207], v[22:25]
	v_mfma_f32_16x16x32_bf16 v[14:17], v[180:183], v[204:207], v[14:17]
	v_mfma_f32_16x16x32_bf16 v[6:9], v[172:175], v[212:215], v[6:9]
	v_mfma_f32_16x16x32_bf16 v[2:5], v[180:183], v[212:215], v[2:5]
	v_mfma_f32_16x16x32_bf16 v[54:57], v[176:179], v[192:195], v[54:57]
	v_mfma_f32_16x16x32_bf16 v[46:49], v[184:187], v[192:195], v[46:49]
	v_mfma_f32_16x16x32_bf16 v[38:41], v[176:179], v[200:203], v[38:41]
	v_mfma_f32_16x16x32_bf16 v[30:33], v[184:187], v[200:203], v[30:33]
	v_mfma_f32_16x16x32_bf16 v[22:25], v[176:179], v[208:211], v[22:25]
	v_mfma_f32_16x16x32_bf16 v[14:17], v[184:187], v[208:211], v[14:17]
	v_mfma_f32_16x16x32_bf16 v[6:9], v[176:179], v[216:219], v[6:9]
	v_mfma_f32_16x16x32_bf16 v[2:5], v[184:187], v[216:219], v[2:5]
	s_setprio 0
	s_barrier
	s_add_i32 s64, 0, 0x18000
	v_add_u32_e32 v146, s64, v151
	s_add_i32 s65, 0, 0x1c000
	ds_read_b128 v[156:159], v146
	ds_read_b128 v[160:163], v146 offset:1024
	ds_read_b128 v[164:167], v146 offset:2048
	ds_read_b128 v[168:171], v146 offset:3072
	v_add_u32_e32 v146, s65, v151
	ds_read_b128 v[172:175], v146
	ds_read_b128 v[176:179], v146 offset:1024
	ds_read_b128 v[180:183], v146 offset:2048
	ds_read_b128 v[184:187], v146 offset:3072
	s_add_u32 s40, s40, 0x20000
	s_addc_u32 s41, s41, 0
	s_mov_b32 m0, s47
	v_lshl_add_u64 v[226:227], s[40:41], 0, v[130:131]
	ds_read_b128 v[188:191], v152 offset:32768
	ds_read_b128 v[192:195], v152 offset:33792
	ds_read_b128 v[196:199], v152 offset:34816
	ds_read_b128 v[200:203], v152 offset:35840
	ds_read_b128 v[204:207], v152 offset:36864
	ds_read_b128 v[208:211], v152 offset:37888
	ds_read_b128 v[212:215], v152 offset:38912
	ds_read_b128 v[216:219], v152 offset:39936
	global_load_lds_dwordx4 v[226:227], off
	v_lshl_add_u64 v[226:227], s[40:41], 0, v[134:135]
	s_mov_b32 m0, s48
	s_nop 0
	global_load_lds_dwordx4 v[226:227], off
	s_waitcnt vmcnt(8)
	s_waitcnt lgkmcnt(0)
	s_barrier
	s_setprio 1
	s_waitcnt lgkmcnt(0)
	v_mfma_f32_16x16x32_bf16 v[126:129], v[156:159], v[188:191], v[126:129]
	v_mfma_f32_16x16x32_bf16 v[122:125], v[164:167], v[188:191], v[122:125]
	v_mfma_f32_16x16x32_bf16 v[114:117], v[156:159], v[196:199], v[114:117]
	v_mfma_f32_16x16x32_bf16 v[106:109], v[164:167], v[196:199], v[106:109]
	v_mfma_f32_16x16x32_bf16 v[98:101], v[156:159], v[204:207], v[98:101]
	v_mfma_f32_16x16x32_bf16 v[90:93], v[164:167], v[204:207], v[90:93]
	v_mfma_f32_16x16x32_bf16 v[82:85], v[156:159], v[212:215], v[82:85]
	v_mfma_f32_16x16x32_bf16 v[74:77], v[164:167], v[212:215], v[74:77]
	v_mfma_f32_16x16x32_bf16 v[126:129], v[160:163], v[192:195], v[126:129]
	v_mfma_f32_16x16x32_bf16 v[122:125], v[168:171], v[192:195], v[122:125]
	v_mfma_f32_16x16x32_bf16 v[114:117], v[160:163], v[200:203], v[114:117]
	v_mfma_f32_16x16x32_bf16 v[106:109], v[168:171], v[200:203], v[106:109]
	v_mfma_f32_16x16x32_bf16 v[98:101], v[160:163], v[208:211], v[98:101]
	v_mfma_f32_16x16x32_bf16 v[90:93], v[168:171], v[208:211], v[90:93]
	v_mfma_f32_16x16x32_bf16 v[82:85], v[160:163], v[216:219], v[82:85]
	v_mfma_f32_16x16x32_bf16 v[74:77], v[168:171], v[216:219], v[74:77]
	s_setprio 0
	s_setprio 1
	v_mfma_f32_16x16x32_bf16 v[118:121], v[172:175], v[188:191], v[118:121]
	v_mfma_f32_16x16x32_bf16 v[110:113], v[180:183], v[188:191], v[110:113]
	v_mfma_f32_16x16x32_bf16 v[102:105], v[172:175], v[196:199], v[102:105]
	v_mfma_f32_16x16x32_bf16 v[94:97], v[180:183], v[196:199], v[94:97]
	v_mfma_f32_16x16x32_bf16 v[86:89], v[172:175], v[204:207], v[86:89]
	v_mfma_f32_16x16x32_bf16 v[78:81], v[180:183], v[204:207], v[78:81]
	v_mfma_f32_16x16x32_bf16 v[70:73], v[172:175], v[212:215], v[70:73]
	v_mfma_f32_16x16x32_bf16 v[66:69], v[180:183], v[212:215], v[66:69]
	v_mfma_f32_16x16x32_bf16 v[118:121], v[176:179], v[192:195], v[118:121]
	v_mfma_f32_16x16x32_bf16 v[110:113], v[184:187], v[192:195], v[110:113]
	v_mfma_f32_16x16x32_bf16 v[102:105], v[176:179], v[200:203], v[102:105]
	v_mfma_f32_16x16x32_bf16 v[94:97], v[184:187], v[200:203], v[94:97]
	v_mfma_f32_16x16x32_bf16 v[86:89], v[176:179], v[208:211], v[86:89]
	v_mfma_f32_16x16x32_bf16 v[78:81], v[184:187], v[208:211], v[78:81]
	v_mfma_f32_16x16x32_bf16 v[70:73], v[176:179], v[216:219], v[70:73]
	v_mfma_f32_16x16x32_bf16 v[66:69], v[184:187], v[216:219], v[66:69]
	s_setprio 0
	s_barrier
	s_add_i32 s40, s64, s45
	v_lshl_add_u64 v[148:149], v[148:149], 0, s[12:13]
	s_mov_b32 m0, s40
	ds_read_b128 v[188:191], v152 offset:49152
	ds_read_b128 v[192:195], v152 offset:50176
	ds_read_b128 v[196:199], v152 offset:51200
	ds_read_b128 v[200:203], v152 offset:52224
	ds_read_b128 v[204:207], v152 offset:53248
	ds_read_b128 v[208:211], v152 offset:54272
	ds_read_b128 v[212:215], v152 offset:55296
	ds_read_b128 v[216:219], v152 offset:56320
	global_load_lds_dwordx4 v[148:149], off
	s_add_i32 m0, s40, 0x2000
	s_add_u32 s38, s38, 0x20080
	v_lshl_add_u64 v[148:149], v[220:221], 0, s[12:13]
	s_addc_u32 s39, s39, 0
	s_add_i32 s40, s65, s45
	global_load_lds_dwordx4 v[148:149], off
	v_lshl_add_u64 v[148:149], s[38:39], 0, v[132:133]
	s_mov_b32 m0, s40
	s_nop 0
	global_load_lds_dwordx4 v[148:149], off
	v_lshl_add_u64 v[148:149], s[38:39], 0, v[136:137]
	s_add_i32 m0, s40, 0x2000
	s_nop 0
	global_load_lds_dwordx4 v[148:149], off
	v_lshl_add_u64 v[148:149], v[222:223], 0, s[12:13]
	s_mov_b32 m0, s50
	s_nop 0
	global_load_lds_dwordx4 v[148:149], off
	v_lshl_add_u64 v[148:149], v[224:225], 0, s[12:13]
	s_mov_b32 m0, s51
	s_nop 0
	global_load_lds_dwordx4 v[148:149], off
	s_waitcnt vmcnt(8)
	s_waitcnt lgkmcnt(0)
	s_barrier
	s_setprio 1
	s_waitcnt lgkmcnt(0)
	v_mfma_f32_16x16x32_bf16 v[62:65], v[156:159], v[188:191], v[62:65]
	v_mfma_f32_16x16x32_bf16 v[58:61], v[164:167], v[188:191], v[58:61]
	v_mfma_f32_16x16x32_bf16 v[50:53], v[156:159], v[196:199], v[50:53]
	v_mfma_f32_16x16x32_bf16 v[42:45], v[164:167], v[196:199], v[42:45]
	v_mfma_f32_16x16x32_bf16 v[34:37], v[156:159], v[204:207], v[34:37]
	v_mfma_f32_16x16x32_bf16 v[26:29], v[164:167], v[204:207], v[26:29]
	v_mfma_f32_16x16x32_bf16 v[18:21], v[156:159], v[212:215], v[18:21]
	v_mfma_f32_16x16x32_bf16 v[10:13], v[164:167], v[212:215], v[10:13]
	v_mfma_f32_16x16x32_bf16 v[62:65], v[160:163], v[192:195], v[62:65]
	v_mfma_f32_16x16x32_bf16 v[58:61], v[168:171], v[192:195], v[58:61]
	v_mfma_f32_16x16x32_bf16 v[50:53], v[160:163], v[200:203], v[50:53]
	v_mfma_f32_16x16x32_bf16 v[42:45], v[168:171], v[200:203], v[42:45]
	v_mfma_f32_16x16x32_bf16 v[34:37], v[160:163], v[208:211], v[34:37]
	v_mfma_f32_16x16x32_bf16 v[26:29], v[168:171], v[208:211], v[26:29]
	v_mfma_f32_16x16x32_bf16 v[18:21], v[160:163], v[216:219], v[18:21]
	v_mfma_f32_16x16x32_bf16 v[10:13], v[168:171], v[216:219], v[10:13]
	s_setprio 0
	s_setprio 1
	v_mfma_f32_16x16x32_bf16 v[54:57], v[172:175], v[188:191], v[54:57]
	v_mfma_f32_16x16x32_bf16 v[46:49], v[180:183], v[188:191], v[46:49]
	v_mfma_f32_16x16x32_bf16 v[38:41], v[172:175], v[196:199], v[38:41]
	v_mfma_f32_16x16x32_bf16 v[30:33], v[180:183], v[196:199], v[30:33]
	v_mfma_f32_16x16x32_bf16 v[22:25], v[172:175], v[204:207], v[22:25]
	v_mfma_f32_16x16x32_bf16 v[14:17], v[180:183], v[204:207], v[14:17]
	v_mfma_f32_16x16x32_bf16 v[6:9], v[172:175], v[212:215], v[6:9]
	v_mfma_f32_16x16x32_bf16 v[2:5], v[180:183], v[212:215], v[2:5]
	v_mfma_f32_16x16x32_bf16 v[54:57], v[176:179], v[192:195], v[54:57]
	v_mfma_f32_16x16x32_bf16 v[46:49], v[184:187], v[192:195], v[46:49]
	v_mfma_f32_16x16x32_bf16 v[38:41], v[176:179], v[200:203], v[38:41]
	v_mfma_f32_16x16x32_bf16 v[30:33], v[184:187], v[200:203], v[30:33]
	v_mfma_f32_16x16x32_bf16 v[22:25], v[176:179], v[208:211], v[22:25]
	v_mfma_f32_16x16x32_bf16 v[14:17], v[184:187], v[208:211], v[14:17]
	v_mfma_f32_16x16x32_bf16 v[6:9], v[176:179], v[216:219], v[6:9]
	v_mfma_f32_16x16x32_bf16 v[2:5], v[184:187], v[216:219], v[2:5]
	s_setprio 0
	s_add_i32 s63, s63, 2
	s_add_u32 s36, s36, 0x100
	s_addc_u32 s37, s37, 0
	s_add_u32 s61, s61, 0x100
	s_addc_u32 s62, s62, 0
	s_cmp_gt_u32 s63, 5
	s_barrier
	s_cbranch_scc0 .LBB0_341
	s_and_b64 vcc, exec, s[14:15]
	s_cbranch_vccz .LBB0_344
	s_barrier

.LBB0_728:
	ds_read_b128 v[130:133], v156
	ds_read_b128 v[134:137], v156 offset:1024
	ds_read_b128 v[160:163], v156 offset:2048
	ds_read_b128 v[164:167], v156 offset:3072
	ds_read_b128 v[168:171], v157
	ds_read_b128 v[172:175], v157 offset:1024
	ds_read_b128 v[176:179], v157 offset:2048
	ds_read_b128 v[180:183], v157 offset:3072
	s_add_u32 s28, s26, 0xfff00080
	s_addc_u32 s29, s27, -1
	s_cmp_eq_u32 s48, 60
	s_cselect_b32 s31, s19, s29
	s_cselect_b32 s30, s44, s28
	s_cselect_b32 s29, s17, s47
	s_cselect_b32 s28, s45, s46
	v_lshl_add_u64 v[216:217], s[26:27], 0, v[146:147]
	s_add_i32 m0, s25, 0xc000
	ds_read_b128 v[184:187], v158
	ds_read_b128 v[188:191], v158 offset:1024
	ds_read_b128 v[192:195], v158 offset:2048
	ds_read_b128 v[196:199], v158 offset:3072
	ds_read_b128 v[200:203], v158 offset:4096
	ds_read_b128 v[204:207], v158 offset:5120
	ds_read_b128 v[208:211], v158 offset:6144
	ds_read_b128 v[212:215], v158 offset:7168
	global_load_lds_dwordx4 v[216:217], off
	v_lshl_add_u64 v[216:217], s[26:27], 0, v[148:149]
	s_add_i32 m0, s25, 0xe000
	s_nop 0
	global_load_lds_dwordx4 v[216:217], off
	s_waitcnt vmcnt(8)
	s_waitcnt lgkmcnt(0)
	s_barrier
	s_setprio 1
	s_waitcnt lgkmcnt(0)
	v_mfma_f32_16x16x32_bf16 v[126:129], v[130:133], v[184:187], v[126:129]
	v_mfma_f32_16x16x32_bf16 v[122:125], v[160:163], v[184:187], v[122:125]
	v_mfma_f32_16x16x32_bf16 v[118:121], v[130:133], v[192:195], v[118:121]
	v_mfma_f32_16x16x32_bf16 v[114:117], v[160:163], v[192:195], v[114:117]
	v_mfma_f32_16x16x32_bf16 v[94:97], v[130:133], v[200:203], v[94:97]
	v_mfma_f32_16x16x32_bf16 v[90:93], v[160:163], v[200:203], v[90:93]
	v_mfma_f32_16x16x32_bf16 v[82:85], v[130:133], v[208:211], v[82:85]
	v_mfma_f32_16x16x32_bf16 v[74:77], v[160:163], v[208:211], v[74:77]
	v_mfma_f32_16x16x32_bf16 v[126:129], v[134:137], v[188:191], v[126:129]
	v_mfma_f32_16x16x32_bf16 v[122:125], v[164:167], v[188:191], v[122:125]
	v_mfma_f32_16x16x32_bf16 v[118:121], v[134:137], v[196:199], v[118:121]
	v_mfma_f32_16x16x32_bf16 v[114:117], v[164:167], v[196:199], v[114:117]
	v_mfma_f32_16x16x32_bf16 v[94:97], v[134:137], v[204:207], v[94:97]
	v_mfma_f32_16x16x32_bf16 v[90:93], v[164:167], v[204:207], v[90:93]
	v_mfma_f32_16x16x32_bf16 v[82:85], v[134:137], v[212:215], v[82:85]
	v_mfma_f32_16x16x32_bf16 v[74:77], v[164:167], v[212:215], v[74:77]
	s_setprio 0
	s_setprio 1
	v_mfma_f32_16x16x32_bf16 v[110:113], v[168:171], v[184:187], v[110:113]
	v_mfma_f32_16x16x32_bf16 v[106:109], v[176:179], v[184:187], v[106:109]
	v_mfma_f32_16x16x32_bf16 v[102:105], v[168:171], v[192:195], v[102:105]
	v_mfma_f32_16x16x32_bf16 v[98:101], v[176:179], v[192:195], v[98:101]
	v_mfma_f32_16x16x32_bf16 v[86:89], v[168:171], v[200:203], v[86:89]
	v_mfma_f32_16x16x32_bf16 v[78:81], v[176:179], v[200:203], v[78:81]
	v_mfma_f32_16x16x32_bf16 v[70:73], v[168:171], v[208:211], v[70:73]
	v_mfma_f32_16x16x32_bf16 v[66:69], v[176:179], v[208:211], v[66:69]
	v_mfma_f32_16x16x32_bf16 v[110:113], v[172:175], v[188:191], v[110:113]
	v_mfma_f32_16x16x32_bf16 v[106:109], v[180:183], v[188:191], v[106:109]
	v_mfma_f32_16x16x32_bf16 v[102:105], v[172:175], v[196:199], v[102:105]
	v_mfma_f32_16x16x32_bf16 v[98:101], v[180:183], v[196:199], v[98:101]
	v_mfma_f32_16x16x32_bf16 v[86:89], v[172:175], v[204:207], v[86:89]
	v_mfma_f32_16x16x32_bf16 v[78:81], v[180:183], v[204:207], v[78:81]
	v_mfma_f32_16x16x32_bf16 v[70:73], v[172:175], v[212:215], v[70:73]
	v_mfma_f32_16x16x32_bf16 v[66:69], v[180:183], v[212:215], v[66:69]
	s_setprio 0
	s_barrier
	s_add_i32 s49, s42, s34
	v_lshl_add_u64 v[216:217], s[28:29], 0, v[140:141]
	s_mov_b32 m0, s49
	ds_read_b128 v[184:187], v158 offset:16384
	ds_read_b128 v[188:191], v158 offset:17408
	ds_read_b128 v[192:195], v158 offset:18432
	ds_read_b128 v[196:199], v158 offset:19456
	ds_read_b128 v[200:203], v158 offset:20480
	ds_read_b128 v[204:207], v158 offset:21504
	ds_read_b128 v[208:211], v158 offset:22528
	ds_read_b128 v[212:215], v158 offset:23552
	global_load_lds_dwordx4 v[216:217], off
	s_add_i32 m0, s49, 0x2000
	s_add_u32 s50, s28, 0x100000
	v_lshl_add_u64 v[218:219], s[28:29], 0, v[144:145]
	s_addc_u32 s51, s29, 0
	s_add_i32 s49, s43, s34
	global_load_lds_dwordx4 v[218:219], off
	v_lshl_add_u64 v[220:221], s[50:51], 0, v[140:141]
	s_mov_b32 m0, s49
	v_lshl_add_u64 v[222:223], s[30:31], 0, v[142:143]
	global_load_lds_dwordx4 v[220:221], off
	v_lshl_add_u64 v[220:221], s[50:51], 0, v[144:145]
	s_add_i32 m0, s49, 0x2000
	s_nop 0
	global_load_lds_dwordx4 v[220:221], off
	v_lshl_add_u64 v[220:221], s[30:31], 0, v[138:139]
	s_mov_b32 m0, s25
	s_nop 0
	global_load_lds_dwordx4 v[220:221], off
	s_mov_b32 m0, s35
	s_nop 0
	global_load_lds_dwordx4 v[222:223], off
	s_waitcnt vmcnt(8)
	s_waitcnt lgkmcnt(0)
	s_barrier
	s_setprio 1
	s_waitcnt lgkmcnt(0)
	v_mfma_f32_16x16x32_bf16 v[62:65], v[130:133], v[184:187], v[62:65]
	v_mfma_f32_16x16x32_bf16 v[58:61], v[160:163], v[184:187], v[58:61]
	v_mfma_f32_16x16x32_bf16 v[50:53], v[130:133], v[192:195], v[50:53]
	v_mfma_f32_16x16x32_bf16 v[42:45], v[160:163], v[192:195], v[42:45]
	v_mfma_f32_16x16x32_bf16 v[34:37], v[130:133], v[200:203], v[34:37]
	v_mfma_f32_16x16x32_bf16 v[26:29], v[160:163], v[200:203], v[26:29]
	v_mfma_f32_16x16x32_bf16 v[18:21], v[130:133], v[208:211], v[18:21]
	v_mfma_f32_16x16x32_bf16 v[10:13], v[160:163], v[208:211], v[10:13]
	v_mfma_f32_16x16x32_bf16 v[62:65], v[134:137], v[188:191], v[62:65]
	v_mfma_f32_16x16x32_bf16 v[58:61], v[164:167], v[188:191], v[58:61]
	v_mfma_f32_16x16x32_bf16 v[50:53], v[134:137], v[196:199], v[50:53]
	v_mfma_f32_16x16x32_bf16 v[42:45], v[164:167], v[196:199], v[42:45]
	v_mfma_f32_16x16x32_bf16 v[34:37], v[134:137], v[204:207], v[34:37]
	v_mfma_f32_16x16x32_bf16 v[26:29], v[164:167], v[204:207], v[26:29]
	v_mfma_f32_16x16x32_bf16 v[18:21], v[134:137], v[212:215], v[18:21]
	v_mfma_f32_16x16x32_bf16 v[10:13], v[164:167], v[212:215], v[10:13]
	s_setprio 0
	s_setprio 1
	v_mfma_f32_16x16x32_bf16 v[54:57], v[168:171], v[184:187], v[54:57]
	v_mfma_f32_16x16x32_bf16 v[46:49], v[176:179], v[184:187], v[46:49]
	v_mfma_f32_16x16x32_bf16 v[38:41], v[168:171], v[192:195], v[38:41]
	v_mfma_f32_16x16x32_bf16 v[30:33], v[176:179], v[192:195], v[30:33]
	v_mfma_f32_16x16x32_bf16 v[22:25], v[168:171], v[200:203], v[22:25]
	v_mfma_f32_16x16x32_bf16 v[14:17], v[176:179], v[200:203], v[14:17]
	v_mfma_f32_16x16x32_bf16 v[6:9], v[168:171], v[208:211], v[6:9]
	v_mfma_f32_16x16x32_bf16 v[2:5], v[176:179], v[208:211], v[2:5]
	v_mfma_f32_16x16x32_bf16 v[54:57], v[172:175], v[188:191], v[54:57]
	v_mfma_f32_16x16x32_bf16 v[46:49], v[180:183], v[188:191], v[46:49]
	v_mfma_f32_16x16x32_bf16 v[38:41], v[172:175], v[196:199], v[38:41]
	v_mfma_f32_16x16x32_bf16 v[30:33], v[180:183], v[196:199], v[30:33]
	v_mfma_f32_16x16x32_bf16 v[22:25], v[172:175], v[204:207], v[22:25]
	v_mfma_f32_16x16x32_bf16 v[14:17], v[180:183], v[204:207], v[14:17]
	v_mfma_f32_16x16x32_bf16 v[6:9], v[172:175], v[212:215], v[6:9]
	v_mfma_f32_16x16x32_bf16 v[2:5], v[180:183], v[212:215], v[2:5]
	s_setprio 0
	s_barrier
	s_add_i32 s49, 0, 0x18000
	v_add_u32_e32 v159, s49, v154
	s_add_i32 s50, 0, 0x1c000
	ds_read_b128 v[130:133], v159
	ds_read_b128 v[134:137], v159 offset:1024
	ds_read_b128 v[160:163], v159 offset:2048
	ds_read_b128 v[164:167], v159 offset:3072
	v_add_u32_e32 v159, s50, v154
	ds_read_b128 v[168:171], v159
	ds_read_b128 v[172:175], v159 offset:1024
	ds_read_b128 v[176:179], v159 offset:2048
	ds_read_b128 v[180:183], v159 offset:3072
	s_add_u32 s30, s30, 0x100000
	s_addc_u32 s31, s31, 0
	s_mov_b32 m0, s36
	v_lshl_add_u64 v[224:225], s[30:31], 0, v[138:139]
	ds_read_b128 v[184:187], v158 offset:32768
	ds_read_b128 v[188:191], v158 offset:33792
	ds_read_b128 v[192:195], v158 offset:34816
	ds_read_b128 v[196:199], v158 offset:35840
	ds_read_b128 v[200:203], v158 offset:36864
	ds_read_b128 v[204:207], v158 offset:37888
	ds_read_b128 v[208:211], v158 offset:38912
	ds_read_b128 v[212:215], v158 offset:39936
	global_load_lds_dwordx4 v[224:225], off
	v_lshl_add_u64 v[224:225], s[30:31], 0, v[142:143]
	s_mov_b32 m0, s37
	s_nop 0
	global_load_lds_dwordx4 v[224:225], off
	s_waitcnt vmcnt(8)
	s_waitcnt lgkmcnt(0)
	s_barrier
	s_setprio 1
	s_waitcnt lgkmcnt(0)
	v_mfma_f32_16x16x32_bf16 v[126:129], v[130:133], v[184:187], v[126:129]
	v_mfma_f32_16x16x32_bf16 v[122:125], v[160:163], v[184:187], v[122:125]
	v_mfma_f32_16x16x32_bf16 v[118:121], v[130:133], v[192:195], v[118:121]
	v_mfma_f32_16x16x32_bf16 v[114:117], v[160:163], v[192:195], v[114:117]
	v_mfma_f32_16x16x32_bf16 v[94:97], v[130:133], v[200:203], v[94:97]
	v_mfma_f32_16x16x32_bf16 v[90:93], v[160:163], v[200:203], v[90:93]
	v_mfma_f32_16x16x32_bf16 v[82:85], v[130:133], v[208:211], v[82:85]
	v_mfma_f32_16x16x32_bf16 v[74:77], v[160:163], v[208:211], v[74:77]
	v_mfma_f32_16x16x32_bf16 v[126:129], v[134:137], v[188:191], v[126:129]
	v_mfma_f32_16x16x32_bf16 v[122:125], v[164:167], v[188:191], v[122:125]
	v_mfma_f32_16x16x32_bf16 v[118:121], v[134:137], v[196:199], v[118:121]
	v_mfma_f32_16x16x32_bf16 v[114:117], v[164:167], v[196:199], v[114:117]
	v_mfma_f32_16x16x32_bf16 v[94:97], v[134:137], v[204:207], v[94:97]
	v_mfma_f32_16x16x32_bf16 v[90:93], v[164:167], v[204:207], v[90:93]
	v_mfma_f32_16x16x32_bf16 v[82:85], v[134:137], v[212:215], v[82:85]
	v_mfma_f32_16x16x32_bf16 v[74:77], v[164:167], v[212:215], v[74:77]
	s_setprio 0
	s_setprio 1
	v_mfma_f32_16x16x32_bf16 v[110:113], v[168:171], v[184:187], v[110:113]
	v_mfma_f32_16x16x32_bf16 v[106:109], v[176:179], v[184:187], v[106:109]
	v_mfma_f32_16x16x32_bf16 v[102:105], v[168:171], v[192:195], v[102:105]
	v_mfma_f32_16x16x32_bf16 v[98:101], v[176:179], v[192:195], v[98:101]
	v_mfma_f32_16x16x32_bf16 v[86:89], v[168:171], v[200:203], v[86:89]
	v_mfma_f32_16x16x32_bf16 v[78:81], v[176:179], v[200:203], v[78:81]
	v_mfma_f32_16x16x32_bf16 v[70:73], v[168:171], v[208:211], v[70:73]
	v_mfma_f32_16x16x32_bf16 v[66:69], v[176:179], v[208:211], v[66:69]
	v_mfma_f32_16x16x32_bf16 v[110:113], v[172:175], v[188:191], v[110:113]
	v_mfma_f32_16x16x32_bf16 v[106:109], v[180:183], v[188:191], v[106:109]
	v_mfma_f32_16x16x32_bf16 v[102:105], v[172:175], v[196:199], v[102:105]
	v_mfma_f32_16x16x32_bf16 v[98:101], v[180:183], v[196:199], v[98:101]
	v_mfma_f32_16x16x32_bf16 v[86:89], v[172:175], v[204:207], v[86:89]
	v_mfma_f32_16x16x32_bf16 v[78:81], v[180:183], v[204:207], v[78:81]
	v_mfma_f32_16x16x32_bf16 v[70:73], v[172:175], v[212:215], v[70:73]
	v_mfma_f32_16x16x32_bf16 v[66:69], v[180:183], v[212:215], v[66:69]
	s_setprio 0
	s_barrier
	s_add_i32 s30, s49, s34
	v_lshl_add_u64 v[216:217], v[216:217], 0, s[10:11]
	s_mov_b32 m0, s30
	ds_read_b128 v[184:187], v158 offset:49152
	ds_read_b128 v[188:191], v158 offset:50176
	ds_read_b128 v[192:195], v158 offset:51200
	ds_read_b128 v[196:199], v158 offset:52224
	ds_read_b128 v[200:203], v158 offset:53248
	ds_read_b128 v[204:207], v158 offset:54272
	ds_read_b128 v[208:211], v158 offset:55296
	ds_read_b128 v[212:215], v158 offset:56320
	global_load_lds_dwordx4 v[216:217], off
	s_add_i32 m0, s30, 0x2000
	s_add_u32 s28, s28, 0x100080
	v_lshl_add_u64 v[216:217], v[218:219], 0, s[10:11]
	s_addc_u32 s29, s29, 0
	s_add_i32 s30, s50, s34
	global_load_lds_dwordx4 v[216:217], off
	v_lshl_add_u64 v[216:217], s[28:29], 0, v[140:141]
	s_mov_b32 m0, s30
	s_nop 0
	global_load_lds_dwordx4 v[216:217], off
	v_lshl_add_u64 v[216:217], s[28:29], 0, v[144:145]
	s_add_i32 m0, s30, 0x2000
	s_nop 0
	global_load_lds_dwordx4 v[216:217], off
	v_lshl_add_u64 v[216:217], v[220:221], 0, s[10:11]
	s_mov_b32 m0, s39
	s_nop 0
	global_load_lds_dwordx4 v[216:217], off
	v_lshl_add_u64 v[216:217], v[222:223], 0, s[10:11]
	s_mov_b32 m0, s40
	s_nop 0
	global_load_lds_dwordx4 v[216:217], off
	s_waitcnt vmcnt(8)
	s_waitcnt lgkmcnt(0)
	s_barrier
	s_setprio 1
	s_waitcnt lgkmcnt(0)
	v_mfma_f32_16x16x32_bf16 v[62:65], v[130:133], v[184:187], v[62:65]
	v_mfma_f32_16x16x32_bf16 v[58:61], v[160:163], v[184:187], v[58:61]
	v_mfma_f32_16x16x32_bf16 v[50:53], v[130:133], v[192:195], v[50:53]
	v_mfma_f32_16x16x32_bf16 v[42:45], v[160:163], v[192:195], v[42:45]
	v_mfma_f32_16x16x32_bf16 v[34:37], v[130:133], v[200:203], v[34:37]
	v_mfma_f32_16x16x32_bf16 v[26:29], v[160:163], v[200:203], v[26:29]
	v_mfma_f32_16x16x32_bf16 v[18:21], v[130:133], v[208:211], v[18:21]
	v_mfma_f32_16x16x32_bf16 v[10:13], v[160:163], v[208:211], v[10:13]
	v_mfma_f32_16x16x32_bf16 v[62:65], v[134:137], v[188:191], v[62:65]
	v_mfma_f32_16x16x32_bf16 v[58:61], v[164:167], v[188:191], v[58:61]
	v_mfma_f32_16x16x32_bf16 v[50:53], v[134:137], v[196:199], v[50:53]
	v_mfma_f32_16x16x32_bf16 v[42:45], v[164:167], v[196:199], v[42:45]
	v_mfma_f32_16x16x32_bf16 v[34:37], v[134:137], v[204:207], v[34:37]
	v_mfma_f32_16x16x32_bf16 v[26:29], v[164:167], v[204:207], v[26:29]
	v_mfma_f32_16x16x32_bf16 v[18:21], v[134:137], v[212:215], v[18:21]
	v_mfma_f32_16x16x32_bf16 v[10:13], v[164:167], v[212:215], v[10:13]
	s_setprio 0
	s_setprio 1
	v_mfma_f32_16x16x32_bf16 v[54:57], v[168:171], v[184:187], v[54:57]
	v_mfma_f32_16x16x32_bf16 v[46:49], v[176:179], v[184:187], v[46:49]
	v_mfma_f32_16x16x32_bf16 v[38:41], v[168:171], v[192:195], v[38:41]
	v_mfma_f32_16x16x32_bf16 v[30:33], v[176:179], v[192:195], v[30:33]
	v_mfma_f32_16x16x32_bf16 v[22:25], v[168:171], v[200:203], v[22:25]
	v_mfma_f32_16x16x32_bf16 v[14:17], v[176:179], v[200:203], v[14:17]
	v_mfma_f32_16x16x32_bf16 v[6:9], v[168:171], v[208:211], v[6:9]
	v_mfma_f32_16x16x32_bf16 v[2:5], v[176:179], v[208:211], v[2:5]
	v_mfma_f32_16x16x32_bf16 v[54:57], v[172:175], v[188:191], v[54:57]
	v_mfma_f32_16x16x32_bf16 v[46:49], v[180:183], v[188:191], v[46:49]
	v_mfma_f32_16x16x32_bf16 v[38:41], v[172:175], v[196:199], v[38:41]
	v_mfma_f32_16x16x32_bf16 v[30:33], v[180:183], v[196:199], v[30:33]
	v_mfma_f32_16x16x32_bf16 v[22:25], v[172:175], v[204:207], v[22:25]
	v_mfma_f32_16x16x32_bf16 v[14:17], v[180:183], v[204:207], v[14:17]
	v_mfma_f32_16x16x32_bf16 v[6:9], v[172:175], v[212:215], v[6:9]
	v_mfma_f32_16x16x32_bf16 v[2:5], v[180:183], v[212:215], v[2:5]
	s_setprio 0
	s_add_i32 s48, s48, 2
	s_add_u32 s26, s26, 0x100
	s_addc_u32 s27, s27, 0
	s_add_u32 s46, s46, 0x100
	s_addc_u32 s47, s47, 0
	s_cmp_gt_u32 s48, 61
	s_barrier
	s_cbranch_scc0 .LBB0_728
	s_and_b64 vcc, exec, s[12:13]
	s_cbranch_vccz .LBB0_731
	s_barrier

.LBB0_860:
	ds_read_b128 v[156:159], v153
	ds_read_b128 v[160:163], v153 offset:1024
	ds_read_b128 v[164:167], v153 offset:2048
	ds_read_b128 v[168:171], v153 offset:3072
	ds_read_b128 v[172:175], v154
	ds_read_b128 v[176:179], v154 offset:1024
	ds_read_b128 v[180:183], v154 offset:2048
	ds_read_b128 v[184:187], v154 offset:3072
	s_add_u32 s28, s26, 0xfff00080
	s_addc_u32 s29, s27, -1
	s_cmp_eq_u32 s51, 60
	s_cselect_b32 s31, s19, s29
	s_cselect_b32 s30, s47, s28
	s_cselect_b32 s29, s17, s50
	s_cselect_b32 s28, s48, s49
	v_lshl_add_u64 v[146:147], s[26:27], 0, v[138:139]
	s_add_i32 m0, s25, 0xc000
	ds_read_b128 v[188:191], v155
	ds_read_b128 v[192:195], v155 offset:1024
	ds_read_b128 v[196:199], v155 offset:2048
	ds_read_b128 v[200:203], v155 offset:3072
	ds_read_b128 v[204:207], v155 offset:4096
	ds_read_b128 v[208:211], v155 offset:5120
	ds_read_b128 v[212:215], v155 offset:6144
	ds_read_b128 v[216:219], v155 offset:7168
	global_load_lds_dwordx4 v[146:147], off
	v_lshl_add_u64 v[146:147], s[26:27], 0, v[140:141]
	s_add_i32 m0, s25, 0xe000
	s_nop 0
	global_load_lds_dwordx4 v[146:147], off
	s_waitcnt vmcnt(8)
	s_waitcnt lgkmcnt(0)
	s_barrier
	s_setprio 1
	s_waitcnt lgkmcnt(0)
	v_mfma_f32_16x16x32_bf16 v[126:129], v[156:159], v[188:191], v[126:129]
	v_mfma_f32_16x16x32_bf16 v[122:125], v[164:167], v[188:191], v[122:125]
	v_mfma_f32_16x16x32_bf16 v[110:113], v[156:159], v[196:199], v[110:113]
	v_mfma_f32_16x16x32_bf16 v[106:109], v[164:167], v[196:199], v[106:109]
	v_mfma_f32_16x16x32_bf16 v[94:97], v[156:159], v[204:207], v[94:97]
	v_mfma_f32_16x16x32_bf16 v[90:93], v[164:167], v[204:207], v[90:93]
	v_mfma_f32_16x16x32_bf16 v[78:81], v[156:159], v[212:215], v[78:81]
	v_mfma_f32_16x16x32_bf16 v[74:77], v[164:167], v[212:215], v[74:77]
	v_mfma_f32_16x16x32_bf16 v[126:129], v[160:163], v[192:195], v[126:129]
	v_mfma_f32_16x16x32_bf16 v[122:125], v[168:171], v[192:195], v[122:125]
	v_mfma_f32_16x16x32_bf16 v[110:113], v[160:163], v[200:203], v[110:113]
	v_mfma_f32_16x16x32_bf16 v[106:109], v[168:171], v[200:203], v[106:109]
	v_mfma_f32_16x16x32_bf16 v[94:97], v[160:163], v[208:211], v[94:97]
	v_mfma_f32_16x16x32_bf16 v[90:93], v[168:171], v[208:211], v[90:93]
	v_mfma_f32_16x16x32_bf16 v[78:81], v[160:163], v[216:219], v[78:81]
	v_mfma_f32_16x16x32_bf16 v[74:77], v[168:171], v[216:219], v[74:77]
	s_setprio 0
	s_setprio 1
	v_mfma_f32_16x16x32_bf16 v[118:121], v[172:175], v[188:191], v[118:121]
	v_mfma_f32_16x16x32_bf16 v[114:117], v[180:183], v[188:191], v[114:117]
	v_mfma_f32_16x16x32_bf16 v[102:105], v[172:175], v[196:199], v[102:105]
	v_mfma_f32_16x16x32_bf16 v[98:101], v[180:183], v[196:199], v[98:101]
	v_mfma_f32_16x16x32_bf16 v[86:89], v[172:175], v[204:207], v[86:89]
	v_mfma_f32_16x16x32_bf16 v[82:85], v[180:183], v[204:207], v[82:85]
	v_mfma_f32_16x16x32_bf16 v[70:73], v[172:175], v[212:215], v[70:73]
	v_mfma_f32_16x16x32_bf16 v[66:69], v[180:183], v[212:215], v[66:69]
	v_mfma_f32_16x16x32_bf16 v[118:121], v[176:179], v[192:195], v[118:121]
	v_mfma_f32_16x16x32_bf16 v[114:117], v[184:187], v[192:195], v[114:117]
	v_mfma_f32_16x16x32_bf16 v[102:105], v[176:179], v[200:203], v[102:105]
	v_mfma_f32_16x16x32_bf16 v[98:101], v[184:187], v[200:203], v[98:101]
	v_mfma_f32_16x16x32_bf16 v[86:89], v[176:179], v[208:211], v[86:89]
	v_mfma_f32_16x16x32_bf16 v[82:85], v[184:187], v[208:211], v[82:85]
	v_mfma_f32_16x16x32_bf16 v[70:73], v[176:179], v[216:219], v[70:73]
	v_mfma_f32_16x16x32_bf16 v[66:69], v[184:187], v[216:219], v[66:69]
	s_setprio 0
	s_barrier
	s_add_i32 s52, s44, s34
	v_lshl_add_u64 v[146:147], s[28:29], 0, v[134:135]
	s_mov_b32 m0, s52
	ds_read_b128 v[188:191], v155 offset:16384
	ds_read_b128 v[192:195], v155 offset:17408
	ds_read_b128 v[196:199], v155 offset:18432
	ds_read_b128 v[200:203], v155 offset:19456
	ds_read_b128 v[204:207], v155 offset:20480
	ds_read_b128 v[208:211], v155 offset:21504
	ds_read_b128 v[212:215], v155 offset:22528
	ds_read_b128 v[216:219], v155 offset:23552
	global_load_lds_dwordx4 v[146:147], off
	s_add_i32 m0, s52, 0x2000
	s_add_u32 s52, s28, 0x100000
	v_lshl_add_u64 v[220:221], s[28:29], 0, v[130:131]
	s_addc_u32 s53, s29, 0
	s_add_i32 s54, s45, s34
	global_load_lds_dwordx4 v[220:221], off
	v_lshl_add_u64 v[222:223], s[52:53], 0, v[134:135]
	s_mov_b32 m0, s54
	v_lshl_add_u64 v[224:225], s[30:31], 0, v[132:133]
	global_load_lds_dwordx4 v[222:223], off
	v_lshl_add_u64 v[222:223], s[52:53], 0, v[130:131]
	s_add_i32 m0, s54, 0x2000
	s_nop 0
	global_load_lds_dwordx4 v[222:223], off
	v_lshl_add_u64 v[222:223], s[30:31], 0, v[136:137]
	s_mov_b32 m0, s25
	s_nop 0
	global_load_lds_dwordx4 v[222:223], off
	s_mov_b32 m0, s37
	s_nop 0
	global_load_lds_dwordx4 v[224:225], off
	s_waitcnt vmcnt(8)
	s_waitcnt lgkmcnt(0)
	s_barrier
	s_setprio 1
	s_waitcnt lgkmcnt(0)
	v_mfma_f32_16x16x32_bf16 v[62:65], v[156:159], v[188:191], v[62:65]
	v_mfma_f32_16x16x32_bf16 v[58:61], v[164:167], v[188:191], v[58:61]
	v_mfma_f32_16x16x32_bf16 v[46:49], v[156:159], v[196:199], v[46:49]
	v_mfma_f32_16x16x32_bf16 v[42:45], v[164:167], v[196:199], v[42:45]
	v_mfma_f32_16x16x32_bf16 v[30:33], v[156:159], v[204:207], v[30:33]
	v_mfma_f32_16x16x32_bf16 v[26:29], v[164:167], v[204:207], v[26:29]
	v_mfma_f32_16x16x32_bf16 v[14:17], v[156:159], v[212:215], v[14:17]
	v_mfma_f32_16x16x32_bf16 v[10:13], v[164:167], v[212:215], v[10:13]
	v_mfma_f32_16x16x32_bf16 v[62:65], v[160:163], v[192:195], v[62:65]
	v_mfma_f32_16x16x32_bf16 v[58:61], v[168:171], v[192:195], v[58:61]
	v_mfma_f32_16x16x32_bf16 v[46:49], v[160:163], v[200:203], v[46:49]
	v_mfma_f32_16x16x32_bf16 v[42:45], v[168:171], v[200:203], v[42:45]
	v_mfma_f32_16x16x32_bf16 v[30:33], v[160:163], v[208:211], v[30:33]
	v_mfma_f32_16x16x32_bf16 v[26:29], v[168:171], v[208:211], v[26:29]
	v_mfma_f32_16x16x32_bf16 v[14:17], v[160:163], v[216:219], v[14:17]
	v_mfma_f32_16x16x32_bf16 v[10:13], v[168:171], v[216:219], v[10:13]
	s_setprio 0
	s_setprio 1
	v_mfma_f32_16x16x32_bf16 v[54:57], v[172:175], v[188:191], v[54:57]
	v_mfma_f32_16x16x32_bf16 v[50:53], v[180:183], v[188:191], v[50:53]
	v_mfma_f32_16x16x32_bf16 v[38:41], v[172:175], v[196:199], v[38:41]
	v_mfma_f32_16x16x32_bf16 v[34:37], v[180:183], v[196:199], v[34:37]
	v_mfma_f32_16x16x32_bf16 v[22:25], v[172:175], v[204:207], v[22:25]
	v_mfma_f32_16x16x32_bf16 v[18:21], v[180:183], v[204:207], v[18:21]
	v_mfma_f32_16x16x32_bf16 v[6:9], v[172:175], v[212:215], v[6:9]
	v_mfma_f32_16x16x32_bf16 v[2:5], v[180:183], v[212:215], v[2:5]
	v_mfma_f32_16x16x32_bf16 v[54:57], v[176:179], v[192:195], v[54:57]
	v_mfma_f32_16x16x32_bf16 v[50:53], v[184:187], v[192:195], v[50:53]
	v_mfma_f32_16x16x32_bf16 v[38:41], v[176:179], v[200:203], v[38:41]
	v_mfma_f32_16x16x32_bf16 v[34:37], v[184:187], v[200:203], v[34:37]
	v_mfma_f32_16x16x32_bf16 v[22:25], v[176:179], v[208:211], v[22:25]
	v_mfma_f32_16x16x32_bf16 v[18:21], v[184:187], v[208:211], v[18:21]
	v_mfma_f32_16x16x32_bf16 v[6:9], v[176:179], v[216:219], v[6:9]
	v_mfma_f32_16x16x32_bf16 v[2:5], v[184:187], v[216:219], v[2:5]
	s_setprio 0
	s_barrier
	s_add_i32 s52, 0, 0x18000
	s_add_i32 s53, 0, 0x1c000
	v_add_u32_e32 v168, s52, v151
	v_add_u32_e32 v184, s53, v151
	ds_read_b128 v[156:159], v168
	ds_read_b128 v[160:163], v168 offset:1024
	ds_read_b128 v[164:167], v168 offset:2048
	ds_read_b128 v[168:171], v168 offset:3072
	ds_read_b128 v[172:175], v184
	ds_read_b128 v[176:179], v184 offset:1024
	ds_read_b128 v[180:183], v184 offset:2048
	ds_read_b128 v[184:187], v184 offset:3072
	s_add_u32 s30, s30, 0x100000
	s_addc_u32 s31, s31, 0
	s_mov_b32 m0, s38
	v_lshl_add_u64 v[226:227], s[30:31], 0, v[136:137]
	ds_read_b128 v[188:191], v155 offset:32768
	ds_read_b128 v[192:195], v155 offset:33792
	ds_read_b128 v[196:199], v155 offset:34816
	ds_read_b128 v[200:203], v155 offset:35840
	ds_read_b128 v[204:207], v155 offset:36864
	ds_read_b128 v[208:211], v155 offset:37888
	ds_read_b128 v[212:215], v155 offset:38912
	ds_read_b128 v[216:219], v155 offset:39936
	global_load_lds_dwordx4 v[226:227], off
	v_lshl_add_u64 v[226:227], s[30:31], 0, v[132:133]
	s_mov_b32 m0, s39
	s_nop 0
	global_load_lds_dwordx4 v[226:227], off
	s_waitcnt vmcnt(8)
	s_waitcnt lgkmcnt(0)
	s_barrier
	s_setprio 1
	s_waitcnt lgkmcnt(0)
	v_mfma_f32_16x16x32_bf16 v[126:129], v[156:159], v[188:191], v[126:129]
	v_mfma_f32_16x16x32_bf16 v[122:125], v[164:167], v[188:191], v[122:125]
	v_mfma_f32_16x16x32_bf16 v[110:113], v[156:159], v[196:199], v[110:113]
	v_mfma_f32_16x16x32_bf16 v[106:109], v[164:167], v[196:199], v[106:109]
	v_mfma_f32_16x16x32_bf16 v[94:97], v[156:159], v[204:207], v[94:97]
	v_mfma_f32_16x16x32_bf16 v[90:93], v[164:167], v[204:207], v[90:93]
	v_mfma_f32_16x16x32_bf16 v[78:81], v[156:159], v[212:215], v[78:81]
	v_mfma_f32_16x16x32_bf16 v[74:77], v[164:167], v[212:215], v[74:77]
	v_mfma_f32_16x16x32_bf16 v[126:129], v[160:163], v[192:195], v[126:129]
	v_mfma_f32_16x16x32_bf16 v[122:125], v[168:171], v[192:195], v[122:125]
	v_mfma_f32_16x16x32_bf16 v[110:113], v[160:163], v[200:203], v[110:113]
	v_mfma_f32_16x16x32_bf16 v[106:109], v[168:171], v[200:203], v[106:109]
	v_mfma_f32_16x16x32_bf16 v[94:97], v[160:163], v[208:211], v[94:97]
	v_mfma_f32_16x16x32_bf16 v[90:93], v[168:171], v[208:211], v[90:93]
	v_mfma_f32_16x16x32_bf16 v[78:81], v[160:163], v[216:219], v[78:81]
	v_mfma_f32_16x16x32_bf16 v[74:77], v[168:171], v[216:219], v[74:77]
	s_setprio 0
	s_setprio 1
	v_mfma_f32_16x16x32_bf16 v[118:121], v[172:175], v[188:191], v[118:121]
	v_mfma_f32_16x16x32_bf16 v[114:117], v[180:183], v[188:191], v[114:117]
	v_mfma_f32_16x16x32_bf16 v[102:105], v[172:175], v[196:199], v[102:105]
	v_mfma_f32_16x16x32_bf16 v[98:101], v[180:183], v[196:199], v[98:101]
	v_mfma_f32_16x16x32_bf16 v[86:89], v[172:175], v[204:207], v[86:89]
	v_mfma_f32_16x16x32_bf16 v[82:85], v[180:183], v[204:207], v[82:85]
	v_mfma_f32_16x16x32_bf16 v[70:73], v[172:175], v[212:215], v[70:73]
	v_mfma_f32_16x16x32_bf16 v[66:69], v[180:183], v[212:215], v[66:69]
	v_mfma_f32_16x16x32_bf16 v[118:121], v[176:179], v[192:195], v[118:121]
	v_mfma_f32_16x16x32_bf16 v[114:117], v[184:187], v[192:195], v[114:117]
	v_mfma_f32_16x16x32_bf16 v[102:105], v[176:179], v[200:203], v[102:105]
	v_mfma_f32_16x16x32_bf16 v[98:101], v[184:187], v[200:203], v[98:101]
	v_mfma_f32_16x16x32_bf16 v[86:89], v[176:179], v[208:211], v[86:89]
	v_mfma_f32_16x16x32_bf16 v[82:85], v[184:187], v[208:211], v[82:85]
	v_mfma_f32_16x16x32_bf16 v[70:73], v[176:179], v[216:219], v[70:73]
	v_mfma_f32_16x16x32_bf16 v[66:69], v[184:187], v[216:219], v[66:69]
	s_setprio 0
	s_barrier
	s_add_i32 s30, s52, s34
	v_lshl_add_u64 v[146:147], v[146:147], 0, s[12:13]
	s_mov_b32 m0, s30
	ds_read_b128 v[188:191], v155 offset:49152
	ds_read_b128 v[192:195], v155 offset:50176
	ds_read_b128 v[196:199], v155 offset:51200
	ds_read_b128 v[200:203], v155 offset:52224
	ds_read_b128 v[204:207], v155 offset:53248
	ds_read_b128 v[208:211], v155 offset:54272
	ds_read_b128 v[212:215], v155 offset:55296
	ds_read_b128 v[216:219], v155 offset:56320
	global_load_lds_dwordx4 v[146:147], off
	s_add_i32 m0, s30, 0x2000
	s_add_u32 s28, s28, 0x100080
	v_lshl_add_u64 v[146:147], v[220:221], 0, s[12:13]
	s_addc_u32 s29, s29, 0
	s_add_i32 s30, s53, s34
	global_load_lds_dwordx4 v[146:147], off
	v_lshl_add_u64 v[146:147], s[28:29], 0, v[134:135]
	s_mov_b32 m0, s30
	s_nop 0
	global_load_lds_dwordx4 v[146:147], off
	v_lshl_add_u64 v[146:147], s[28:29], 0, v[130:131]
	s_add_i32 m0, s30, 0x2000
	s_nop 0
	global_load_lds_dwordx4 v[146:147], off
	v_lshl_add_u64 v[146:147], v[222:223], 0, s[12:13]
	s_mov_b32 m0, s41
	s_nop 0
	global_load_lds_dwordx4 v[146:147], off
	v_lshl_add_u64 v[146:147], v[224:225], 0, s[12:13]
	s_mov_b32 m0, s42
	s_nop 0
	global_load_lds_dwordx4 v[146:147], off
	s_waitcnt vmcnt(8)
	s_waitcnt lgkmcnt(0)
	s_barrier
	s_setprio 1
	s_waitcnt lgkmcnt(0)
	v_mfma_f32_16x16x32_bf16 v[62:65], v[156:159], v[188:191], v[62:65]
	v_mfma_f32_16x16x32_bf16 v[58:61], v[164:167], v[188:191], v[58:61]
	v_mfma_f32_16x16x32_bf16 v[46:49], v[156:159], v[196:199], v[46:49]
	v_mfma_f32_16x16x32_bf16 v[42:45], v[164:167], v[196:199], v[42:45]
	v_mfma_f32_16x16x32_bf16 v[30:33], v[156:159], v[204:207], v[30:33]
	v_mfma_f32_16x16x32_bf16 v[26:29], v[164:167], v[204:207], v[26:29]
	v_mfma_f32_16x16x32_bf16 v[14:17], v[156:159], v[212:215], v[14:17]
	v_mfma_f32_16x16x32_bf16 v[10:13], v[164:167], v[212:215], v[10:13]
	v_mfma_f32_16x16x32_bf16 v[62:65], v[160:163], v[192:195], v[62:65]
	v_mfma_f32_16x16x32_bf16 v[58:61], v[168:171], v[192:195], v[58:61]
	v_mfma_f32_16x16x32_bf16 v[46:49], v[160:163], v[200:203], v[46:49]
	v_mfma_f32_16x16x32_bf16 v[42:45], v[168:171], v[200:203], v[42:45]
	v_mfma_f32_16x16x32_bf16 v[30:33], v[160:163], v[208:211], v[30:33]
	v_mfma_f32_16x16x32_bf16 v[26:29], v[168:171], v[208:211], v[26:29]
	v_mfma_f32_16x16x32_bf16 v[14:17], v[160:163], v[216:219], v[14:17]
	v_mfma_f32_16x16x32_bf16 v[10:13], v[168:171], v[216:219], v[10:13]
	s_setprio 0
	s_setprio 1
	v_mfma_f32_16x16x32_bf16 v[54:57], v[172:175], v[188:191], v[54:57]
	v_mfma_f32_16x16x32_bf16 v[50:53], v[180:183], v[188:191], v[50:53]
	v_mfma_f32_16x16x32_bf16 v[38:41], v[172:175], v[196:199], v[38:41]
	v_mfma_f32_16x16x32_bf16 v[34:37], v[180:183], v[196:199], v[34:37]
	v_mfma_f32_16x16x32_bf16 v[22:25], v[172:175], v[204:207], v[22:25]
	v_mfma_f32_16x16x32_bf16 v[18:21], v[180:183], v[204:207], v[18:21]
	v_mfma_f32_16x16x32_bf16 v[6:9], v[172:175], v[212:215], v[6:9]
	v_mfma_f32_16x16x32_bf16 v[2:5], v[180:183], v[212:215], v[2:5]
	v_mfma_f32_16x16x32_bf16 v[54:57], v[176:179], v[192:195], v[54:57]
	v_mfma_f32_16x16x32_bf16 v[50:53], v[184:187], v[192:195], v[50:53]
	v_mfma_f32_16x16x32_bf16 v[38:41], v[176:179], v[200:203], v[38:41]
	v_mfma_f32_16x16x32_bf16 v[34:37], v[184:187], v[200:203], v[34:37]
	v_mfma_f32_16x16x32_bf16 v[22:25], v[176:179], v[208:211], v[22:25]
	v_mfma_f32_16x16x32_bf16 v[18:21], v[184:187], v[208:211], v[18:21]
	v_mfma_f32_16x16x32_bf16 v[6:9], v[176:179], v[216:219], v[6:9]
	v_mfma_f32_16x16x32_bf16 v[2:5], v[184:187], v[216:219], v[2:5]
	s_setprio 0
	s_add_i32 s51, s51, 2
	s_add_u32 s26, s26, 0x100
	s_addc_u32 s27, s27, 0
	s_add_u32 s49, s49, 0x100
	s_addc_u32 s50, s50, 0
	s_cmp_gt_u32 s51, 61
	s_barrier
	s_cbranch_scc0 .LBB0_860
	s_and_b64 vcc, exec, s[14:15]
	s_cbranch_vccz .LBB0_863
	s_barrier

.LBB0_955:
	ds_read_b128 v[130:133], v199
	ds_read_b128 v[134:137], v199 offset:1024
	ds_read_b128 v[138:141], v199 offset:2048
	ds_read_b128 v[142:145], v199 offset:3072
	ds_read_b128 v[146:149], v200
	ds_read_b128 v[166:169], v200 offset:1024
	ds_read_b128 v[170:173], v200 offset:2048
	ds_read_b128 v[174:177], v200 offset:3072
	s_add_u32 s26, s24, 0xffd50080
	s_addc_u32 s27, s25, -1
	s_cmpk_eq_i32 s50, 0xa8
	s_cselect_b32 s29, s9, s27
	s_cselect_b32 s28, s8, s26
	s_cselect_b32 s27, s23, s49
	s_cselect_b32 s26, s22, s48
	v_lshl_add_u64 v[194:195], s[24:25], 0, v[158:159]
	s_add_i32 m0, s35, 0xc000
	ds_read_b128 v[178:181], v201
	ds_read_b128 v[182:185], v201 offset:1024
	ds_read_b128 v[186:189], v201 offset:2048
	ds_read_b128 v[190:193], v201 offset:3072
	ds_read_b128 v[202:205], v201 offset:4096
	ds_read_b128 v[206:209], v201 offset:5120
	ds_read_b128 v[210:213], v201 offset:6144
	ds_read_b128 v[214:217], v201 offset:7168
	global_load_lds_dwordx4 v[194:195], off
	v_lshl_add_u64 v[194:195], s[24:25], 0, v[160:161]
	s_add_i32 m0, s35, 0xe000
	s_nop 0
	global_load_lds_dwordx4 v[194:195], off
	s_waitcnt vmcnt(8)
	s_waitcnt lgkmcnt(0)
	s_barrier
	s_setprio 1
	s_waitcnt lgkmcnt(0)
	v_mfma_f32_16x16x32_bf16 v[126:129], v[130:133], v[178:181], v[126:129]
	v_mfma_f32_16x16x32_bf16 v[122:125], v[138:141], v[178:181], v[122:125]
	v_mfma_f32_16x16x32_bf16 v[118:121], v[130:133], v[186:189], v[118:121]
	v_mfma_f32_16x16x32_bf16 v[114:117], v[138:141], v[186:189], v[114:117]
	v_mfma_f32_16x16x32_bf16 v[110:113], v[130:133], v[202:205], v[110:113]
	v_mfma_f32_16x16x32_bf16 v[106:109], v[138:141], v[202:205], v[106:109]
	v_mfma_f32_16x16x32_bf16 v[102:105], v[130:133], v[210:213], v[102:105]
	v_mfma_f32_16x16x32_bf16 v[98:101], v[138:141], v[210:213], v[98:101]
	v_mfma_f32_16x16x32_bf16 v[126:129], v[134:137], v[182:185], v[126:129]
	v_mfma_f32_16x16x32_bf16 v[122:125], v[142:145], v[182:185], v[122:125]
	v_mfma_f32_16x16x32_bf16 v[118:121], v[134:137], v[190:193], v[118:121]
	v_mfma_f32_16x16x32_bf16 v[114:117], v[142:145], v[190:193], v[114:117]
	v_mfma_f32_16x16x32_bf16 v[110:113], v[134:137], v[206:209], v[110:113]
	v_mfma_f32_16x16x32_bf16 v[106:109], v[142:145], v[206:209], v[106:109]
	v_mfma_f32_16x16x32_bf16 v[102:105], v[134:137], v[214:217], v[102:105]
	v_mfma_f32_16x16x32_bf16 v[98:101], v[142:145], v[214:217], v[98:101]
	s_setprio 0
	s_setprio 1
	v_mfma_f32_16x16x32_bf16 v[62:65], v[146:149], v[178:181], v[62:65]
	v_mfma_f32_16x16x32_bf16 v[58:61], v[170:173], v[178:181], v[58:61]
	v_mfma_f32_16x16x32_bf16 v[54:57], v[146:149], v[186:189], v[54:57]
	v_mfma_f32_16x16x32_bf16 v[50:53], v[170:173], v[186:189], v[50:53]
	v_mfma_f32_16x16x32_bf16 v[46:49], v[146:149], v[202:205], v[46:49]
	v_mfma_f32_16x16x32_bf16 v[42:45], v[170:173], v[202:205], v[42:45]
	v_mfma_f32_16x16x32_bf16 v[38:41], v[146:149], v[210:213], v[38:41]
	v_mfma_f32_16x16x32_bf16 v[34:37], v[170:173], v[210:213], v[34:37]
	v_mfma_f32_16x16x32_bf16 v[62:65], v[166:169], v[182:185], v[62:65]
	v_mfma_f32_16x16x32_bf16 v[58:61], v[174:177], v[182:185], v[58:61]
	v_mfma_f32_16x16x32_bf16 v[54:57], v[166:169], v[190:193], v[54:57]
	v_mfma_f32_16x16x32_bf16 v[50:53], v[174:177], v[190:193], v[50:53]
	v_mfma_f32_16x16x32_bf16 v[46:49], v[166:169], v[206:209], v[46:49]
	v_mfma_f32_16x16x32_bf16 v[42:45], v[174:177], v[206:209], v[42:45]
	v_mfma_f32_16x16x32_bf16 v[38:41], v[166:169], v[214:217], v[38:41]
	v_mfma_f32_16x16x32_bf16 v[34:37], v[174:177], v[214:217], v[34:37]
	s_setprio 0
	s_barrier
	s_add_i32 s51, s43, s34
	v_lshl_add_u64 v[194:195], s[26:27], 0, v[152:153]
	s_mov_b32 m0, s51
	ds_read_b128 v[178:181], v201 offset:16384
	ds_read_b128 v[182:185], v201 offset:17408
	ds_read_b128 v[186:189], v201 offset:18432
	ds_read_b128 v[190:193], v201 offset:19456
	ds_read_b128 v[202:205], v201 offset:20480
	ds_read_b128 v[206:209], v201 offset:21504
	ds_read_b128 v[210:213], v201 offset:22528
	ds_read_b128 v[214:217], v201 offset:23552
	global_load_lds_dwordx4 v[194:195], off
	s_add_i32 m0, s51, 0x2000
	s_add_u32 s52, s26, 0x2b0000
	v_lshl_add_u64 v[218:219], s[26:27], 0, v[156:157]
	s_addc_u32 s53, s27, 0
	s_add_i32 s51, s44, s34
	global_load_lds_dwordx4 v[218:219], off
	v_lshl_add_u64 v[220:221], s[52:53], 0, v[152:153]
	s_mov_b32 m0, s51
	v_lshl_add_u64 v[222:223], s[28:29], 0, v[154:155]
	global_load_lds_dwordx4 v[220:221], off
	v_lshl_add_u64 v[220:221], s[52:53], 0, v[156:157]
	s_add_i32 m0, s51, 0x2000
	s_nop 0
	global_load_lds_dwordx4 v[220:221], off
	v_lshl_add_u64 v[220:221], s[28:29], 0, v[150:151]
	s_mov_b32 m0, s35
	s_nop 0
	global_load_lds_dwordx4 v[220:221], off
	s_mov_b32 m0, s36
	s_nop 0
	global_load_lds_dwordx4 v[222:223], off
	s_waitcnt vmcnt(8)
	s_waitcnt lgkmcnt(0)
	s_barrier
	s_setprio 1
	s_waitcnt lgkmcnt(0)
	v_mfma_f32_16x16x32_bf16 v[94:97], v[130:133], v[178:181], v[94:97]
	v_mfma_f32_16x16x32_bf16 v[90:93], v[138:141], v[178:181], v[90:93]
	v_mfma_f32_16x16x32_bf16 v[86:89], v[130:133], v[186:189], v[86:89]
	v_mfma_f32_16x16x32_bf16 v[82:85], v[138:141], v[186:189], v[82:85]
	v_mfma_f32_16x16x32_bf16 v[78:81], v[130:133], v[202:205], v[78:81]
	v_mfma_f32_16x16x32_bf16 v[74:77], v[138:141], v[202:205], v[74:77]
	v_mfma_f32_16x16x32_bf16 v[70:73], v[130:133], v[210:213], v[70:73]
	v_mfma_f32_16x16x32_bf16 v[66:69], v[138:141], v[210:213], v[66:69]
	v_mfma_f32_16x16x32_bf16 v[94:97], v[134:137], v[182:185], v[94:97]
	v_mfma_f32_16x16x32_bf16 v[90:93], v[142:145], v[182:185], v[90:93]
	v_mfma_f32_16x16x32_bf16 v[86:89], v[134:137], v[190:193], v[86:89]
	v_mfma_f32_16x16x32_bf16 v[82:85], v[142:145], v[190:193], v[82:85]
	v_mfma_f32_16x16x32_bf16 v[78:81], v[134:137], v[206:209], v[78:81]
	v_mfma_f32_16x16x32_bf16 v[74:77], v[142:145], v[206:209], v[74:77]
	v_mfma_f32_16x16x32_bf16 v[70:73], v[134:137], v[214:217], v[70:73]
	v_mfma_f32_16x16x32_bf16 v[66:69], v[142:145], v[214:217], v[66:69]
	s_setprio 0
	s_setprio 1
	v_mfma_f32_16x16x32_bf16 v[30:33], v[146:149], v[178:181], v[30:33]
	v_mfma_f32_16x16x32_bf16 v[26:29], v[170:173], v[178:181], v[26:29]
	v_mfma_f32_16x16x32_bf16 v[22:25], v[146:149], v[186:189], v[22:25]
	v_mfma_f32_16x16x32_bf16 v[18:21], v[170:173], v[186:189], v[18:21]
	v_mfma_f32_16x16x32_bf16 v[14:17], v[146:149], v[202:205], v[14:17]
	v_mfma_f32_16x16x32_bf16 v[10:13], v[170:173], v[202:205], v[10:13]
	v_mfma_f32_16x16x32_bf16 v[6:9], v[146:149], v[210:213], v[6:9]
	v_mfma_f32_16x16x32_bf16 v[2:5], v[170:173], v[210:213], v[2:5]
	v_mfma_f32_16x16x32_bf16 v[30:33], v[166:169], v[182:185], v[30:33]
	v_mfma_f32_16x16x32_bf16 v[26:29], v[174:177], v[182:185], v[26:29]
	v_mfma_f32_16x16x32_bf16 v[22:25], v[166:169], v[190:193], v[22:25]
	v_mfma_f32_16x16x32_bf16 v[18:21], v[174:177], v[190:193], v[18:21]
	v_mfma_f32_16x16x32_bf16 v[14:17], v[166:169], v[206:209], v[14:17]
	v_mfma_f32_16x16x32_bf16 v[10:13], v[174:177], v[206:209], v[10:13]
	v_mfma_f32_16x16x32_bf16 v[6:9], v[166:169], v[214:217], v[6:9]
	v_mfma_f32_16x16x32_bf16 v[2:5], v[174:177], v[214:217], v[2:5]
	s_setprio 0
	s_barrier
	s_add_i32 s51, 0, 0x18000
	s_add_i32 s52, 0, 0x1c000
	v_add_u32_e32 v142, s51, v197
	v_add_u32_e32 v174, s52, v197
	ds_read_b128 v[130:133], v142
	ds_read_b128 v[134:137], v142 offset:1024
	ds_read_b128 v[138:141], v142 offset:2048
	ds_read_b128 v[142:145], v142 offset:3072
	ds_read_b128 v[146:149], v174
	ds_read_b128 v[166:169], v174 offset:1024
	ds_read_b128 v[170:173], v174 offset:2048
	ds_read_b128 v[174:177], v174 offset:3072
	s_add_u32 s28, s28, 0x2b0000
	s_addc_u32 s29, s29, 0
	s_mov_b32 m0, s37
	v_lshl_add_u64 v[224:225], s[28:29], 0, v[150:151]
	ds_read_b128 v[178:181], v201 offset:32768
	ds_read_b128 v[182:185], v201 offset:33792
	ds_read_b128 v[186:189], v201 offset:34816
	ds_read_b128 v[190:193], v201 offset:35840
	ds_read_b128 v[202:205], v201 offset:36864
	ds_read_b128 v[206:209], v201 offset:37888
	ds_read_b128 v[210:213], v201 offset:38912
	ds_read_b128 v[214:217], v201 offset:39936
	global_load_lds_dwordx4 v[224:225], off
	v_lshl_add_u64 v[224:225], s[28:29], 0, v[154:155]
	s_mov_b32 m0, s38
	s_nop 0
	global_load_lds_dwordx4 v[224:225], off
	s_waitcnt vmcnt(8)
	s_waitcnt lgkmcnt(0)
	s_barrier
	s_setprio 1
	s_waitcnt lgkmcnt(0)
	v_mfma_f32_16x16x32_bf16 v[126:129], v[130:133], v[178:181], v[126:129]
	v_mfma_f32_16x16x32_bf16 v[122:125], v[138:141], v[178:181], v[122:125]
	v_mfma_f32_16x16x32_bf16 v[118:121], v[130:133], v[186:189], v[118:121]
	v_mfma_f32_16x16x32_bf16 v[114:117], v[138:141], v[186:189], v[114:117]
	v_mfma_f32_16x16x32_bf16 v[110:113], v[130:133], v[202:205], v[110:113]
	v_mfma_f32_16x16x32_bf16 v[106:109], v[138:141], v[202:205], v[106:109]
	v_mfma_f32_16x16x32_bf16 v[102:105], v[130:133], v[210:213], v[102:105]
	v_mfma_f32_16x16x32_bf16 v[98:101], v[138:141], v[210:213], v[98:101]
	v_mfma_f32_16x16x32_bf16 v[126:129], v[134:137], v[182:185], v[126:129]
	v_mfma_f32_16x16x32_bf16 v[122:125], v[142:145], v[182:185], v[122:125]
	v_mfma_f32_16x16x32_bf16 v[118:121], v[134:137], v[190:193], v[118:121]
	v_mfma_f32_16x16x32_bf16 v[114:117], v[142:145], v[190:193], v[114:117]
	v_mfma_f32_16x16x32_bf16 v[110:113], v[134:137], v[206:209], v[110:113]
	v_mfma_f32_16x16x32_bf16 v[106:109], v[142:145], v[206:209], v[106:109]
	v_mfma_f32_16x16x32_bf16 v[102:105], v[134:137], v[214:217], v[102:105]
	v_mfma_f32_16x16x32_bf16 v[98:101], v[142:145], v[214:217], v[98:101]
	s_setprio 0
	s_setprio 1
	v_mfma_f32_16x16x32_bf16 v[62:65], v[146:149], v[178:181], v[62:65]
	v_mfma_f32_16x16x32_bf16 v[58:61], v[170:173], v[178:181], v[58:61]
	v_mfma_f32_16x16x32_bf16 v[54:57], v[146:149], v[186:189], v[54:57]
	v_mfma_f32_16x16x32_bf16 v[50:53], v[170:173], v[186:189], v[50:53]
	v_mfma_f32_16x16x32_bf16 v[46:49], v[146:149], v[202:205], v[46:49]
	v_mfma_f32_16x16x32_bf16 v[42:45], v[170:173], v[202:205], v[42:45]
	v_mfma_f32_16x16x32_bf16 v[38:41], v[146:149], v[210:213], v[38:41]
	v_mfma_f32_16x16x32_bf16 v[34:37], v[170:173], v[210:213], v[34:37]
	v_mfma_f32_16x16x32_bf16 v[62:65], v[166:169], v[182:185], v[62:65]
	v_mfma_f32_16x16x32_bf16 v[58:61], v[174:177], v[182:185], v[58:61]
	v_mfma_f32_16x16x32_bf16 v[54:57], v[166:169], v[190:193], v[54:57]
	v_mfma_f32_16x16x32_bf16 v[50:53], v[174:177], v[190:193], v[50:53]
	v_mfma_f32_16x16x32_bf16 v[46:49], v[166:169], v[206:209], v[46:49]
	v_mfma_f32_16x16x32_bf16 v[42:45], v[174:177], v[206:209], v[42:45]
	v_mfma_f32_16x16x32_bf16 v[38:41], v[166:169], v[214:217], v[38:41]
	v_mfma_f32_16x16x32_bf16 v[34:37], v[174:177], v[214:217], v[34:37]
	s_setprio 0
	s_barrier
	s_add_i32 s28, s51, s34
	v_lshl_add_u64 v[194:195], v[194:195], 0, s[16:17]
	s_mov_b32 m0, s28
	ds_read_b128 v[178:181], v201 offset:49152
	ds_read_b128 v[182:185], v201 offset:50176
	ds_read_b128 v[186:189], v201 offset:51200
	ds_read_b128 v[190:193], v201 offset:52224
	ds_read_b128 v[202:205], v201 offset:53248
	ds_read_b128 v[206:209], v201 offset:54272
	ds_read_b128 v[210:213], v201 offset:55296
	ds_read_b128 v[214:217], v201 offset:56320
	global_load_lds_dwordx4 v[194:195], off
	s_add_i32 m0, s28, 0x2000
	s_add_u32 s26, s26, 0x2b0080
	v_lshl_add_u64 v[194:195], v[218:219], 0, s[16:17]
	s_addc_u32 s27, s27, 0
	s_add_i32 s28, s52, s34
	global_load_lds_dwordx4 v[194:195], off
	v_lshl_add_u64 v[194:195], s[26:27], 0, v[152:153]
	s_mov_b32 m0, s28
	s_nop 0
	global_load_lds_dwordx4 v[194:195], off
	v_lshl_add_u64 v[194:195], s[26:27], 0, v[156:157]
	s_add_i32 m0, s28, 0x2000
	s_nop 0
	global_load_lds_dwordx4 v[194:195], off
	v_lshl_add_u64 v[194:195], v[220:221], 0, s[16:17]
	s_mov_b32 m0, s40
	s_nop 0
	global_load_lds_dwordx4 v[194:195], off
	v_lshl_add_u64 v[194:195], v[222:223], 0, s[16:17]
	s_mov_b32 m0, s41
	s_nop 0
	global_load_lds_dwordx4 v[194:195], off
	s_waitcnt vmcnt(8)
	s_waitcnt lgkmcnt(0)
	s_barrier
	s_setprio 1
	s_waitcnt lgkmcnt(0)
	v_mfma_f32_16x16x32_bf16 v[94:97], v[130:133], v[178:181], v[94:97]
	v_mfma_f32_16x16x32_bf16 v[90:93], v[138:141], v[178:181], v[90:93]
	v_mfma_f32_16x16x32_bf16 v[86:89], v[130:133], v[186:189], v[86:89]
	v_mfma_f32_16x16x32_bf16 v[82:85], v[138:141], v[186:189], v[82:85]
	v_mfma_f32_16x16x32_bf16 v[78:81], v[130:133], v[202:205], v[78:81]
	v_mfma_f32_16x16x32_bf16 v[74:77], v[138:141], v[202:205], v[74:77]
	v_mfma_f32_16x16x32_bf16 v[70:73], v[130:133], v[210:213], v[70:73]
	v_mfma_f32_16x16x32_bf16 v[66:69], v[138:141], v[210:213], v[66:69]
	v_mfma_f32_16x16x32_bf16 v[94:97], v[134:137], v[182:185], v[94:97]
	v_mfma_f32_16x16x32_bf16 v[90:93], v[142:145], v[182:185], v[90:93]
	v_mfma_f32_16x16x32_bf16 v[86:89], v[134:137], v[190:193], v[86:89]
	v_mfma_f32_16x16x32_bf16 v[82:85], v[142:145], v[190:193], v[82:85]
	v_mfma_f32_16x16x32_bf16 v[78:81], v[134:137], v[206:209], v[78:81]
	v_mfma_f32_16x16x32_bf16 v[74:77], v[142:145], v[206:209], v[74:77]
	v_mfma_f32_16x16x32_bf16 v[70:73], v[134:137], v[214:217], v[70:73]
	v_mfma_f32_16x16x32_bf16 v[66:69], v[142:145], v[214:217], v[66:69]
	s_setprio 0
	s_setprio 1
	v_mfma_f32_16x16x32_bf16 v[30:33], v[146:149], v[178:181], v[30:33]
	v_mfma_f32_16x16x32_bf16 v[26:29], v[170:173], v[178:181], v[26:29]
	v_mfma_f32_16x16x32_bf16 v[22:25], v[146:149], v[186:189], v[22:25]
	v_mfma_f32_16x16x32_bf16 v[18:21], v[170:173], v[186:189], v[18:21]
	v_mfma_f32_16x16x32_bf16 v[14:17], v[146:149], v[202:205], v[14:17]
	v_mfma_f32_16x16x32_bf16 v[10:13], v[170:173], v[202:205], v[10:13]
	v_mfma_f32_16x16x32_bf16 v[6:9], v[146:149], v[210:213], v[6:9]
	v_mfma_f32_16x16x32_bf16 v[2:5], v[170:173], v[210:213], v[2:5]
	v_mfma_f32_16x16x32_bf16 v[30:33], v[166:169], v[182:185], v[30:33]
	v_mfma_f32_16x16x32_bf16 v[26:29], v[174:177], v[182:185], v[26:29]
	v_mfma_f32_16x16x32_bf16 v[22:25], v[166:169], v[190:193], v[22:25]
	v_mfma_f32_16x16x32_bf16 v[18:21], v[174:177], v[190:193], v[18:21]
	v_mfma_f32_16x16x32_bf16 v[14:17], v[166:169], v[206:209], v[14:17]
	v_mfma_f32_16x16x32_bf16 v[10:13], v[174:177], v[206:209], v[10:13]
	v_mfma_f32_16x16x32_bf16 v[6:9], v[166:169], v[214:217], v[6:9]
	v_mfma_f32_16x16x32_bf16 v[2:5], v[174:177], v[214:217], v[2:5]
	s_setprio 0
	s_add_i32 s50, s50, 2
	s_add_u32 s24, s24, 0x100
	s_addc_u32 s25, s25, 0
	s_add_u32 s48, s48, 0x100
	s_addc_u32 s49, s49, 0
	s_cmpk_gt_u32 s50, 0xa9
	s_barrier
	s_cbranch_scc0 .LBB0_955
	s_and_b64 vcc, exec, s[18:19]
	s_cbranch_vccz .LBB0_958
	s_barrier

.LBB0_1087:
	ds_read_b128 v[148:151], v156
	ds_read_b128 v[160:163], v156 offset:1024
	ds_read_b128 v[164:167], v156 offset:2048
	ds_read_b128 v[168:171], v156 offset:3072
	ds_read_b128 v[172:175], v157
	ds_read_b128 v[176:179], v157 offset:1024
	ds_read_b128 v[180:183], v157 offset:2048
	ds_read_b128 v[184:187], v157 offset:3072
	s_add_u32 s28, s26, 0xfff00080
	s_addc_u32 s29, s27, -1
	s_cmp_eq_u32 s51, 60
	s_cselect_b32 s31, s19, s29
	s_cselect_b32 s30, s47, s28
	s_cselect_b32 s29, s17, s50
	s_cselect_b32 s28, s48, s49
	v_lshl_add_u64 v[220:221], s[26:27], 0, v[138:139]
	s_add_i32 m0, s25, 0xc000
	ds_read_b128 v[188:191], v158
	ds_read_b128 v[192:195], v158 offset:1024
	ds_read_b128 v[196:199], v158 offset:2048
	ds_read_b128 v[200:203], v158 offset:3072
	ds_read_b128 v[204:207], v158 offset:4096
	ds_read_b128 v[208:211], v158 offset:5120
	ds_read_b128 v[212:215], v158 offset:6144
	ds_read_b128 v[216:219], v158 offset:7168
	global_load_lds_dwordx4 v[220:221], off
	v_lshl_add_u64 v[220:221], s[26:27], 0, v[140:141]
	s_add_i32 m0, s25, 0xe000
	s_nop 0
	global_load_lds_dwordx4 v[220:221], off
	s_waitcnt vmcnt(8)
	s_waitcnt lgkmcnt(0)
	s_barrier
	s_setprio 1
	s_waitcnt lgkmcnt(0)
	v_mfma_f32_16x16x32_bf16 v[126:129], v[148:151], v[188:191], v[126:129]
	v_mfma_f32_16x16x32_bf16 v[122:125], v[164:167], v[188:191], v[122:125]
	v_mfma_f32_16x16x32_bf16 v[114:117], v[148:151], v[196:199], v[114:117]
	v_mfma_f32_16x16x32_bf16 v[106:109], v[164:167], v[196:199], v[106:109]
	v_mfma_f32_16x16x32_bf16 v[98:101], v[148:151], v[204:207], v[98:101]
	v_mfma_f32_16x16x32_bf16 v[90:93], v[164:167], v[204:207], v[90:93]
	v_mfma_f32_16x16x32_bf16 v[82:85], v[148:151], v[212:215], v[82:85]
	v_mfma_f32_16x16x32_bf16 v[74:77], v[164:167], v[212:215], v[74:77]
	v_mfma_f32_16x16x32_bf16 v[126:129], v[160:163], v[192:195], v[126:129]
	v_mfma_f32_16x16x32_bf16 v[122:125], v[168:171], v[192:195], v[122:125]
	v_mfma_f32_16x16x32_bf16 v[114:117], v[160:163], v[200:203], v[114:117]
	v_mfma_f32_16x16x32_bf16 v[106:109], v[168:171], v[200:203], v[106:109]
	v_mfma_f32_16x16x32_bf16 v[98:101], v[160:163], v[208:211], v[98:101]
	v_mfma_f32_16x16x32_bf16 v[90:93], v[168:171], v[208:211], v[90:93]
	v_mfma_f32_16x16x32_bf16 v[82:85], v[160:163], v[216:219], v[82:85]
	v_mfma_f32_16x16x32_bf16 v[74:77], v[168:171], v[216:219], v[74:77]
	s_setprio 0
	s_setprio 1
	v_mfma_f32_16x16x32_bf16 v[118:121], v[172:175], v[188:191], v[118:121]
	v_mfma_f32_16x16x32_bf16 v[110:113], v[180:183], v[188:191], v[110:113]
	v_mfma_f32_16x16x32_bf16 v[102:105], v[172:175], v[196:199], v[102:105]
	v_mfma_f32_16x16x32_bf16 v[94:97], v[180:183], v[196:199], v[94:97]
	v_mfma_f32_16x16x32_bf16 v[86:89], v[172:175], v[204:207], v[86:89]
	v_mfma_f32_16x16x32_bf16 v[78:81], v[180:183], v[204:207], v[78:81]
	v_mfma_f32_16x16x32_bf16 v[70:73], v[172:175], v[212:215], v[70:73]
	v_mfma_f32_16x16x32_bf16 v[66:69], v[180:183], v[212:215], v[66:69]
	v_mfma_f32_16x16x32_bf16 v[118:121], v[176:179], v[192:195], v[118:121]
	v_mfma_f32_16x16x32_bf16 v[110:113], v[184:187], v[192:195], v[110:113]
	v_mfma_f32_16x16x32_bf16 v[102:105], v[176:179], v[200:203], v[102:105]
	v_mfma_f32_16x16x32_bf16 v[94:97], v[184:187], v[200:203], v[94:97]
	v_mfma_f32_16x16x32_bf16 v[86:89], v[176:179], v[208:211], v[86:89]
	v_mfma_f32_16x16x32_bf16 v[78:81], v[184:187], v[208:211], v[78:81]
	v_mfma_f32_16x16x32_bf16 v[70:73], v[176:179], v[216:219], v[70:73]
	v_mfma_f32_16x16x32_bf16 v[66:69], v[184:187], v[216:219], v[66:69]
	s_setprio 0
	s_barrier
	s_add_i32 s52, s44, s34
	v_lshl_add_u64 v[220:221], s[28:29], 0, v[134:135]
	s_mov_b32 m0, s52
	ds_read_b128 v[188:191], v158 offset:16384
	ds_read_b128 v[192:195], v158 offset:17408
	ds_read_b128 v[196:199], v158 offset:18432
	ds_read_b128 v[200:203], v158 offset:19456
	ds_read_b128 v[204:207], v158 offset:20480
	ds_read_b128 v[208:211], v158 offset:21504
	ds_read_b128 v[212:215], v158 offset:22528
	ds_read_b128 v[216:219], v158 offset:23552
	global_load_lds_dwordx4 v[220:221], off
	s_add_i32 m0, s52, 0x2000
	s_add_u32 s52, s28, 0x100000
	v_lshl_add_u64 v[222:223], s[28:29], 0, v[130:131]
	s_addc_u32 s53, s29, 0
	s_add_i32 s54, s45, s34
	global_load_lds_dwordx4 v[222:223], off
	v_lshl_add_u64 v[224:225], s[52:53], 0, v[134:135]
	s_mov_b32 m0, s54
	v_lshl_add_u64 v[226:227], s[30:31], 0, v[132:133]
	global_load_lds_dwordx4 v[224:225], off
	v_lshl_add_u64 v[224:225], s[52:53], 0, v[130:131]
	s_add_i32 m0, s54, 0x2000
	s_nop 0
	global_load_lds_dwordx4 v[224:225], off
	v_lshl_add_u64 v[224:225], s[30:31], 0, v[136:137]
	s_mov_b32 m0, s25
	s_nop 0
	global_load_lds_dwordx4 v[224:225], off
	s_mov_b32 m0, s37
	s_nop 0
	global_load_lds_dwordx4 v[226:227], off
	s_waitcnt vmcnt(8)
	s_waitcnt lgkmcnt(0)
	s_barrier
	s_setprio 1
	s_waitcnt lgkmcnt(0)
	v_mfma_f32_16x16x32_bf16 v[62:65], v[148:151], v[188:191], v[62:65]
	v_mfma_f32_16x16x32_bf16 v[58:61], v[164:167], v[188:191], v[58:61]
	v_mfma_f32_16x16x32_bf16 v[50:53], v[148:151], v[196:199], v[50:53]
	v_mfma_f32_16x16x32_bf16 v[42:45], v[164:167], v[196:199], v[42:45]
	v_mfma_f32_16x16x32_bf16 v[34:37], v[148:151], v[204:207], v[34:37]
	v_mfma_f32_16x16x32_bf16 v[26:29], v[164:167], v[204:207], v[26:29]
	v_mfma_f32_16x16x32_bf16 v[18:21], v[148:151], v[212:215], v[18:21]
	v_mfma_f32_16x16x32_bf16 v[10:13], v[164:167], v[212:215], v[10:13]
	v_mfma_f32_16x16x32_bf16 v[62:65], v[160:163], v[192:195], v[62:65]
	v_mfma_f32_16x16x32_bf16 v[58:61], v[168:171], v[192:195], v[58:61]
	v_mfma_f32_16x16x32_bf16 v[50:53], v[160:163], v[200:203], v[50:53]
	v_mfma_f32_16x16x32_bf16 v[42:45], v[168:171], v[200:203], v[42:45]
	v_mfma_f32_16x16x32_bf16 v[34:37], v[160:163], v[208:211], v[34:37]
	v_mfma_f32_16x16x32_bf16 v[26:29], v[168:171], v[208:211], v[26:29]
	v_mfma_f32_16x16x32_bf16 v[18:21], v[160:163], v[216:219], v[18:21]
	v_mfma_f32_16x16x32_bf16 v[10:13], v[168:171], v[216:219], v[10:13]
	s_setprio 0
	s_setprio 1
	v_mfma_f32_16x16x32_bf16 v[54:57], v[172:175], v[188:191], v[54:57]
	v_mfma_f32_16x16x32_bf16 v[46:49], v[180:183], v[188:191], v[46:49]
	v_mfma_f32_16x16x32_bf16 v[38:41], v[172:175], v[196:199], v[38:41]
	v_mfma_f32_16x16x32_bf16 v[30:33], v[180:183], v[196:199], v[30:33]
	v_mfma_f32_16x16x32_bf16 v[22:25], v[172:175], v[204:207], v[22:25]
	v_mfma_f32_16x16x32_bf16 v[14:17], v[180:183], v[204:207], v[14:17]
	v_mfma_f32_16x16x32_bf16 v[6:9], v[172:175], v[212:215], v[6:9]
	v_mfma_f32_16x16x32_bf16 v[2:5], v[180:183], v[212:215], v[2:5]
	v_mfma_f32_16x16x32_bf16 v[54:57], v[176:179], v[192:195], v[54:57]
	v_mfma_f32_16x16x32_bf16 v[46:49], v[184:187], v[192:195], v[46:49]
	v_mfma_f32_16x16x32_bf16 v[38:41], v[176:179], v[200:203], v[38:41]
	v_mfma_f32_16x16x32_bf16 v[30:33], v[184:187], v[200:203], v[30:33]
	v_mfma_f32_16x16x32_bf16 v[22:25], v[176:179], v[208:211], v[22:25]
	v_mfma_f32_16x16x32_bf16 v[14:17], v[184:187], v[208:211], v[14:17]
	v_mfma_f32_16x16x32_bf16 v[6:9], v[176:179], v[216:219], v[6:9]
	v_mfma_f32_16x16x32_bf16 v[2:5], v[184:187], v[216:219], v[2:5]
	s_setprio 0
	s_barrier
	s_add_i32 s52, 0, 0x18000
	v_add_u32_e32 v146, s52, v154
	s_add_i32 s53, 0, 0x1c000
	ds_read_b128 v[148:151], v146
	ds_read_b128 v[160:163], v146 offset:1024
	ds_read_b128 v[164:167], v146 offset:2048
	ds_read_b128 v[168:171], v146 offset:3072
	v_add_u32_e32 v146, s53, v154
	ds_read_b128 v[172:175], v146
	ds_read_b128 v[176:179], v146 offset:1024
	ds_read_b128 v[180:183], v146 offset:2048
	ds_read_b128 v[184:187], v146 offset:3072
	s_add_u32 s30, s30, 0x100000
	s_addc_u32 s31, s31, 0
	s_mov_b32 m0, s38
	v_lshl_add_u64 v[228:229], s[30:31], 0, v[136:137]
	ds_read_b128 v[188:191], v158 offset:32768
	ds_read_b128 v[192:195], v158 offset:33792
	ds_read_b128 v[196:199], v158 offset:34816
	ds_read_b128 v[200:203], v158 offset:35840
	ds_read_b128 v[204:207], v158 offset:36864
	ds_read_b128 v[208:211], v158 offset:37888
	ds_read_b128 v[212:215], v158 offset:38912
	ds_read_b128 v[216:219], v158 offset:39936
	global_load_lds_dwordx4 v[228:229], off
	v_lshl_add_u64 v[228:229], s[30:31], 0, v[132:133]
	s_mov_b32 m0, s39
	s_nop 0
	global_load_lds_dwordx4 v[228:229], off
	s_waitcnt vmcnt(8)
	s_waitcnt lgkmcnt(0)
	s_barrier
	s_setprio 1
	s_waitcnt lgkmcnt(0)
	v_mfma_f32_16x16x32_bf16 v[126:129], v[148:151], v[188:191], v[126:129]
	v_mfma_f32_16x16x32_bf16 v[122:125], v[164:167], v[188:191], v[122:125]
	v_mfma_f32_16x16x32_bf16 v[114:117], v[148:151], v[196:199], v[114:117]
	v_mfma_f32_16x16x32_bf16 v[106:109], v[164:167], v[196:199], v[106:109]
	v_mfma_f32_16x16x32_bf16 v[98:101], v[148:151], v[204:207], v[98:101]
	v_mfma_f32_16x16x32_bf16 v[90:93], v[164:167], v[204:207], v[90:93]
	v_mfma_f32_16x16x32_bf16 v[82:85], v[148:151], v[212:215], v[82:85]
	v_mfma_f32_16x16x32_bf16 v[74:77], v[164:167], v[212:215], v[74:77]
	v_mfma_f32_16x16x32_bf16 v[126:129], v[160:163], v[192:195], v[126:129]
	v_mfma_f32_16x16x32_bf16 v[122:125], v[168:171], v[192:195], v[122:125]
	v_mfma_f32_16x16x32_bf16 v[114:117], v[160:163], v[200:203], v[114:117]
	v_mfma_f32_16x16x32_bf16 v[106:109], v[168:171], v[200:203], v[106:109]
	v_mfma_f32_16x16x32_bf16 v[98:101], v[160:163], v[208:211], v[98:101]
	v_mfma_f32_16x16x32_bf16 v[90:93], v[168:171], v[208:211], v[90:93]
	v_mfma_f32_16x16x32_bf16 v[82:85], v[160:163], v[216:219], v[82:85]
	v_mfma_f32_16x16x32_bf16 v[74:77], v[168:171], v[216:219], v[74:77]
	s_setprio 0
	s_setprio 1
	v_mfma_f32_16x16x32_bf16 v[118:121], v[172:175], v[188:191], v[118:121]
	v_mfma_f32_16x16x32_bf16 v[110:113], v[180:183], v[188:191], v[110:113]
	v_mfma_f32_16x16x32_bf16 v[102:105], v[172:175], v[196:199], v[102:105]
	v_mfma_f32_16x16x32_bf16 v[94:97], v[180:183], v[196:199], v[94:97]
	v_mfma_f32_16x16x32_bf16 v[86:89], v[172:175], v[204:207], v[86:89]
	v_mfma_f32_16x16x32_bf16 v[78:81], v[180:183], v[204:207], v[78:81]
	v_mfma_f32_16x16x32_bf16 v[70:73], v[172:175], v[212:215], v[70:73]
	v_mfma_f32_16x16x32_bf16 v[66:69], v[180:183], v[212:215], v[66:69]
	v_mfma_f32_16x16x32_bf16 v[118:121], v[176:179], v[192:195], v[118:121]
	v_mfma_f32_16x16x32_bf16 v[110:113], v[184:187], v[192:195], v[110:113]
	v_mfma_f32_16x16x32_bf16 v[102:105], v[176:179], v[200:203], v[102:105]
	v_mfma_f32_16x16x32_bf16 v[94:97], v[184:187], v[200:203], v[94:97]
	v_mfma_f32_16x16x32_bf16 v[86:89], v[176:179], v[208:211], v[86:89]
	v_mfma_f32_16x16x32_bf16 v[78:81], v[184:187], v[208:211], v[78:81]
	v_mfma_f32_16x16x32_bf16 v[70:73], v[176:179], v[216:219], v[70:73]
	v_mfma_f32_16x16x32_bf16 v[66:69], v[184:187], v[216:219], v[66:69]
	s_setprio 0
	s_barrier
	s_add_i32 s30, s52, s34
	v_lshl_add_u64 v[220:221], v[220:221], 0, s[12:13]
	s_mov_b32 m0, s30
	ds_read_b128 v[188:191], v158 offset:49152
	ds_read_b128 v[192:195], v158 offset:50176
	ds_read_b128 v[196:199], v158 offset:51200
	ds_read_b128 v[200:203], v158 offset:52224
	ds_read_b128 v[204:207], v158 offset:53248
	ds_read_b128 v[208:211], v158 offset:54272
	ds_read_b128 v[212:215], v158 offset:55296
	ds_read_b128 v[216:219], v158 offset:56320
	global_load_lds_dwordx4 v[220:221], off
	s_add_i32 m0, s30, 0x2000
	s_add_u32 s28, s28, 0x100080
	v_lshl_add_u64 v[220:221], v[222:223], 0, s[12:13]
	s_addc_u32 s29, s29, 0
	s_add_i32 s30, s53, s34
	global_load_lds_dwordx4 v[220:221], off
	v_lshl_add_u64 v[220:221], s[28:29], 0, v[134:135]
	s_mov_b32 m0, s30
	s_nop 0
	global_load_lds_dwordx4 v[220:221], off
	v_lshl_add_u64 v[220:221], s[28:29], 0, v[130:131]
	s_add_i32 m0, s30, 0x2000
	s_nop 0
	global_load_lds_dwordx4 v[220:221], off
	v_lshl_add_u64 v[220:221], v[224:225], 0, s[12:13]
	s_mov_b32 m0, s41
	s_nop 0
	global_load_lds_dwordx4 v[220:221], off
	v_lshl_add_u64 v[220:221], v[226:227], 0, s[12:13]
	s_mov_b32 m0, s42
	s_nop 0
	global_load_lds_dwordx4 v[220:221], off
	s_waitcnt vmcnt(8)
	s_waitcnt lgkmcnt(0)
	s_barrier
	s_setprio 1
	s_waitcnt lgkmcnt(0)
	v_mfma_f32_16x16x32_bf16 v[62:65], v[148:151], v[188:191], v[62:65]
	v_mfma_f32_16x16x32_bf16 v[58:61], v[164:167], v[188:191], v[58:61]
	v_mfma_f32_16x16x32_bf16 v[50:53], v[148:151], v[196:199], v[50:53]
	v_mfma_f32_16x16x32_bf16 v[42:45], v[164:167], v[196:199], v[42:45]
	v_mfma_f32_16x16x32_bf16 v[34:37], v[148:151], v[204:207], v[34:37]
	v_mfma_f32_16x16x32_bf16 v[26:29], v[164:167], v[204:207], v[26:29]
	v_mfma_f32_16x16x32_bf16 v[18:21], v[148:151], v[212:215], v[18:21]
	v_mfma_f32_16x16x32_bf16 v[10:13], v[164:167], v[212:215], v[10:13]
	v_mfma_f32_16x16x32_bf16 v[62:65], v[160:163], v[192:195], v[62:65]
	v_mfma_f32_16x16x32_bf16 v[58:61], v[168:171], v[192:195], v[58:61]
	v_mfma_f32_16x16x32_bf16 v[50:53], v[160:163], v[200:203], v[50:53]
	v_mfma_f32_16x16x32_bf16 v[42:45], v[168:171], v[200:203], v[42:45]
	v_mfma_f32_16x16x32_bf16 v[34:37], v[160:163], v[208:211], v[34:37]
	v_mfma_f32_16x16x32_bf16 v[26:29], v[168:171], v[208:211], v[26:29]
	v_mfma_f32_16x16x32_bf16 v[18:21], v[160:163], v[216:219], v[18:21]
	v_mfma_f32_16x16x32_bf16 v[10:13], v[168:171], v[216:219], v[10:13]
	s_setprio 0
	s_setprio 1
	v_mfma_f32_16x16x32_bf16 v[54:57], v[172:175], v[188:191], v[54:57]
	v_mfma_f32_16x16x32_bf16 v[46:49], v[180:183], v[188:191], v[46:49]
	v_mfma_f32_16x16x32_bf16 v[38:41], v[172:175], v[196:199], v[38:41]
	v_mfma_f32_16x16x32_bf16 v[30:33], v[180:183], v[196:199], v[30:33]
	v_mfma_f32_16x16x32_bf16 v[22:25], v[172:175], v[204:207], v[22:25]
	v_mfma_f32_16x16x32_bf16 v[14:17], v[180:183], v[204:207], v[14:17]
	v_mfma_f32_16x16x32_bf16 v[6:9], v[172:175], v[212:215], v[6:9]
	v_mfma_f32_16x16x32_bf16 v[2:5], v[180:183], v[212:215], v[2:5]
	v_mfma_f32_16x16x32_bf16 v[54:57], v[176:179], v[192:195], v[54:57]
	v_mfma_f32_16x16x32_bf16 v[46:49], v[184:187], v[192:195], v[46:49]
	v_mfma_f32_16x16x32_bf16 v[38:41], v[176:179], v[200:203], v[38:41]
	v_mfma_f32_16x16x32_bf16 v[30:33], v[184:187], v[200:203], v[30:33]
	v_mfma_f32_16x16x32_bf16 v[22:25], v[176:179], v[208:211], v[22:25]
	v_mfma_f32_16x16x32_bf16 v[14:17], v[184:187], v[208:211], v[14:17]
	v_mfma_f32_16x16x32_bf16 v[6:9], v[176:179], v[216:219], v[6:9]
	v_mfma_f32_16x16x32_bf16 v[2:5], v[184:187], v[216:219], v[2:5]
	s_setprio 0
	s_add_i32 s51, s51, 2
	s_add_u32 s26, s26, 0x100
	s_addc_u32 s27, s27, 0
	s_add_u32 s49, s49, 0x100
	s_addc_u32 s50, s50, 0
	s_cmp_gt_u32 s51, 61
	s_barrier
	s_cbranch_scc0 .LBB0_1087
	s_and_b64 vcc, exec, s[14:15]
	s_cbranch_vccz .LBB0_1090
	s_barrier

.LBB0_1241:
	ds_read_b128 v[144:147], v162
	ds_read_b128 v[166:169], v162 offset:1024
	ds_read_b128 v[170:173], v162 offset:2048
	ds_read_b128 v[174:177], v162 offset:3072
	ds_read_b128 v[178:181], v163
	ds_read_b128 v[182:185], v163 offset:1024
	ds_read_b128 v[186:189], v163 offset:2048
	ds_read_b128 v[190:193], v163 offset:3072
	s_add_u32 s40, s38, 0xfff00080
	s_addc_u32 s41, s39, -1
	s_cmp_eq_u32 s63, 60
	s_cselect_b32 s43, s2, s41
	s_cselect_b32 s42, s29, s40
	s_cselect_b32 s41, s27, s62
	s_cselect_b32 s40, s60, s61
	v_lshl_add_u64 v[148:149], s[38:39], 0, v[138:139]
	s_add_i32 m0, s37, 0xc000
	ds_read_b128 v[194:197], v164
	ds_read_b128 v[198:201], v164 offset:1024
	ds_read_b128 v[202:205], v164 offset:2048
	ds_read_b128 v[206:209], v164 offset:3072
	ds_read_b128 v[210:213], v164 offset:4096
	ds_read_b128 v[214:217], v164 offset:5120
	ds_read_b128 v[218:221], v164 offset:6144
	ds_read_b128 v[222:225], v164 offset:7168
	global_load_lds_dwordx4 v[148:149], off
	v_lshl_add_u64 v[148:149], s[38:39], 0, v[140:141]
	s_add_i32 m0, s37, 0xe000
	s_nop 0
	global_load_lds_dwordx4 v[148:149], off
	s_waitcnt vmcnt(8)
	s_waitcnt lgkmcnt(0)
	s_barrier
	s_setprio 1
	s_waitcnt lgkmcnt(0)
	v_mfma_f32_16x16x32_bf16 v[126:129], v[144:147], v[194:197], v[126:129]
	v_mfma_f32_16x16x32_bf16 v[122:125], v[170:173], v[194:197], v[122:125]
	v_mfma_f32_16x16x32_bf16 v[110:113], v[144:147], v[202:205], v[110:113]
	v_mfma_f32_16x16x32_bf16 v[106:109], v[170:173], v[202:205], v[106:109]
	v_mfma_f32_16x16x32_bf16 v[94:97], v[144:147], v[210:213], v[94:97]
	v_mfma_f32_16x16x32_bf16 v[90:93], v[170:173], v[210:213], v[90:93]
	v_mfma_f32_16x16x32_bf16 v[78:81], v[144:147], v[218:221], v[78:81]
	v_mfma_f32_16x16x32_bf16 v[74:77], v[170:173], v[218:221], v[74:77]
	v_mfma_f32_16x16x32_bf16 v[126:129], v[166:169], v[198:201], v[126:129]
	v_mfma_f32_16x16x32_bf16 v[122:125], v[174:177], v[198:201], v[122:125]
	v_mfma_f32_16x16x32_bf16 v[110:113], v[166:169], v[206:209], v[110:113]
	v_mfma_f32_16x16x32_bf16 v[106:109], v[174:177], v[206:209], v[106:109]
	v_mfma_f32_16x16x32_bf16 v[94:97], v[166:169], v[214:217], v[94:97]
	v_mfma_f32_16x16x32_bf16 v[90:93], v[174:177], v[214:217], v[90:93]
	v_mfma_f32_16x16x32_bf16 v[78:81], v[166:169], v[222:225], v[78:81]
	v_mfma_f32_16x16x32_bf16 v[74:77], v[174:177], v[222:225], v[74:77]
	s_setprio 0
	s_setprio 1
	v_mfma_f32_16x16x32_bf16 v[118:121], v[178:181], v[194:197], v[118:121]
	v_mfma_f32_16x16x32_bf16 v[114:117], v[186:189], v[194:197], v[114:117]
	v_mfma_f32_16x16x32_bf16 v[102:105], v[178:181], v[202:205], v[102:105]
	v_mfma_f32_16x16x32_bf16 v[98:101], v[186:189], v[202:205], v[98:101]
	v_mfma_f32_16x16x32_bf16 v[86:89], v[178:181], v[210:213], v[86:89]
	v_mfma_f32_16x16x32_bf16 v[82:85], v[186:189], v[210:213], v[82:85]
	v_mfma_f32_16x16x32_bf16 v[70:73], v[178:181], v[218:221], v[70:73]
	v_mfma_f32_16x16x32_bf16 v[66:69], v[186:189], v[218:221], v[66:69]
	v_mfma_f32_16x16x32_bf16 v[118:121], v[182:185], v[198:201], v[118:121]
	v_mfma_f32_16x16x32_bf16 v[114:117], v[190:193], v[198:201], v[114:117]
	v_mfma_f32_16x16x32_bf16 v[102:105], v[182:185], v[206:209], v[102:105]
	v_mfma_f32_16x16x32_bf16 v[98:101], v[190:193], v[206:209], v[98:101]
	v_mfma_f32_16x16x32_bf16 v[86:89], v[182:185], v[214:217], v[86:89]
	v_mfma_f32_16x16x32_bf16 v[82:85], v[190:193], v[214:217], v[82:85]
	v_mfma_f32_16x16x32_bf16 v[70:73], v[182:185], v[222:225], v[70:73]
	v_mfma_f32_16x16x32_bf16 v[66:69], v[190:193], v[222:225], v[66:69]
	s_setprio 0
	s_barrier
	s_add_i32 s64, s56, s45
	v_lshl_add_u64 v[148:149], s[40:41], 0, v[132:133]
	s_mov_b32 m0, s64
	ds_read_b128 v[194:197], v164 offset:16384
	ds_read_b128 v[198:201], v164 offset:17408
	ds_read_b128 v[202:205], v164 offset:18432
	ds_read_b128 v[206:209], v164 offset:19456
	ds_read_b128 v[210:213], v164 offset:20480
	ds_read_b128 v[214:217], v164 offset:21504
	ds_read_b128 v[218:221], v164 offset:22528
	ds_read_b128 v[222:225], v164 offset:23552
	global_load_lds_dwordx4 v[148:149], off
	s_add_i32 m0, s64, 0x2000
	s_add_u32 s64, s40, 0x100000
	v_lshl_add_u64 v[226:227], s[40:41], 0, v[136:137]
	s_addc_u32 s65, s41, 0
	s_add_i32 s66, s57, s45
	global_load_lds_dwordx4 v[226:227], off
	v_lshl_add_u64 v[228:229], s[64:65], 0, v[132:133]
	s_mov_b32 m0, s66
	v_lshl_add_u64 v[230:231], s[42:43], 0, v[134:135]
	global_load_lds_dwordx4 v[228:229], off
	v_lshl_add_u64 v[228:229], s[64:65], 0, v[136:137]
	s_add_i32 m0, s66, 0x2000
	s_nop 0
	global_load_lds_dwordx4 v[228:229], off
	v_lshl_add_u64 v[228:229], s[42:43], 0, v[130:131]
	s_mov_b32 m0, s37
	s_nop 0
	global_load_lds_dwordx4 v[228:229], off
	s_mov_b32 m0, s46
	s_nop 0
	global_load_lds_dwordx4 v[230:231], off
	s_waitcnt vmcnt(8)
	s_waitcnt lgkmcnt(0)
	s_barrier
	s_setprio 1
	s_waitcnt lgkmcnt(0)
	v_mfma_f32_16x16x32_bf16 v[62:65], v[144:147], v[194:197], v[62:65]
	v_mfma_f32_16x16x32_bf16 v[58:61], v[170:173], v[194:197], v[58:61]
	v_mfma_f32_16x16x32_bf16 v[46:49], v[144:147], v[202:205], v[46:49]
	v_mfma_f32_16x16x32_bf16 v[42:45], v[170:173], v[202:205], v[42:45]
	v_mfma_f32_16x16x32_bf16 v[30:33], v[144:147], v[210:213], v[30:33]
	v_mfma_f32_16x16x32_bf16 v[26:29], v[170:173], v[210:213], v[26:29]
	v_mfma_f32_16x16x32_bf16 v[14:17], v[144:147], v[218:221], v[14:17]
	v_mfma_f32_16x16x32_bf16 v[10:13], v[170:173], v[218:221], v[10:13]
	v_mfma_f32_16x16x32_bf16 v[62:65], v[166:169], v[198:201], v[62:65]
	v_mfma_f32_16x16x32_bf16 v[58:61], v[174:177], v[198:201], v[58:61]
	v_mfma_f32_16x16x32_bf16 v[46:49], v[166:169], v[206:209], v[46:49]
	v_mfma_f32_16x16x32_bf16 v[42:45], v[174:177], v[206:209], v[42:45]
	v_mfma_f32_16x16x32_bf16 v[30:33], v[166:169], v[214:217], v[30:33]
	v_mfma_f32_16x16x32_bf16 v[26:29], v[174:177], v[214:217], v[26:29]
	v_mfma_f32_16x16x32_bf16 v[14:17], v[166:169], v[222:225], v[14:17]
	v_mfma_f32_16x16x32_bf16 v[10:13], v[174:177], v[222:225], v[10:13]
	s_setprio 0
	s_setprio 1
	v_mfma_f32_16x16x32_bf16 v[54:57], v[178:181], v[194:197], v[54:57]
	v_mfma_f32_16x16x32_bf16 v[50:53], v[186:189], v[194:197], v[50:53]
	v_mfma_f32_16x16x32_bf16 v[38:41], v[178:181], v[202:205], v[38:41]
	v_mfma_f32_16x16x32_bf16 v[34:37], v[186:189], v[202:205], v[34:37]
	v_mfma_f32_16x16x32_bf16 v[22:25], v[178:181], v[210:213], v[22:25]
	v_mfma_f32_16x16x32_bf16 v[18:21], v[186:189], v[210:213], v[18:21]
	v_mfma_f32_16x16x32_bf16 v[6:9], v[178:181], v[218:221], v[6:9]
	v_mfma_f32_16x16x32_bf16 v[2:5], v[186:189], v[218:221], v[2:5]
	v_mfma_f32_16x16x32_bf16 v[54:57], v[182:185], v[198:201], v[54:57]
	v_mfma_f32_16x16x32_bf16 v[50:53], v[190:193], v[198:201], v[50:53]
	v_mfma_f32_16x16x32_bf16 v[38:41], v[182:185], v[206:209], v[38:41]
	v_mfma_f32_16x16x32_bf16 v[34:37], v[190:193], v[206:209], v[34:37]
	v_mfma_f32_16x16x32_bf16 v[22:25], v[182:185], v[214:217], v[22:25]
	v_mfma_f32_16x16x32_bf16 v[18:21], v[190:193], v[214:217], v[18:21]
	v_mfma_f32_16x16x32_bf16 v[6:9], v[182:185], v[222:225], v[6:9]
	v_mfma_f32_16x16x32_bf16 v[2:5], v[190:193], v[222:225], v[2:5]
	s_setprio 0
	s_barrier
	s_add_i32 s64, 0, 0x18000
	v_add_u32_e32 v142, s64, v160
	s_add_i32 s65, 0, 0x1c000
	ds_read_b128 v[144:147], v142
	ds_read_b128 v[166:169], v142 offset:1024
	ds_read_b128 v[170:173], v142 offset:2048
	ds_read_b128 v[174:177], v142 offset:3072
	v_add_u32_e32 v142, s65, v160
	ds_read_b128 v[178:181], v142
	ds_read_b128 v[182:185], v142 offset:1024
	ds_read_b128 v[186:189], v142 offset:2048
	ds_read_b128 v[190:193], v142 offset:3072
	s_add_u32 s42, s42, 0x100000
	s_addc_u32 s43, s43, 0
	s_mov_b32 m0, s47
	v_lshl_add_u64 v[232:233], s[42:43], 0, v[130:131]
	ds_read_b128 v[194:197], v164 offset:32768
	ds_read_b128 v[198:201], v164 offset:33792
	ds_read_b128 v[202:205], v164 offset:34816
	ds_read_b128 v[206:209], v164 offset:35840
	ds_read_b128 v[210:213], v164 offset:36864
	ds_read_b128 v[214:217], v164 offset:37888
	ds_read_b128 v[218:221], v164 offset:38912
	ds_read_b128 v[222:225], v164 offset:39936
	global_load_lds_dwordx4 v[232:233], off
	v_lshl_add_u64 v[232:233], s[42:43], 0, v[134:135]
	s_mov_b32 m0, s48
	s_nop 0
	global_load_lds_dwordx4 v[232:233], off
	s_waitcnt vmcnt(8)
	s_waitcnt lgkmcnt(0)
	s_barrier
	s_setprio 1
	s_waitcnt lgkmcnt(0)
	v_mfma_f32_16x16x32_bf16 v[126:129], v[144:147], v[194:197], v[126:129]
	v_mfma_f32_16x16x32_bf16 v[122:125], v[170:173], v[194:197], v[122:125]
	v_mfma_f32_16x16x32_bf16 v[110:113], v[144:147], v[202:205], v[110:113]
	v_mfma_f32_16x16x32_bf16 v[106:109], v[170:173], v[202:205], v[106:109]
	v_mfma_f32_16x16x32_bf16 v[94:97], v[144:147], v[210:213], v[94:97]
	v_mfma_f32_16x16x32_bf16 v[90:93], v[170:173], v[210:213], v[90:93]
	v_mfma_f32_16x16x32_bf16 v[78:81], v[144:147], v[218:221], v[78:81]
	v_mfma_f32_16x16x32_bf16 v[74:77], v[170:173], v[218:221], v[74:77]
	v_mfma_f32_16x16x32_bf16 v[126:129], v[166:169], v[198:201], v[126:129]
	v_mfma_f32_16x16x32_bf16 v[122:125], v[174:177], v[198:201], v[122:125]
	v_mfma_f32_16x16x32_bf16 v[110:113], v[166:169], v[206:209], v[110:113]
	v_mfma_f32_16x16x32_bf16 v[106:109], v[174:177], v[206:209], v[106:109]
	v_mfma_f32_16x16x32_bf16 v[94:97], v[166:169], v[214:217], v[94:97]
	v_mfma_f32_16x16x32_bf16 v[90:93], v[174:177], v[214:217], v[90:93]
	v_mfma_f32_16x16x32_bf16 v[78:81], v[166:169], v[222:225], v[78:81]
	v_mfma_f32_16x16x32_bf16 v[74:77], v[174:177], v[222:225], v[74:77]
	s_setprio 0
	s_setprio 1
	v_mfma_f32_16x16x32_bf16 v[118:121], v[178:181], v[194:197], v[118:121]
	v_mfma_f32_16x16x32_bf16 v[114:117], v[186:189], v[194:197], v[114:117]
	v_mfma_f32_16x16x32_bf16 v[102:105], v[178:181], v[202:205], v[102:105]
	v_mfma_f32_16x16x32_bf16 v[98:101], v[186:189], v[202:205], v[98:101]
	v_mfma_f32_16x16x32_bf16 v[86:89], v[178:181], v[210:213], v[86:89]
	v_mfma_f32_16x16x32_bf16 v[82:85], v[186:189], v[210:213], v[82:85]
	v_mfma_f32_16x16x32_bf16 v[70:73], v[178:181], v[218:221], v[70:73]
	v_mfma_f32_16x16x32_bf16 v[66:69], v[186:189], v[218:221], v[66:69]
	v_mfma_f32_16x16x32_bf16 v[118:121], v[182:185], v[198:201], v[118:121]
	v_mfma_f32_16x16x32_bf16 v[114:117], v[190:193], v[198:201], v[114:117]
	v_mfma_f32_16x16x32_bf16 v[102:105], v[182:185], v[206:209], v[102:105]
	v_mfma_f32_16x16x32_bf16 v[98:101], v[190:193], v[206:209], v[98:101]
	v_mfma_f32_16x16x32_bf16 v[86:89], v[182:185], v[214:217], v[86:89]
	v_mfma_f32_16x16x32_bf16 v[82:85], v[190:193], v[214:217], v[82:85]
	v_mfma_f32_16x16x32_bf16 v[70:73], v[182:185], v[222:225], v[70:73]
	v_mfma_f32_16x16x32_bf16 v[66:69], v[190:193], v[222:225], v[66:69]
	s_setprio 0
	s_barrier
	s_add_i32 s42, s64, s45
	v_lshl_add_u64 v[148:149], v[148:149], 0, s[12:13]
	s_mov_b32 m0, s42
	ds_read_b128 v[194:197], v164 offset:49152
	ds_read_b128 v[198:201], v164 offset:50176
	ds_read_b128 v[202:205], v164 offset:51200
	ds_read_b128 v[206:209], v164 offset:52224
	ds_read_b128 v[210:213], v164 offset:53248
	ds_read_b128 v[214:217], v164 offset:54272
	ds_read_b128 v[218:221], v164 offset:55296
	ds_read_b128 v[222:225], v164 offset:56320
	global_load_lds_dwordx4 v[148:149], off
	s_add_i32 m0, s42, 0x2000
	s_add_u32 s40, s40, 0x100080
	v_lshl_add_u64 v[148:149], v[226:227], 0, s[12:13]
	s_addc_u32 s41, s41, 0
	s_add_i32 s42, s65, s45
	global_load_lds_dwordx4 v[148:149], off
	v_lshl_add_u64 v[148:149], s[40:41], 0, v[132:133]
	s_mov_b32 m0, s42
	s_nop 0
	global_load_lds_dwordx4 v[148:149], off
	v_lshl_add_u64 v[148:149], s[40:41], 0, v[136:137]
	s_add_i32 m0, s42, 0x2000
	s_nop 0
	global_load_lds_dwordx4 v[148:149], off
	v_lshl_add_u64 v[148:149], v[228:229], 0, s[12:13]
	s_mov_b32 m0, s53
	s_nop 0
	global_load_lds_dwordx4 v[148:149], off
	v_lshl_add_u64 v[148:149], v[230:231], 0, s[12:13]
	s_mov_b32 m0, s54
	s_nop 0
	global_load_lds_dwordx4 v[148:149], off
	s_waitcnt vmcnt(8)
	s_waitcnt lgkmcnt(0)
	s_barrier
	s_setprio 1
	s_waitcnt lgkmcnt(0)
	v_mfma_f32_16x16x32_bf16 v[62:65], v[144:147], v[194:197], v[62:65]
	v_mfma_f32_16x16x32_bf16 v[58:61], v[170:173], v[194:197], v[58:61]
	v_mfma_f32_16x16x32_bf16 v[46:49], v[144:147], v[202:205], v[46:49]
	v_mfma_f32_16x16x32_bf16 v[42:45], v[170:173], v[202:205], v[42:45]
	v_mfma_f32_16x16x32_bf16 v[30:33], v[144:147], v[210:213], v[30:33]
	v_mfma_f32_16x16x32_bf16 v[26:29], v[170:173], v[210:213], v[26:29]
	v_mfma_f32_16x16x32_bf16 v[14:17], v[144:147], v[218:221], v[14:17]
	v_mfma_f32_16x16x32_bf16 v[10:13], v[170:173], v[218:221], v[10:13]
	v_mfma_f32_16x16x32_bf16 v[62:65], v[166:169], v[198:201], v[62:65]
	v_mfma_f32_16x16x32_bf16 v[58:61], v[174:177], v[198:201], v[58:61]
	v_mfma_f32_16x16x32_bf16 v[46:49], v[166:169], v[206:209], v[46:49]
	v_mfma_f32_16x16x32_bf16 v[42:45], v[174:177], v[206:209], v[42:45]
	v_mfma_f32_16x16x32_bf16 v[30:33], v[166:169], v[214:217], v[30:33]
	v_mfma_f32_16x16x32_bf16 v[26:29], v[174:177], v[214:217], v[26:29]
	v_mfma_f32_16x16x32_bf16 v[14:17], v[166:169], v[222:225], v[14:17]
	v_mfma_f32_16x16x32_bf16 v[10:13], v[174:177], v[222:225], v[10:13]
	s_setprio 0
	s_setprio 1
	v_mfma_f32_16x16x32_bf16 v[54:57], v[178:181], v[194:197], v[54:57]
	v_mfma_f32_16x16x32_bf16 v[50:53], v[186:189], v[194:197], v[50:53]
	v_mfma_f32_16x16x32_bf16 v[38:41], v[178:181], v[202:205], v[38:41]
	v_mfma_f32_16x16x32_bf16 v[34:37], v[186:189], v[202:205], v[34:37]
	v_mfma_f32_16x16x32_bf16 v[22:25], v[178:181], v[210:213], v[22:25]
	v_mfma_f32_16x16x32_bf16 v[18:21], v[186:189], v[210:213], v[18:21]
	v_mfma_f32_16x16x32_bf16 v[6:9], v[178:181], v[218:221], v[6:9]
	v_mfma_f32_16x16x32_bf16 v[2:5], v[186:189], v[218:221], v[2:5]
	v_mfma_f32_16x16x32_bf16 v[54:57], v[182:185], v[198:201], v[54:57]
	v_mfma_f32_16x16x32_bf16 v[50:53], v[190:193], v[198:201], v[50:53]
	v_mfma_f32_16x16x32_bf16 v[38:41], v[182:185], v[206:209], v[38:41]
	v_mfma_f32_16x16x32_bf16 v[34:37], v[190:193], v[206:209], v[34:37]
	v_mfma_f32_16x16x32_bf16 v[22:25], v[182:185], v[214:217], v[22:25]
	v_mfma_f32_16x16x32_bf16 v[18:21], v[190:193], v[214:217], v[18:21]
	v_mfma_f32_16x16x32_bf16 v[6:9], v[182:185], v[222:225], v[6:9]
	v_mfma_f32_16x16x32_bf16 v[2:5], v[190:193], v[222:225], v[2:5]
	s_setprio 0
	s_add_i32 s63, s63, 2
	s_add_u32 s38, s38, 0x100
	s_addc_u32 s39, s39, 0
	s_add_u32 s61, s61, 0x100
	s_addc_u32 s62, s62, 0
	s_cmp_gt_u32 s63, 61
	s_barrier
	s_cbranch_scc0 .LBB0_1241
	s_and_b64 vcc, exec, s[14:15]
	s_cbranch_vccz .LBB0_1244
	s_barrier

.LBB0_1294:
	ds_read_b128 v[144:147], v151
	ds_read_b128 v[160:163], v151 offset:1024
	ds_read_b128 v[164:167], v151 offset:2048
	ds_read_b128 v[168:171], v151 offset:3072
	ds_read_b128 v[172:175], v152
	ds_read_b128 v[176:179], v152 offset:1024
	ds_read_b128 v[180:183], v152 offset:2048
	ds_read_b128 v[184:187], v152 offset:3072
	s_add_u32 s40, s38, 0xfff00080
	s_addc_u32 s41, s39, -1
	s_cmp_eq_u32 s64, 60
	s_cselect_b32 s43, s2, s41
	s_cselect_b32 s42, s29, s40
	s_cselect_b32 s41, s27, s63
	s_cselect_b32 s40, s61, s62
	v_lshl_add_u64 v[148:149], s[38:39], 0, v[138:139]
	s_add_i32 m0, s37, 0xc000
	ds_read_b128 v[188:191], v153
	ds_read_b128 v[192:195], v153 offset:1024
	ds_read_b128 v[196:199], v153 offset:2048
	ds_read_b128 v[200:203], v153 offset:3072
	ds_read_b128 v[204:207], v153 offset:4096
	ds_read_b128 v[208:211], v153 offset:5120
	ds_read_b128 v[212:215], v153 offset:6144
	ds_read_b128 v[216:219], v153 offset:7168
	global_load_lds_dwordx4 v[148:149], off
	v_lshl_add_u64 v[148:149], s[38:39], 0, v[140:141]
	s_add_i32 m0, s37, 0xe000
	s_nop 0
	global_load_lds_dwordx4 v[148:149], off
	s_waitcnt vmcnt(8)
	s_waitcnt lgkmcnt(0)
	s_barrier
	s_setprio 1
	s_waitcnt lgkmcnt(0)
	v_mfma_f32_16x16x32_bf16 v[126:129], v[144:147], v[188:191], v[126:129]
	v_mfma_f32_16x16x32_bf16 v[122:125], v[164:167], v[188:191], v[122:125]
	v_mfma_f32_16x16x32_bf16 v[110:113], v[144:147], v[196:199], v[110:113]
	v_mfma_f32_16x16x32_bf16 v[106:109], v[164:167], v[196:199], v[106:109]
	v_mfma_f32_16x16x32_bf16 v[94:97], v[144:147], v[204:207], v[94:97]
	v_mfma_f32_16x16x32_bf16 v[90:93], v[164:167], v[204:207], v[90:93]
	v_mfma_f32_16x16x32_bf16 v[78:81], v[144:147], v[212:215], v[78:81]
	v_mfma_f32_16x16x32_bf16 v[74:77], v[164:167], v[212:215], v[74:77]
	v_mfma_f32_16x16x32_bf16 v[126:129], v[160:163], v[192:195], v[126:129]
	v_mfma_f32_16x16x32_bf16 v[122:125], v[168:171], v[192:195], v[122:125]
	v_mfma_f32_16x16x32_bf16 v[110:113], v[160:163], v[200:203], v[110:113]
	v_mfma_f32_16x16x32_bf16 v[106:109], v[168:171], v[200:203], v[106:109]
	v_mfma_f32_16x16x32_bf16 v[94:97], v[160:163], v[208:211], v[94:97]
	v_mfma_f32_16x16x32_bf16 v[90:93], v[168:171], v[208:211], v[90:93]
	v_mfma_f32_16x16x32_bf16 v[78:81], v[160:163], v[216:219], v[78:81]
	v_mfma_f32_16x16x32_bf16 v[74:77], v[168:171], v[216:219], v[74:77]
	s_setprio 0
	s_setprio 1
	v_mfma_f32_16x16x32_bf16 v[118:121], v[172:175], v[188:191], v[118:121]
	v_mfma_f32_16x16x32_bf16 v[114:117], v[180:183], v[188:191], v[114:117]
	v_mfma_f32_16x16x32_bf16 v[102:105], v[172:175], v[196:199], v[102:105]
	v_mfma_f32_16x16x32_bf16 v[98:101], v[180:183], v[196:199], v[98:101]
	v_mfma_f32_16x16x32_bf16 v[86:89], v[172:175], v[204:207], v[86:89]
	v_mfma_f32_16x16x32_bf16 v[82:85], v[180:183], v[204:207], v[82:85]
	v_mfma_f32_16x16x32_bf16 v[70:73], v[172:175], v[212:215], v[70:73]
	v_mfma_f32_16x16x32_bf16 v[66:69], v[180:183], v[212:215], v[66:69]
	v_mfma_f32_16x16x32_bf16 v[118:121], v[176:179], v[192:195], v[118:121]
	v_mfma_f32_16x16x32_bf16 v[114:117], v[184:187], v[192:195], v[114:117]
	v_mfma_f32_16x16x32_bf16 v[102:105], v[176:179], v[200:203], v[102:105]
	v_mfma_f32_16x16x32_bf16 v[98:101], v[184:187], v[200:203], v[98:101]
	v_mfma_f32_16x16x32_bf16 v[86:89], v[176:179], v[208:211], v[86:89]
	v_mfma_f32_16x16x32_bf16 v[82:85], v[184:187], v[208:211], v[82:85]
	v_mfma_f32_16x16x32_bf16 v[70:73], v[176:179], v[216:219], v[70:73]
	v_mfma_f32_16x16x32_bf16 v[66:69], v[184:187], v[216:219], v[66:69]
	s_setprio 0
	s_barrier
	s_add_i32 s65, s57, s46
	v_lshl_add_u64 v[148:149], s[40:41], 0, v[132:133]
	s_mov_b32 m0, s65
	ds_read_b128 v[188:191], v153 offset:16384
	ds_read_b128 v[192:195], v153 offset:17408
	ds_read_b128 v[196:199], v153 offset:18432
	ds_read_b128 v[200:203], v153 offset:19456
	ds_read_b128 v[204:207], v153 offset:20480
	ds_read_b128 v[208:211], v153 offset:21504
	ds_read_b128 v[212:215], v153 offset:22528
	ds_read_b128 v[216:219], v153 offset:23552
	global_load_lds_dwordx4 v[148:149], off
	s_add_i32 m0, s65, 0x2000
	s_add_u32 s66, s40, 0x100000
	v_lshl_add_u64 v[220:221], s[40:41], 0, v[136:137]
	s_addc_u32 s67, s41, 0
	s_add_i32 s65, s58, s46
	global_load_lds_dwordx4 v[220:221], off
	v_lshl_add_u64 v[222:223], s[66:67], 0, v[132:133]
	s_mov_b32 m0, s65
	v_lshl_add_u64 v[224:225], s[42:43], 0, v[134:135]
	global_load_lds_dwordx4 v[222:223], off
	v_lshl_add_u64 v[222:223], s[66:67], 0, v[136:137]
	s_add_i32 m0, s65, 0x2000
	s_nop 0
	global_load_lds_dwordx4 v[222:223], off
	v_lshl_add_u64 v[222:223], s[42:43], 0, v[130:131]
	s_mov_b32 m0, s37
	s_nop 0
	global_load_lds_dwordx4 v[222:223], off
	s_mov_b32 m0, s47
	s_nop 0
	global_load_lds_dwordx4 v[224:225], off
	s_waitcnt vmcnt(8)
	s_waitcnt lgkmcnt(0)
	s_barrier
	s_setprio 1
	s_waitcnt lgkmcnt(0)
	v_mfma_f32_16x16x32_bf16 v[62:65], v[144:147], v[188:191], v[62:65]
	v_mfma_f32_16x16x32_bf16 v[58:61], v[164:167], v[188:191], v[58:61]
	v_mfma_f32_16x16x32_bf16 v[46:49], v[144:147], v[196:199], v[46:49]
	v_mfma_f32_16x16x32_bf16 v[42:45], v[164:167], v[196:199], v[42:45]
	v_mfma_f32_16x16x32_bf16 v[30:33], v[144:147], v[204:207], v[30:33]
	v_mfma_f32_16x16x32_bf16 v[26:29], v[164:167], v[204:207], v[26:29]
	v_mfma_f32_16x16x32_bf16 v[14:17], v[144:147], v[212:215], v[14:17]
	v_mfma_f32_16x16x32_bf16 v[10:13], v[164:167], v[212:215], v[10:13]
	v_mfma_f32_16x16x32_bf16 v[62:65], v[160:163], v[192:195], v[62:65]
	v_mfma_f32_16x16x32_bf16 v[58:61], v[168:171], v[192:195], v[58:61]
	v_mfma_f32_16x16x32_bf16 v[46:49], v[160:163], v[200:203], v[46:49]
	v_mfma_f32_16x16x32_bf16 v[42:45], v[168:171], v[200:203], v[42:45]
	v_mfma_f32_16x16x32_bf16 v[30:33], v[160:163], v[208:211], v[30:33]
	v_mfma_f32_16x16x32_bf16 v[26:29], v[168:171], v[208:211], v[26:29]
	v_mfma_f32_16x16x32_bf16 v[14:17], v[160:163], v[216:219], v[14:17]
	v_mfma_f32_16x16x32_bf16 v[10:13], v[168:171], v[216:219], v[10:13]
	s_setprio 0
	s_setprio 1
	v_mfma_f32_16x16x32_bf16 v[54:57], v[172:175], v[188:191], v[54:57]
	v_mfma_f32_16x16x32_bf16 v[50:53], v[180:183], v[188:191], v[50:53]
	v_mfma_f32_16x16x32_bf16 v[38:41], v[172:175], v[196:199], v[38:41]
	v_mfma_f32_16x16x32_bf16 v[34:37], v[180:183], v[196:199], v[34:37]
	v_mfma_f32_16x16x32_bf16 v[22:25], v[172:175], v[204:207], v[22:25]
	v_mfma_f32_16x16x32_bf16 v[18:21], v[180:183], v[204:207], v[18:21]
	v_mfma_f32_16x16x32_bf16 v[6:9], v[172:175], v[212:215], v[6:9]
	v_mfma_f32_16x16x32_bf16 v[2:5], v[180:183], v[212:215], v[2:5]
	v_mfma_f32_16x16x32_bf16 v[54:57], v[176:179], v[192:195], v[54:57]
	v_mfma_f32_16x16x32_bf16 v[50:53], v[184:187], v[192:195], v[50:53]
	v_mfma_f32_16x16x32_bf16 v[38:41], v[176:179], v[200:203], v[38:41]
	v_mfma_f32_16x16x32_bf16 v[34:37], v[184:187], v[200:203], v[34:37]
	v_mfma_f32_16x16x32_bf16 v[22:25], v[176:179], v[208:211], v[22:25]
	v_mfma_f32_16x16x32_bf16 v[18:21], v[184:187], v[208:211], v[18:21]
	v_mfma_f32_16x16x32_bf16 v[6:9], v[176:179], v[216:219], v[6:9]
	v_mfma_f32_16x16x32_bf16 v[2:5], v[184:187], v[216:219], v[2:5]
	s_setprio 0
	s_barrier
	s_add_i32 s65, 0, 0x18000
	v_add_u32_e32 v142, s65, v156
	s_add_i32 s66, 0, 0x1c000
	ds_read_b128 v[144:147], v142
	ds_read_b128 v[160:163], v142 offset:1024
	ds_read_b128 v[164:167], v142 offset:2048
	ds_read_b128 v[168:171], v142 offset:3072
	v_add_u32_e32 v142, s66, v156
	ds_read_b128 v[172:175], v142
	ds_read_b128 v[176:179], v142 offset:1024
	ds_read_b128 v[180:183], v142 offset:2048
	ds_read_b128 v[184:187], v142 offset:3072
	s_add_u32 s42, s42, 0x100000
	s_addc_u32 s43, s43, 0
	s_mov_b32 m0, s48
	v_lshl_add_u64 v[226:227], s[42:43], 0, v[130:131]
	ds_read_b128 v[188:191], v153 offset:32768
	ds_read_b128 v[192:195], v153 offset:33792
	ds_read_b128 v[196:199], v153 offset:34816
	ds_read_b128 v[200:203], v153 offset:35840
	ds_read_b128 v[204:207], v153 offset:36864
	ds_read_b128 v[208:211], v153 offset:37888
	ds_read_b128 v[212:215], v153 offset:38912
	ds_read_b128 v[216:219], v153 offset:39936
	global_load_lds_dwordx4 v[226:227], off
	v_lshl_add_u64 v[226:227], s[42:43], 0, v[134:135]
	s_mov_b32 m0, s49
	s_nop 0
	global_load_lds_dwordx4 v[226:227], off
	s_waitcnt vmcnt(8)
	s_waitcnt lgkmcnt(0)
	s_barrier
	s_setprio 1
	s_waitcnt lgkmcnt(0)
	v_mfma_f32_16x16x32_bf16 v[126:129], v[144:147], v[188:191], v[126:129]
	v_mfma_f32_16x16x32_bf16 v[122:125], v[164:167], v[188:191], v[122:125]
	v_mfma_f32_16x16x32_bf16 v[110:113], v[144:147], v[196:199], v[110:113]
	v_mfma_f32_16x16x32_bf16 v[106:109], v[164:167], v[196:199], v[106:109]
	v_mfma_f32_16x16x32_bf16 v[94:97], v[144:147], v[204:207], v[94:97]
	v_mfma_f32_16x16x32_bf16 v[90:93], v[164:167], v[204:207], v[90:93]
	v_mfma_f32_16x16x32_bf16 v[78:81], v[144:147], v[212:215], v[78:81]
	v_mfma_f32_16x16x32_bf16 v[74:77], v[164:167], v[212:215], v[74:77]
	v_mfma_f32_16x16x32_bf16 v[126:129], v[160:163], v[192:195], v[126:129]
	v_mfma_f32_16x16x32_bf16 v[122:125], v[168:171], v[192:195], v[122:125]
	v_mfma_f32_16x16x32_bf16 v[110:113], v[160:163], v[200:203], v[110:113]
	v_mfma_f32_16x16x32_bf16 v[106:109], v[168:171], v[200:203], v[106:109]
	v_mfma_f32_16x16x32_bf16 v[94:97], v[160:163], v[208:211], v[94:97]
	v_mfma_f32_16x16x32_bf16 v[90:93], v[168:171], v[208:211], v[90:93]
	v_mfma_f32_16x16x32_bf16 v[78:81], v[160:163], v[216:219], v[78:81]
	v_mfma_f32_16x16x32_bf16 v[74:77], v[168:171], v[216:219], v[74:77]
	s_setprio 0
	s_setprio 1
	v_mfma_f32_16x16x32_bf16 v[118:121], v[172:175], v[188:191], v[118:121]
	v_mfma_f32_16x16x32_bf16 v[114:117], v[180:183], v[188:191], v[114:117]
	v_mfma_f32_16x16x32_bf16 v[102:105], v[172:175], v[196:199], v[102:105]
	v_mfma_f32_16x16x32_bf16 v[98:101], v[180:183], v[196:199], v[98:101]
	v_mfma_f32_16x16x32_bf16 v[86:89], v[172:175], v[204:207], v[86:89]
	v_mfma_f32_16x16x32_bf16 v[82:85], v[180:183], v[204:207], v[82:85]
	v_mfma_f32_16x16x32_bf16 v[70:73], v[172:175], v[212:215], v[70:73]
	v_mfma_f32_16x16x32_bf16 v[66:69], v[180:183], v[212:215], v[66:69]
	v_mfma_f32_16x16x32_bf16 v[118:121], v[176:179], v[192:195], v[118:121]
	v_mfma_f32_16x16x32_bf16 v[114:117], v[184:187], v[192:195], v[114:117]
	v_mfma_f32_16x16x32_bf16 v[102:105], v[176:179], v[200:203], v[102:105]
	v_mfma_f32_16x16x32_bf16 v[98:101], v[184:187], v[200:203], v[98:101]
	v_mfma_f32_16x16x32_bf16 v[86:89], v[176:179], v[208:211], v[86:89]
	v_mfma_f32_16x16x32_bf16 v[82:85], v[184:187], v[208:211], v[82:85]
	v_mfma_f32_16x16x32_bf16 v[70:73], v[176:179], v[216:219], v[70:73]
	v_mfma_f32_16x16x32_bf16 v[66:69], v[184:187], v[216:219], v[66:69]
	s_setprio 0
	s_barrier
	s_add_i32 s42, s65, s46
	v_lshl_add_u64 v[148:149], v[148:149], 0, s[12:13]
	s_mov_b32 m0, s42
	ds_read_b128 v[188:191], v153 offset:49152
	ds_read_b128 v[192:195], v153 offset:50176
	ds_read_b128 v[196:199], v153 offset:51200
	ds_read_b128 v[200:203], v153 offset:52224
	ds_read_b128 v[204:207], v153 offset:53248
	ds_read_b128 v[208:211], v153 offset:54272
	ds_read_b128 v[212:215], v153 offset:55296
	ds_read_b128 v[216:219], v153 offset:56320
	global_load_lds_dwordx4 v[148:149], off
	s_add_i32 m0, s42, 0x2000
	s_add_u32 s40, s40, 0x100080
	v_lshl_add_u64 v[148:149], v[220:221], 0, s[12:13]
	s_addc_u32 s41, s41, 0
	s_add_i32 s42, s66, s46
	global_load_lds_dwordx4 v[148:149], off
	v_lshl_add_u64 v[148:149], s[40:41], 0, v[132:133]
	s_mov_b32 m0, s42
	s_nop 0
	global_load_lds_dwordx4 v[148:149], off
	v_lshl_add_u64 v[148:149], s[40:41], 0, v[136:137]
	s_add_i32 m0, s42, 0x2000
	s_nop 0
	global_load_lds_dwordx4 v[148:149], off
	v_lshl_add_u64 v[148:149], v[222:223], 0, s[12:13]
	s_mov_b32 m0, s54
	s_nop 0
	global_load_lds_dwordx4 v[148:149], off
	v_lshl_add_u64 v[148:149], v[224:225], 0, s[12:13]
	s_mov_b32 m0, s55
	s_nop 0
	global_load_lds_dwordx4 v[148:149], off
	s_waitcnt vmcnt(8)
	s_waitcnt lgkmcnt(0)
	s_barrier
	s_setprio 1
	s_waitcnt lgkmcnt(0)
	v_mfma_f32_16x16x32_bf16 v[62:65], v[144:147], v[188:191], v[62:65]
	v_mfma_f32_16x16x32_bf16 v[58:61], v[164:167], v[188:191], v[58:61]
	v_mfma_f32_16x16x32_bf16 v[46:49], v[144:147], v[196:199], v[46:49]
	v_mfma_f32_16x16x32_bf16 v[42:45], v[164:167], v[196:199], v[42:45]
	v_mfma_f32_16x16x32_bf16 v[30:33], v[144:147], v[204:207], v[30:33]
	v_mfma_f32_16x16x32_bf16 v[26:29], v[164:167], v[204:207], v[26:29]
	v_mfma_f32_16x16x32_bf16 v[14:17], v[144:147], v[212:215], v[14:17]
	v_mfma_f32_16x16x32_bf16 v[10:13], v[164:167], v[212:215], v[10:13]
	v_mfma_f32_16x16x32_bf16 v[62:65], v[160:163], v[192:195], v[62:65]
	v_mfma_f32_16x16x32_bf16 v[58:61], v[168:171], v[192:195], v[58:61]
	v_mfma_f32_16x16x32_bf16 v[46:49], v[160:163], v[200:203], v[46:49]
	v_mfma_f32_16x16x32_bf16 v[42:45], v[168:171], v[200:203], v[42:45]
	v_mfma_f32_16x16x32_bf16 v[30:33], v[160:163], v[208:211], v[30:33]
	v_mfma_f32_16x16x32_bf16 v[26:29], v[168:171], v[208:211], v[26:29]
	v_mfma_f32_16x16x32_bf16 v[14:17], v[160:163], v[216:219], v[14:17]
	v_mfma_f32_16x16x32_bf16 v[10:13], v[168:171], v[216:219], v[10:13]
	s_setprio 0
	s_setprio 1
	v_mfma_f32_16x16x32_bf16 v[54:57], v[172:175], v[188:191], v[54:57]
	v_mfma_f32_16x16x32_bf16 v[50:53], v[180:183], v[188:191], v[50:53]
	v_mfma_f32_16x16x32_bf16 v[38:41], v[172:175], v[196:199], v[38:41]
	v_mfma_f32_16x16x32_bf16 v[34:37], v[180:183], v[196:199], v[34:37]
	v_mfma_f32_16x16x32_bf16 v[22:25], v[172:175], v[204:207], v[22:25]
	v_mfma_f32_16x16x32_bf16 v[18:21], v[180:183], v[204:207], v[18:21]
	v_mfma_f32_16x16x32_bf16 v[6:9], v[172:175], v[212:215], v[6:9]
	v_mfma_f32_16x16x32_bf16 v[2:5], v[180:183], v[212:215], v[2:5]
	v_mfma_f32_16x16x32_bf16 v[54:57], v[176:179], v[192:195], v[54:57]
	v_mfma_f32_16x16x32_bf16 v[50:53], v[184:187], v[192:195], v[50:53]
	v_mfma_f32_16x16x32_bf16 v[38:41], v[176:179], v[200:203], v[38:41]
	v_mfma_f32_16x16x32_bf16 v[34:37], v[184:187], v[200:203], v[34:37]
	v_mfma_f32_16x16x32_bf16 v[22:25], v[176:179], v[208:211], v[22:25]
	v_mfma_f32_16x16x32_bf16 v[18:21], v[184:187], v[208:211], v[18:21]
	v_mfma_f32_16x16x32_bf16 v[6:9], v[176:179], v[216:219], v[6:9]
	v_mfma_f32_16x16x32_bf16 v[2:5], v[184:187], v[216:219], v[2:5]
	s_setprio 0
	s_add_i32 s64, s64, 2
	s_add_u32 s38, s38, 0x100
	s_addc_u32 s39, s39, 0
	s_add_u32 s62, s62, 0x100
	s_addc_u32 s63, s63, 0
	s_cmp_gt_u32 s64, 61
	s_barrier
	s_cbranch_scc0 .LBB0_1294
	s_and_b64 vcc, exec, s[14:15]
	s_cbranch_vccz .LBB0_1297
	s_barrier

.LBB0_2142:
	ds_read_b128 v[130:133], v199
	ds_read_b128 v[134:137], v199 offset:1024
	ds_read_b128 v[138:141], v199 offset:2048
	ds_read_b128 v[142:145], v199 offset:3072
	ds_read_b128 v[146:149], v200
	ds_read_b128 v[166:169], v200 offset:1024
	ds_read_b128 v[170:173], v200 offset:2048
	ds_read_b128 v[174:177], v200 offset:3072
	s_add_u32 s34, s30, 0xfff00080
	s_addc_u32 s35, s31, -1
	s_cmp_eq_u32 s52, 60
	s_cselect_b32 s37, s23, s35
	s_cselect_b32 s36, s48, s34
	s_cselect_b32 s35, s21, s51
	s_cselect_b32 s34, s49, s50
	v_lshl_add_u64 v[194:195], s[30:31], 0, v[158:159]
	s_add_i32 m0, s29, 0xc000
	ds_read_b128 v[178:181], v201
	ds_read_b128 v[182:185], v201 offset:1024
	ds_read_b128 v[186:189], v201 offset:2048
	ds_read_b128 v[190:193], v201 offset:3072
	ds_read_b128 v[202:205], v201 offset:4096
	ds_read_b128 v[206:209], v201 offset:5120
	ds_read_b128 v[210:213], v201 offset:6144
	ds_read_b128 v[214:217], v201 offset:7168
	global_load_lds_dwordx4 v[194:195], off
	v_lshl_add_u64 v[194:195], s[30:31], 0, v[160:161]
	s_add_i32 m0, s29, 0xe000
	s_nop 0
	global_load_lds_dwordx4 v[194:195], off
	s_waitcnt vmcnt(8)
	s_waitcnt lgkmcnt(0)
	s_barrier
	s_setprio 1
	s_waitcnt lgkmcnt(0)
	v_mfma_f32_16x16x32_bf16 v[126:129], v[130:133], v[178:181], v[126:129]
	v_mfma_f32_16x16x32_bf16 v[122:125], v[138:141], v[178:181], v[122:125]
	v_mfma_f32_16x16x32_bf16 v[118:121], v[130:133], v[186:189], v[118:121]
	v_mfma_f32_16x16x32_bf16 v[114:117], v[138:141], v[186:189], v[114:117]
	v_mfma_f32_16x16x32_bf16 v[110:113], v[130:133], v[202:205], v[110:113]
	v_mfma_f32_16x16x32_bf16 v[106:109], v[138:141], v[202:205], v[106:109]
	v_mfma_f32_16x16x32_bf16 v[102:105], v[130:133], v[210:213], v[102:105]
	v_mfma_f32_16x16x32_bf16 v[98:101], v[138:141], v[210:213], v[98:101]
	v_mfma_f32_16x16x32_bf16 v[126:129], v[134:137], v[182:185], v[126:129]
	v_mfma_f32_16x16x32_bf16 v[122:125], v[142:145], v[182:185], v[122:125]
	v_mfma_f32_16x16x32_bf16 v[118:121], v[134:137], v[190:193], v[118:121]
	v_mfma_f32_16x16x32_bf16 v[114:117], v[142:145], v[190:193], v[114:117]
	v_mfma_f32_16x16x32_bf16 v[110:113], v[134:137], v[206:209], v[110:113]
	v_mfma_f32_16x16x32_bf16 v[106:109], v[142:145], v[206:209], v[106:109]
	v_mfma_f32_16x16x32_bf16 v[102:105], v[134:137], v[214:217], v[102:105]
	v_mfma_f32_16x16x32_bf16 v[98:101], v[142:145], v[214:217], v[98:101]
	s_setprio 0
	s_setprio 1
	v_mfma_f32_16x16x32_bf16 v[62:65], v[146:149], v[178:181], v[62:65]
	v_mfma_f32_16x16x32_bf16 v[58:61], v[170:173], v[178:181], v[58:61]
	v_mfma_f32_16x16x32_bf16 v[54:57], v[146:149], v[186:189], v[54:57]
	v_mfma_f32_16x16x32_bf16 v[50:53], v[170:173], v[186:189], v[50:53]
	v_mfma_f32_16x16x32_bf16 v[46:49], v[146:149], v[202:205], v[46:49]
	v_mfma_f32_16x16x32_bf16 v[42:45], v[170:173], v[202:205], v[42:45]
	v_mfma_f32_16x16x32_bf16 v[38:41], v[146:149], v[210:213], v[38:41]
	v_mfma_f32_16x16x32_bf16 v[34:37], v[170:173], v[210:213], v[34:37]
	v_mfma_f32_16x16x32_bf16 v[62:65], v[166:169], v[182:185], v[62:65]
	v_mfma_f32_16x16x32_bf16 v[58:61], v[174:177], v[182:185], v[58:61]
	v_mfma_f32_16x16x32_bf16 v[54:57], v[166:169], v[190:193], v[54:57]
	v_mfma_f32_16x16x32_bf16 v[50:53], v[174:177], v[190:193], v[50:53]
	v_mfma_f32_16x16x32_bf16 v[46:49], v[166:169], v[206:209], v[46:49]
	v_mfma_f32_16x16x32_bf16 v[42:45], v[174:177], v[206:209], v[42:45]
	v_mfma_f32_16x16x32_bf16 v[38:41], v[166:169], v[214:217], v[38:41]
	v_mfma_f32_16x16x32_bf16 v[34:37], v[174:177], v[214:217], v[34:37]
	s_setprio 0
	s_barrier
	s_add_i32 s53, s46, s38
	v_lshl_add_u64 v[194:195], s[34:35], 0, v[152:153]
	s_mov_b32 m0, s53
	ds_read_b128 v[178:181], v201 offset:16384
	ds_read_b128 v[182:185], v201 offset:17408
	ds_read_b128 v[186:189], v201 offset:18432
	ds_read_b128 v[190:193], v201 offset:19456
	ds_read_b128 v[202:205], v201 offset:20480
	ds_read_b128 v[206:209], v201 offset:21504
	ds_read_b128 v[210:213], v201 offset:22528
	ds_read_b128 v[214:217], v201 offset:23552
	global_load_lds_dwordx4 v[194:195], off
	s_add_i32 m0, s53, 0x2000
	s_add_u32 s54, s34, 0x100000
	v_lshl_add_u64 v[218:219], s[34:35], 0, v[156:157]
	s_addc_u32 s55, s35, 0
	s_add_i32 s53, s47, s38
	global_load_lds_dwordx4 v[218:219], off
	v_lshl_add_u64 v[220:221], s[54:55], 0, v[152:153]
	s_mov_b32 m0, s53
	v_lshl_add_u64 v[222:223], s[36:37], 0, v[154:155]
	global_load_lds_dwordx4 v[220:221], off
	v_lshl_add_u64 v[220:221], s[54:55], 0, v[156:157]
	s_add_i32 m0, s53, 0x2000
	s_nop 0
	global_load_lds_dwordx4 v[220:221], off
	v_lshl_add_u64 v[220:221], s[36:37], 0, v[150:151]
	s_mov_b32 m0, s29
	s_nop 0
	global_load_lds_dwordx4 v[220:221], off
	s_mov_b32 m0, s39
	s_nop 0
	global_load_lds_dwordx4 v[222:223], off
	s_waitcnt vmcnt(8)
	s_waitcnt lgkmcnt(0)
	s_barrier
	s_setprio 1
	s_waitcnt lgkmcnt(0)
	v_mfma_f32_16x16x32_bf16 v[94:97], v[130:133], v[178:181], v[94:97]
	v_mfma_f32_16x16x32_bf16 v[90:93], v[138:141], v[178:181], v[90:93]
	v_mfma_f32_16x16x32_bf16 v[86:89], v[130:133], v[186:189], v[86:89]
	v_mfma_f32_16x16x32_bf16 v[82:85], v[138:141], v[186:189], v[82:85]
	v_mfma_f32_16x16x32_bf16 v[78:81], v[130:133], v[202:205], v[78:81]
	v_mfma_f32_16x16x32_bf16 v[74:77], v[138:141], v[202:205], v[74:77]
	v_mfma_f32_16x16x32_bf16 v[70:73], v[130:133], v[210:213], v[70:73]
	v_mfma_f32_16x16x32_bf16 v[66:69], v[138:141], v[210:213], v[66:69]
	v_mfma_f32_16x16x32_bf16 v[94:97], v[134:137], v[182:185], v[94:97]
	v_mfma_f32_16x16x32_bf16 v[90:93], v[142:145], v[182:185], v[90:93]
	v_mfma_f32_16x16x32_bf16 v[86:89], v[134:137], v[190:193], v[86:89]
	v_mfma_f32_16x16x32_bf16 v[82:85], v[142:145], v[190:193], v[82:85]
	v_mfma_f32_16x16x32_bf16 v[78:81], v[134:137], v[206:209], v[78:81]
	v_mfma_f32_16x16x32_bf16 v[74:77], v[142:145], v[206:209], v[74:77]
	v_mfma_f32_16x16x32_bf16 v[70:73], v[134:137], v[214:217], v[70:73]
	v_mfma_f32_16x16x32_bf16 v[66:69], v[142:145], v[214:217], v[66:69]
	s_setprio 0
	s_setprio 1
	v_mfma_f32_16x16x32_bf16 v[30:33], v[146:149], v[178:181], v[30:33]
	v_mfma_f32_16x16x32_bf16 v[26:29], v[170:173], v[178:181], v[26:29]
	v_mfma_f32_16x16x32_bf16 v[22:25], v[146:149], v[186:189], v[22:25]
	v_mfma_f32_16x16x32_bf16 v[18:21], v[170:173], v[186:189], v[18:21]
	v_mfma_f32_16x16x32_bf16 v[14:17], v[146:149], v[202:205], v[14:17]
	v_mfma_f32_16x16x32_bf16 v[10:13], v[170:173], v[202:205], v[10:13]
	v_mfma_f32_16x16x32_bf16 v[6:9], v[146:149], v[210:213], v[6:9]
	v_mfma_f32_16x16x32_bf16 v[2:5], v[170:173], v[210:213], v[2:5]
	v_mfma_f32_16x16x32_bf16 v[30:33], v[166:169], v[182:185], v[30:33]
	v_mfma_f32_16x16x32_bf16 v[26:29], v[174:177], v[182:185], v[26:29]
	v_mfma_f32_16x16x32_bf16 v[22:25], v[166:169], v[190:193], v[22:25]
	v_mfma_f32_16x16x32_bf16 v[18:21], v[174:177], v[190:193], v[18:21]
	v_mfma_f32_16x16x32_bf16 v[14:17], v[166:169], v[206:209], v[14:17]
	v_mfma_f32_16x16x32_bf16 v[10:13], v[174:177], v[206:209], v[10:13]
	v_mfma_f32_16x16x32_bf16 v[6:9], v[166:169], v[214:217], v[6:9]
	v_mfma_f32_16x16x32_bf16 v[2:5], v[174:177], v[214:217], v[2:5]
	s_setprio 0
	s_barrier
	s_add_i32 s53, 0, 0x18000
	s_add_i32 s54, 0, 0x1c000
	v_add_u32_e32 v142, s53, v197
	v_add_u32_e32 v174, s54, v197
	ds_read_b128 v[130:133], v142
	ds_read_b128 v[134:137], v142 offset:1024
	ds_read_b128 v[138:141], v142 offset:2048
	ds_read_b128 v[142:145], v142 offset:3072
	ds_read_b128 v[146:149], v174
	ds_read_b128 v[166:169], v174 offset:1024
	ds_read_b128 v[170:173], v174 offset:2048
	ds_read_b128 v[174:177], v174 offset:3072
	s_add_u32 s36, s36, 0x100000
	s_addc_u32 s37, s37, 0
	s_mov_b32 m0, s40
	v_lshl_add_u64 v[224:225], s[36:37], 0, v[150:151]
	ds_read_b128 v[178:181], v201 offset:32768
	ds_read_b128 v[182:185], v201 offset:33792
	ds_read_b128 v[186:189], v201 offset:34816
	ds_read_b128 v[190:193], v201 offset:35840
	ds_read_b128 v[202:205], v201 offset:36864
	ds_read_b128 v[206:209], v201 offset:37888
	ds_read_b128 v[210:213], v201 offset:38912
	ds_read_b128 v[214:217], v201 offset:39936
	global_load_lds_dwordx4 v[224:225], off
	v_lshl_add_u64 v[224:225], s[36:37], 0, v[154:155]
	s_mov_b32 m0, s41
	s_nop 0
	global_load_lds_dwordx4 v[224:225], off
	s_waitcnt vmcnt(8)
	s_waitcnt lgkmcnt(0)
	s_barrier
	s_setprio 1
	s_waitcnt lgkmcnt(0)
	v_mfma_f32_16x16x32_bf16 v[126:129], v[130:133], v[178:181], v[126:129]
	v_mfma_f32_16x16x32_bf16 v[122:125], v[138:141], v[178:181], v[122:125]
	v_mfma_f32_16x16x32_bf16 v[118:121], v[130:133], v[186:189], v[118:121]
	v_mfma_f32_16x16x32_bf16 v[114:117], v[138:141], v[186:189], v[114:117]
	v_mfma_f32_16x16x32_bf16 v[110:113], v[130:133], v[202:205], v[110:113]
	v_mfma_f32_16x16x32_bf16 v[106:109], v[138:141], v[202:205], v[106:109]
	v_mfma_f32_16x16x32_bf16 v[102:105], v[130:133], v[210:213], v[102:105]
	v_mfma_f32_16x16x32_bf16 v[98:101], v[138:141], v[210:213], v[98:101]
	v_mfma_f32_16x16x32_bf16 v[126:129], v[134:137], v[182:185], v[126:129]
	v_mfma_f32_16x16x32_bf16 v[122:125], v[142:145], v[182:185], v[122:125]
	v_mfma_f32_16x16x32_bf16 v[118:121], v[134:137], v[190:193], v[118:121]
	v_mfma_f32_16x16x32_bf16 v[114:117], v[142:145], v[190:193], v[114:117]
	v_mfma_f32_16x16x32_bf16 v[110:113], v[134:137], v[206:209], v[110:113]
	v_mfma_f32_16x16x32_bf16 v[106:109], v[142:145], v[206:209], v[106:109]
	v_mfma_f32_16x16x32_bf16 v[102:105], v[134:137], v[214:217], v[102:105]
	v_mfma_f32_16x16x32_bf16 v[98:101], v[142:145], v[214:217], v[98:101]
	s_setprio 0
	s_setprio 1
	v_mfma_f32_16x16x32_bf16 v[62:65], v[146:149], v[178:181], v[62:65]
	v_mfma_f32_16x16x32_bf16 v[58:61], v[170:173], v[178:181], v[58:61]
	v_mfma_f32_16x16x32_bf16 v[54:57], v[146:149], v[186:189], v[54:57]
	v_mfma_f32_16x16x32_bf16 v[50:53], v[170:173], v[186:189], v[50:53]
	v_mfma_f32_16x16x32_bf16 v[46:49], v[146:149], v[202:205], v[46:49]
	v_mfma_f32_16x16x32_bf16 v[42:45], v[170:173], v[202:205], v[42:45]
	v_mfma_f32_16x16x32_bf16 v[38:41], v[146:149], v[210:213], v[38:41]
	v_mfma_f32_16x16x32_bf16 v[34:37], v[170:173], v[210:213], v[34:37]
	v_mfma_f32_16x16x32_bf16 v[62:65], v[166:169], v[182:185], v[62:65]
	v_mfma_f32_16x16x32_bf16 v[58:61], v[174:177], v[182:185], v[58:61]
	v_mfma_f32_16x16x32_bf16 v[54:57], v[166:169], v[190:193], v[54:57]
	v_mfma_f32_16x16x32_bf16 v[50:53], v[174:177], v[190:193], v[50:53]
	v_mfma_f32_16x16x32_bf16 v[46:49], v[166:169], v[206:209], v[46:49]
	v_mfma_f32_16x16x32_bf16 v[42:45], v[174:177], v[206:209], v[42:45]
	v_mfma_f32_16x16x32_bf16 v[38:41], v[166:169], v[214:217], v[38:41]
	v_mfma_f32_16x16x32_bf16 v[34:37], v[174:177], v[214:217], v[34:37]
	s_setprio 0
	s_barrier
	s_add_i32 s36, s53, s38
	v_lshl_add_u64 v[194:195], v[194:195], 0, s[14:15]
	s_mov_b32 m0, s36
	ds_read_b128 v[178:181], v201 offset:49152
	ds_read_b128 v[182:185], v201 offset:50176
	ds_read_b128 v[186:189], v201 offset:51200
	ds_read_b128 v[190:193], v201 offset:52224
	ds_read_b128 v[202:205], v201 offset:53248
	ds_read_b128 v[206:209], v201 offset:54272
	ds_read_b128 v[210:213], v201 offset:55296
	ds_read_b128 v[214:217], v201 offset:56320
	global_load_lds_dwordx4 v[194:195], off
	s_add_i32 m0, s36, 0x2000
	s_add_u32 s34, s34, 0x100080
	v_lshl_add_u64 v[194:195], v[218:219], 0, s[14:15]
	s_addc_u32 s35, s35, 0
	s_add_i32 s36, s54, s38
	global_load_lds_dwordx4 v[194:195], off
	v_lshl_add_u64 v[194:195], s[34:35], 0, v[152:153]
	s_mov_b32 m0, s36
	s_nop 0
	global_load_lds_dwordx4 v[194:195], off
	v_lshl_add_u64 v[194:195], s[34:35], 0, v[156:157]
	s_add_i32 m0, s36, 0x2000
	s_nop 0
	global_load_lds_dwordx4 v[194:195], off
	v_lshl_add_u64 v[194:195], v[220:221], 0, s[14:15]
	s_mov_b32 m0, s43
	s_nop 0
	global_load_lds_dwordx4 v[194:195], off
	v_lshl_add_u64 v[194:195], v[222:223], 0, s[14:15]
	s_mov_b32 m0, s44
	s_nop 0
	global_load_lds_dwordx4 v[194:195], off
	s_waitcnt vmcnt(8)
	s_waitcnt lgkmcnt(0)
	s_barrier
	s_setprio 1
	s_waitcnt lgkmcnt(0)
	v_mfma_f32_16x16x32_bf16 v[94:97], v[130:133], v[178:181], v[94:97]
	v_mfma_f32_16x16x32_bf16 v[90:93], v[138:141], v[178:181], v[90:93]
	v_mfma_f32_16x16x32_bf16 v[86:89], v[130:133], v[186:189], v[86:89]
	v_mfma_f32_16x16x32_bf16 v[82:85], v[138:141], v[186:189], v[82:85]
	v_mfma_f32_16x16x32_bf16 v[78:81], v[130:133], v[202:205], v[78:81]
	v_mfma_f32_16x16x32_bf16 v[74:77], v[138:141], v[202:205], v[74:77]
	v_mfma_f32_16x16x32_bf16 v[70:73], v[130:133], v[210:213], v[70:73]
	v_mfma_f32_16x16x32_bf16 v[66:69], v[138:141], v[210:213], v[66:69]
	v_mfma_f32_16x16x32_bf16 v[94:97], v[134:137], v[182:185], v[94:97]
	v_mfma_f32_16x16x32_bf16 v[90:93], v[142:145], v[182:185], v[90:93]
	v_mfma_f32_16x16x32_bf16 v[86:89], v[134:137], v[190:193], v[86:89]
	v_mfma_f32_16x16x32_bf16 v[82:85], v[142:145], v[190:193], v[82:85]
	v_mfma_f32_16x16x32_bf16 v[78:81], v[134:137], v[206:209], v[78:81]
	v_mfma_f32_16x16x32_bf16 v[74:77], v[142:145], v[206:209], v[74:77]
	v_mfma_f32_16x16x32_bf16 v[70:73], v[134:137], v[214:217], v[70:73]
	v_mfma_f32_16x16x32_bf16 v[66:69], v[142:145], v[214:217], v[66:69]
	s_setprio 0
	s_setprio 1
	v_mfma_f32_16x16x32_bf16 v[30:33], v[146:149], v[178:181], v[30:33]
	v_mfma_f32_16x16x32_bf16 v[26:29], v[170:173], v[178:181], v[26:29]
	v_mfma_f32_16x16x32_bf16 v[22:25], v[146:149], v[186:189], v[22:25]
	v_mfma_f32_16x16x32_bf16 v[18:21], v[170:173], v[186:189], v[18:21]
	v_mfma_f32_16x16x32_bf16 v[14:17], v[146:149], v[202:205], v[14:17]
	v_mfma_f32_16x16x32_bf16 v[10:13], v[170:173], v[202:205], v[10:13]
	v_mfma_f32_16x16x32_bf16 v[6:9], v[146:149], v[210:213], v[6:9]
	v_mfma_f32_16x16x32_bf16 v[2:5], v[170:173], v[210:213], v[2:5]
	v_mfma_f32_16x16x32_bf16 v[30:33], v[166:169], v[182:185], v[30:33]
	v_mfma_f32_16x16x32_bf16 v[26:29], v[174:177], v[182:185], v[26:29]
	v_mfma_f32_16x16x32_bf16 v[22:25], v[166:169], v[190:193], v[22:25]
	v_mfma_f32_16x16x32_bf16 v[18:21], v[174:177], v[190:193], v[18:21]
	v_mfma_f32_16x16x32_bf16 v[14:17], v[166:169], v[206:209], v[14:17]
	v_mfma_f32_16x16x32_bf16 v[10:13], v[174:177], v[206:209], v[10:13]
	v_mfma_f32_16x16x32_bf16 v[6:9], v[166:169], v[214:217], v[6:9]
	v_mfma_f32_16x16x32_bf16 v[2:5], v[174:177], v[214:217], v[2:5]
	s_setprio 0
	s_add_i32 s52, s52, 2
	s_add_u32 s30, s30, 0x100
	s_addc_u32 s31, s31, 0
	s_add_u32 s50, s50, 0x100
	s_addc_u32 s51, s51, 0
	s_cmp_gt_u32 s52, 61
	s_barrier
	s_cbranch_scc0 .LBB0_2142
	s_and_b64 vcc, exec, s[16:17]
	s_cbranch_vccz .LBB0_2145
	s_barrier

.LBB0_2369:
	ds_read_b128 v[130:133], v197
	ds_read_b128 v[134:137], v197 offset:1024
	ds_read_b128 v[138:141], v197 offset:2048
	ds_read_b128 v[142:145], v197 offset:3072
	ds_read_b128 v[146:149], v198
	ds_read_b128 v[166:169], v198 offset:1024
	ds_read_b128 v[170:173], v198 offset:2048
	ds_read_b128 v[174:177], v198 offset:3072
	s_add_u32 s28, s26, 0xffd50080
	s_addc_u32 s29, s27, -1
	s_cmpk_eq_i32 s52, 0xa8
	s_cselect_b32 s31, s9, s29
	s_cselect_b32 s30, s8, s28
	s_cselect_b32 s29, s25, s51
	s_cselect_b32 s28, s24, s50
	v_lshl_add_u64 v[216:217], s[26:27], 0, v[158:159]
	s_add_i32 m0, s37, 0xc000
	ds_read_b128 v[178:181], v199
	ds_read_b128 v[182:185], v199 offset:1024
	ds_read_b128 v[186:189], v199 offset:2048
	ds_read_b128 v[190:193], v199 offset:3072
	ds_read_b128 v[200:203], v199 offset:4096
	ds_read_b128 v[204:207], v199 offset:5120
	ds_read_b128 v[208:211], v199 offset:6144
	ds_read_b128 v[212:215], v199 offset:7168
	global_load_lds_dwordx4 v[216:217], off
	v_lshl_add_u64 v[216:217], s[26:27], 0, v[160:161]
	s_add_i32 m0, s37, 0xe000
	s_nop 0
	global_load_lds_dwordx4 v[216:217], off
	s_waitcnt vmcnt(8)
	s_waitcnt lgkmcnt(0)
	s_barrier
	s_setprio 1
	s_waitcnt lgkmcnt(0)
	v_mfma_f32_16x16x32_bf16 v[126:129], v[130:133], v[178:181], v[126:129]
	v_mfma_f32_16x16x32_bf16 v[122:125], v[138:141], v[178:181], v[122:125]
	v_mfma_f32_16x16x32_bf16 v[118:121], v[130:133], v[186:189], v[118:121]
	v_mfma_f32_16x16x32_bf16 v[114:117], v[138:141], v[186:189], v[114:117]
	v_mfma_f32_16x16x32_bf16 v[110:113], v[130:133], v[200:203], v[110:113]
	v_mfma_f32_16x16x32_bf16 v[106:109], v[138:141], v[200:203], v[106:109]
	v_mfma_f32_16x16x32_bf16 v[102:105], v[130:133], v[208:211], v[102:105]
	v_mfma_f32_16x16x32_bf16 v[98:101], v[138:141], v[208:211], v[98:101]
	v_mfma_f32_16x16x32_bf16 v[126:129], v[134:137], v[182:185], v[126:129]
	v_mfma_f32_16x16x32_bf16 v[122:125], v[142:145], v[182:185], v[122:125]
	v_mfma_f32_16x16x32_bf16 v[118:121], v[134:137], v[190:193], v[118:121]
	v_mfma_f32_16x16x32_bf16 v[114:117], v[142:145], v[190:193], v[114:117]
	v_mfma_f32_16x16x32_bf16 v[110:113], v[134:137], v[204:207], v[110:113]
	v_mfma_f32_16x16x32_bf16 v[106:109], v[142:145], v[204:207], v[106:109]
	v_mfma_f32_16x16x32_bf16 v[102:105], v[134:137], v[212:215], v[102:105]
	v_mfma_f32_16x16x32_bf16 v[98:101], v[142:145], v[212:215], v[98:101]
	s_setprio 0
	s_setprio 1
	v_mfma_f32_16x16x32_bf16 v[62:65], v[146:149], v[178:181], v[62:65]
	v_mfma_f32_16x16x32_bf16 v[58:61], v[170:173], v[178:181], v[58:61]
	v_mfma_f32_16x16x32_bf16 v[54:57], v[146:149], v[186:189], v[54:57]
	v_mfma_f32_16x16x32_bf16 v[50:53], v[170:173], v[186:189], v[50:53]
	v_mfma_f32_16x16x32_bf16 v[46:49], v[146:149], v[200:203], v[46:49]
	v_mfma_f32_16x16x32_bf16 v[42:45], v[170:173], v[200:203], v[42:45]
	v_mfma_f32_16x16x32_bf16 v[38:41], v[146:149], v[208:211], v[38:41]
	v_mfma_f32_16x16x32_bf16 v[34:37], v[170:173], v[208:211], v[34:37]
	v_mfma_f32_16x16x32_bf16 v[62:65], v[166:169], v[182:185], v[62:65]
	v_mfma_f32_16x16x32_bf16 v[58:61], v[174:177], v[182:185], v[58:61]
	v_mfma_f32_16x16x32_bf16 v[54:57], v[166:169], v[190:193], v[54:57]
	v_mfma_f32_16x16x32_bf16 v[50:53], v[174:177], v[190:193], v[50:53]
	v_mfma_f32_16x16x32_bf16 v[46:49], v[166:169], v[204:207], v[46:49]
	v_mfma_f32_16x16x32_bf16 v[42:45], v[174:177], v[204:207], v[42:45]
	v_mfma_f32_16x16x32_bf16 v[38:41], v[166:169], v[212:215], v[38:41]
	v_mfma_f32_16x16x32_bf16 v[34:37], v[174:177], v[212:215], v[34:37]
	s_setprio 0
	s_barrier
	s_add_i32 s53, s45, s36
	v_lshl_add_u64 v[216:217], s[28:29], 0, v[152:153]
	s_mov_b32 m0, s53
	ds_read_b128 v[178:181], v199 offset:16384
	ds_read_b128 v[182:185], v199 offset:17408
	ds_read_b128 v[186:189], v199 offset:18432
	ds_read_b128 v[190:193], v199 offset:19456
	ds_read_b128 v[200:203], v199 offset:20480
	ds_read_b128 v[204:207], v199 offset:21504
	ds_read_b128 v[208:211], v199 offset:22528
	ds_read_b128 v[212:215], v199 offset:23552
	global_load_lds_dwordx4 v[216:217], off
	s_add_i32 m0, s53, 0x2000
	s_add_u32 s54, s28, 0x2b0000
	v_lshl_add_u64 v[218:219], s[28:29], 0, v[156:157]
	s_addc_u32 s55, s29, 0
	s_add_i32 s53, s46, s36
	global_load_lds_dwordx4 v[218:219], off
	v_lshl_add_u64 v[220:221], s[54:55], 0, v[152:153]
	s_mov_b32 m0, s53
	v_lshl_add_u64 v[222:223], s[30:31], 0, v[154:155]
	global_load_lds_dwordx4 v[220:221], off
	v_lshl_add_u64 v[220:221], s[54:55], 0, v[156:157]
	s_add_i32 m0, s53, 0x2000
	s_nop 0
	global_load_lds_dwordx4 v[220:221], off
	v_lshl_add_u64 v[220:221], s[30:31], 0, v[150:151]
	s_mov_b32 m0, s37
	s_nop 0
	global_load_lds_dwordx4 v[220:221], off
	s_mov_b32 m0, s38
	s_nop 0
	global_load_lds_dwordx4 v[222:223], off
	s_waitcnt vmcnt(8)
	s_waitcnt lgkmcnt(0)
	s_barrier
	s_setprio 1
	s_waitcnt lgkmcnt(0)
	v_mfma_f32_16x16x32_bf16 v[94:97], v[130:133], v[178:181], v[94:97]
	v_mfma_f32_16x16x32_bf16 v[90:93], v[138:141], v[178:181], v[90:93]
	v_mfma_f32_16x16x32_bf16 v[86:89], v[130:133], v[186:189], v[86:89]
	v_mfma_f32_16x16x32_bf16 v[82:85], v[138:141], v[186:189], v[82:85]
	v_mfma_f32_16x16x32_bf16 v[78:81], v[130:133], v[200:203], v[78:81]
	v_mfma_f32_16x16x32_bf16 v[74:77], v[138:141], v[200:203], v[74:77]
	v_mfma_f32_16x16x32_bf16 v[70:73], v[130:133], v[208:211], v[70:73]
	v_mfma_f32_16x16x32_bf16 v[66:69], v[138:141], v[208:211], v[66:69]
	v_mfma_f32_16x16x32_bf16 v[94:97], v[134:137], v[182:185], v[94:97]
	v_mfma_f32_16x16x32_bf16 v[90:93], v[142:145], v[182:185], v[90:93]
	v_mfma_f32_16x16x32_bf16 v[86:89], v[134:137], v[190:193], v[86:89]
	v_mfma_f32_16x16x32_bf16 v[82:85], v[142:145], v[190:193], v[82:85]
	v_mfma_f32_16x16x32_bf16 v[78:81], v[134:137], v[204:207], v[78:81]
	v_mfma_f32_16x16x32_bf16 v[74:77], v[142:145], v[204:207], v[74:77]
	v_mfma_f32_16x16x32_bf16 v[70:73], v[134:137], v[212:215], v[70:73]
	v_mfma_f32_16x16x32_bf16 v[66:69], v[142:145], v[212:215], v[66:69]
	s_setprio 0
	s_setprio 1
	v_mfma_f32_16x16x32_bf16 v[30:33], v[146:149], v[178:181], v[30:33]
	v_mfma_f32_16x16x32_bf16 v[26:29], v[170:173], v[178:181], v[26:29]
	v_mfma_f32_16x16x32_bf16 v[22:25], v[146:149], v[186:189], v[22:25]
	v_mfma_f32_16x16x32_bf16 v[18:21], v[170:173], v[186:189], v[18:21]
	v_mfma_f32_16x16x32_bf16 v[14:17], v[146:149], v[200:203], v[14:17]
	v_mfma_f32_16x16x32_bf16 v[10:13], v[170:173], v[200:203], v[10:13]
	v_mfma_f32_16x16x32_bf16 v[6:9], v[146:149], v[208:211], v[6:9]
	v_mfma_f32_16x16x32_bf16 v[2:5], v[170:173], v[208:211], v[2:5]
	v_mfma_f32_16x16x32_bf16 v[30:33], v[166:169], v[182:185], v[30:33]
	v_mfma_f32_16x16x32_bf16 v[26:29], v[174:177], v[182:185], v[26:29]
	v_mfma_f32_16x16x32_bf16 v[22:25], v[166:169], v[190:193], v[22:25]
	v_mfma_f32_16x16x32_bf16 v[18:21], v[174:177], v[190:193], v[18:21]
	v_mfma_f32_16x16x32_bf16 v[14:17], v[166:169], v[204:207], v[14:17]
	v_mfma_f32_16x16x32_bf16 v[10:13], v[174:177], v[204:207], v[10:13]
	v_mfma_f32_16x16x32_bf16 v[6:9], v[166:169], v[212:215], v[6:9]
	v_mfma_f32_16x16x32_bf16 v[2:5], v[174:177], v[212:215], v[2:5]
	s_setprio 0
	s_barrier
	s_add_i32 s53, 0, 0x18000
	s_add_i32 s54, 0, 0x1c000
	v_add_u32_e32 v142, s53, v195
	v_add_u32_e32 v174, s54, v195
	ds_read_b128 v[130:133], v142
	ds_read_b128 v[134:137], v142 offset:1024
	ds_read_b128 v[138:141], v142 offset:2048
	ds_read_b128 v[142:145], v142 offset:3072
	ds_read_b128 v[146:149], v174
	ds_read_b128 v[166:169], v174 offset:1024
	ds_read_b128 v[170:173], v174 offset:2048
	ds_read_b128 v[174:177], v174 offset:3072
	s_add_u32 s30, s30, 0x2b0000
	s_addc_u32 s31, s31, 0
	s_mov_b32 m0, s39
	v_lshl_add_u64 v[224:225], s[30:31], 0, v[150:151]
	ds_read_b128 v[178:181], v199 offset:32768
	ds_read_b128 v[182:185], v199 offset:33792
	ds_read_b128 v[186:189], v199 offset:34816
	ds_read_b128 v[190:193], v199 offset:35840
	ds_read_b128 v[200:203], v199 offset:36864
	ds_read_b128 v[204:207], v199 offset:37888
	ds_read_b128 v[208:211], v199 offset:38912
	ds_read_b128 v[212:215], v199 offset:39936
	global_load_lds_dwordx4 v[224:225], off
	v_lshl_add_u64 v[224:225], s[30:31], 0, v[154:155]
	s_mov_b32 m0, s40
	s_nop 0
	global_load_lds_dwordx4 v[224:225], off
	s_waitcnt vmcnt(8)
	s_waitcnt lgkmcnt(0)
	s_barrier
	s_setprio 1
	s_waitcnt lgkmcnt(0)
	v_mfma_f32_16x16x32_bf16 v[126:129], v[130:133], v[178:181], v[126:129]
	v_mfma_f32_16x16x32_bf16 v[122:125], v[138:141], v[178:181], v[122:125]
	v_mfma_f32_16x16x32_bf16 v[118:121], v[130:133], v[186:189], v[118:121]
	v_mfma_f32_16x16x32_bf16 v[114:117], v[138:141], v[186:189], v[114:117]
	v_mfma_f32_16x16x32_bf16 v[110:113], v[130:133], v[200:203], v[110:113]
	v_mfma_f32_16x16x32_bf16 v[106:109], v[138:141], v[200:203], v[106:109]
	v_mfma_f32_16x16x32_bf16 v[102:105], v[130:133], v[208:211], v[102:105]
	v_mfma_f32_16x16x32_bf16 v[98:101], v[138:141], v[208:211], v[98:101]
	v_mfma_f32_16x16x32_bf16 v[126:129], v[134:137], v[182:185], v[126:129]
	v_mfma_f32_16x16x32_bf16 v[122:125], v[142:145], v[182:185], v[122:125]
	v_mfma_f32_16x16x32_bf16 v[118:121], v[134:137], v[190:193], v[118:121]
	v_mfma_f32_16x16x32_bf16 v[114:117], v[142:145], v[190:193], v[114:117]
	v_mfma_f32_16x16x32_bf16 v[110:113], v[134:137], v[204:207], v[110:113]
	v_mfma_f32_16x16x32_bf16 v[106:109], v[142:145], v[204:207], v[106:109]
	v_mfma_f32_16x16x32_bf16 v[102:105], v[134:137], v[212:215], v[102:105]
	v_mfma_f32_16x16x32_bf16 v[98:101], v[142:145], v[212:215], v[98:101]
	s_setprio 0
	s_setprio 1
	v_mfma_f32_16x16x32_bf16 v[62:65], v[146:149], v[178:181], v[62:65]
	v_mfma_f32_16x16x32_bf16 v[58:61], v[170:173], v[178:181], v[58:61]
	v_mfma_f32_16x16x32_bf16 v[54:57], v[146:149], v[186:189], v[54:57]
	v_mfma_f32_16x16x32_bf16 v[50:53], v[170:173], v[186:189], v[50:53]
	v_mfma_f32_16x16x32_bf16 v[46:49], v[146:149], v[200:203], v[46:49]
	v_mfma_f32_16x16x32_bf16 v[42:45], v[170:173], v[200:203], v[42:45]
	v_mfma_f32_16x16x32_bf16 v[38:41], v[146:149], v[208:211], v[38:41]
	v_mfma_f32_16x16x32_bf16 v[34:37], v[170:173], v[208:211], v[34:37]
	v_mfma_f32_16x16x32_bf16 v[62:65], v[166:169], v[182:185], v[62:65]
	v_mfma_f32_16x16x32_bf16 v[58:61], v[174:177], v[182:185], v[58:61]
	v_mfma_f32_16x16x32_bf16 v[54:57], v[166:169], v[190:193], v[54:57]
	v_mfma_f32_16x16x32_bf16 v[50:53], v[174:177], v[190:193], v[50:53]
	v_mfma_f32_16x16x32_bf16 v[46:49], v[166:169], v[204:207], v[46:49]
	v_mfma_f32_16x16x32_bf16 v[42:45], v[174:177], v[204:207], v[42:45]
	v_mfma_f32_16x16x32_bf16 v[38:41], v[166:169], v[212:215], v[38:41]
	v_mfma_f32_16x16x32_bf16 v[34:37], v[174:177], v[212:215], v[34:37]
	s_setprio 0
	s_barrier
	s_add_i32 s30, s53, s36
	v_lshl_add_u64 v[216:217], v[216:217], 0, s[18:19]
	s_mov_b32 m0, s30
	ds_read_b128 v[178:181], v199 offset:49152
	ds_read_b128 v[182:185], v199 offset:50176
	ds_read_b128 v[186:189], v199 offset:51200
	ds_read_b128 v[190:193], v199 offset:52224
	ds_read_b128 v[200:203], v199 offset:53248
	ds_read_b128 v[204:207], v199 offset:54272
	ds_read_b128 v[208:211], v199 offset:55296
	ds_read_b128 v[212:215], v199 offset:56320
	global_load_lds_dwordx4 v[216:217], off
	s_add_i32 m0, s30, 0x2000
	s_add_u32 s28, s28, 0x2b0080
	v_lshl_add_u64 v[216:217], v[218:219], 0, s[18:19]
	s_addc_u32 s29, s29, 0
	s_add_i32 s30, s54, s36
	global_load_lds_dwordx4 v[216:217], off
	v_lshl_add_u64 v[216:217], s[28:29], 0, v[152:153]
	s_mov_b32 m0, s30
	s_nop 0
	global_load_lds_dwordx4 v[216:217], off
	v_lshl_add_u64 v[216:217], s[28:29], 0, v[156:157]
	s_add_i32 m0, s30, 0x2000
	s_nop 0
	global_load_lds_dwordx4 v[216:217], off
	v_lshl_add_u64 v[216:217], v[220:221], 0, s[18:19]
	s_mov_b32 m0, s42
	s_nop 0
	global_load_lds_dwordx4 v[216:217], off
	v_lshl_add_u64 v[216:217], v[222:223], 0, s[18:19]
	s_mov_b32 m0, s43
	s_nop 0
	global_load_lds_dwordx4 v[216:217], off
	s_waitcnt vmcnt(8)
	s_waitcnt lgkmcnt(0)
	s_barrier
	s_setprio 1
	s_waitcnt lgkmcnt(0)
	v_mfma_f32_16x16x32_bf16 v[94:97], v[130:133], v[178:181], v[94:97]
	v_mfma_f32_16x16x32_bf16 v[90:93], v[138:141], v[178:181], v[90:93]
	v_mfma_f32_16x16x32_bf16 v[86:89], v[130:133], v[186:189], v[86:89]
	v_mfma_f32_16x16x32_bf16 v[82:85], v[138:141], v[186:189], v[82:85]
	v_mfma_f32_16x16x32_bf16 v[78:81], v[130:133], v[200:203], v[78:81]
	v_mfma_f32_16x16x32_bf16 v[74:77], v[138:141], v[200:203], v[74:77]
	v_mfma_f32_16x16x32_bf16 v[70:73], v[130:133], v[208:211], v[70:73]
	v_mfma_f32_16x16x32_bf16 v[66:69], v[138:141], v[208:211], v[66:69]
	v_mfma_f32_16x16x32_bf16 v[94:97], v[134:137], v[182:185], v[94:97]
	v_mfma_f32_16x16x32_bf16 v[90:93], v[142:145], v[182:185], v[90:93]
	v_mfma_f32_16x16x32_bf16 v[86:89], v[134:137], v[190:193], v[86:89]
	v_mfma_f32_16x16x32_bf16 v[82:85], v[142:145], v[190:193], v[82:85]
	v_mfma_f32_16x16x32_bf16 v[78:81], v[134:137], v[204:207], v[78:81]
	v_mfma_f32_16x16x32_bf16 v[74:77], v[142:145], v[204:207], v[74:77]
	v_mfma_f32_16x16x32_bf16 v[70:73], v[134:137], v[212:215], v[70:73]
	v_mfma_f32_16x16x32_bf16 v[66:69], v[142:145], v[212:215], v[66:69]
	s_setprio 0
	s_setprio 1
	v_mfma_f32_16x16x32_bf16 v[30:33], v[146:149], v[178:181], v[30:33]
	v_mfma_f32_16x16x32_bf16 v[26:29], v[170:173], v[178:181], v[26:29]
	v_mfma_f32_16x16x32_bf16 v[22:25], v[146:149], v[186:189], v[22:25]
	v_mfma_f32_16x16x32_bf16 v[18:21], v[170:173], v[186:189], v[18:21]
	v_mfma_f32_16x16x32_bf16 v[14:17], v[146:149], v[200:203], v[14:17]
	v_mfma_f32_16x16x32_bf16 v[10:13], v[170:173], v[200:203], v[10:13]
	v_mfma_f32_16x16x32_bf16 v[6:9], v[146:149], v[208:211], v[6:9]
	v_mfma_f32_16x16x32_bf16 v[2:5], v[170:173], v[208:211], v[2:5]
	v_mfma_f32_16x16x32_bf16 v[30:33], v[166:169], v[182:185], v[30:33]
	v_mfma_f32_16x16x32_bf16 v[26:29], v[174:177], v[182:185], v[26:29]
	v_mfma_f32_16x16x32_bf16 v[22:25], v[166:169], v[190:193], v[22:25]
	v_mfma_f32_16x16x32_bf16 v[18:21], v[174:177], v[190:193], v[18:21]
	v_mfma_f32_16x16x32_bf16 v[14:17], v[166:169], v[204:207], v[14:17]
	v_mfma_f32_16x16x32_bf16 v[10:13], v[174:177], v[204:207], v[10:13]
	v_mfma_f32_16x16x32_bf16 v[6:9], v[166:169], v[212:215], v[6:9]
	v_mfma_f32_16x16x32_bf16 v[2:5], v[174:177], v[212:215], v[2:5]
	s_setprio 0
	s_add_i32 s52, s52, 2
	s_add_u32 s26, s26, 0x100
	s_addc_u32 s27, s27, 0
	s_add_u32 s50, s50, 0x100
	s_addc_u32 s51, s51, 0
	s_cmpk_gt_u32 s52, 0xa9
	s_barrier
	s_cbranch_scc0 .LBB0_2369
	s_and_b64 vcc, exec, s[20:21]
	s_cbranch_vccz .LBB0_2372
	s_barrier
